# plus: R1S state sweeps re-emitted with 3-stage load pipeline; gated conv re-emitted (8 rows per thread, taps hoisted, sliding window); R1S units remapped so V^T sharers sit on one XCD
# speedup vs baseline: 1.0202x; 1.0019x over previous
; __device__ __forceinline__ void r1s_sweep(const bf16_t* __restrict__ kT, const bf16_t* __restrict__ vT, bf16_t* __restrict__ STd, int bh, int s, int wid, int fr, int fq, float lg, float gC, bool fwd) {
;     float w[4][8];
; #pragma unroll
;     for (int ks = 0; ks < 4; ++ks)
; #pragma unroll
;         for (int e = 0; e < 8; ++e) { const int t = 32 * ks + 8 * fq + e; w[ks][e] = __builtin_amdgcn_exp2f(lg * (float)(fwd ? 127 - t : t)); }
;     f32x4 S = {0.f, 0.f, 0.f, 0.f};
;     const size_t koff = (size_t)(16 * s + fr) * 128 + 8 * fq, voff = (size_t)(16 * wid + fr) * 128 + 8 * fq;
;     bf16_t* dst0 = STd + (16 * wid + fr) * 128 + 16 * s + 4 * fq;
; __device__ __forceinline__ void r1s_phase(KP p, int G, int bid, int wv) {
;     ...
;     for (int u = bid; u < 256; u += G) {
;         const int bh = u >> 3, s = u & 7, h = bh & 7;
.LBB0_110:
	s_andn2_b64 vcc, exec, s[0:1]
	s_cbranch_vccnz .LBB0_122
	v_writelane_b32 v254, s26, 35
	v_mov_b32_e32 v252, 0x3727c5ac
	v_mov_b32_e32 v93, v221
	v_writelane_b32 v254, s27, 36
	s_andn2_b64 vcc, exec, s[58:59]
	s_mov_b32 s12, 0xbfb8aa3b
	s_mov_b32 s13, 0xc2b17218
	s_mov_b32 s14, 0x7f800000
	s_mov_b32 s15, 0x3f317218
	s_mov_b32 s22, 0x33800000
	s_mov_b32 s23, 0x8000
	s_mov_b32 s24, 0x18000
	s_mov_b32 s25, 0x28000
	s_mov_b32 s26, 0x30000
	s_mov_b32 s27, 0x38000
	s_mov_b32 s29, 0x40000
	s_mov_b32 s30, 0x48000
	s_mov_b32 s31, 0x50000
	s_mov_b32 s34, 0x58000
	s_mov_b32 s36, 0x60000
	s_mov_b32 s37, 0x68000
	s_mov_b32 s38, 0x70000
	s_mov_b32 s39, 0x78000
	s_cbranch_vccnz .LBB0_114
	v_bfe_u32 v0, v93, 4, 2
	v_lshlrev_b32_e32 v126, 3, v0
	s_waitcnt vmcnt(0)
	v_xor_b32_e32 v2, 0x7f, v126
	v_cvt_f32_ubyte0_e32 v127, v2
	v_xor_b32_e32 v2, 0x7e, v126
	v_cvt_f32_ubyte0_e32 v128, v2
	v_xor_b32_e32 v2, 0x7d, v126
	v_cvt_f32_ubyte0_e32 v129, v2
	v_xor_b32_e32 v2, 0x7c, v126
	v_cvt_f32_ubyte0_e32 v130, v2
	v_xor_b32_e32 v2, 0x7b, v126
	v_cvt_f32_ubyte0_e32 v131, v2
	v_xor_b32_e32 v2, 0x7a, v126
	v_cvt_f32_ubyte0_e32 v132, v2
	v_xor_b32_e32 v2, 0x79, v126
	v_cvt_f32_ubyte0_e32 v133, v2
	v_xor_b32_e32 v2, 0x78, v126
	v_cvt_f32_ubyte0_e32 v134, v2
	v_xor_b32_e32 v2, 0x5f, v126
	v_cvt_f32_ubyte0_e32 v135, v2
	v_xor_b32_e32 v2, 0x5e, v126
	v_cvt_f32_ubyte0_e32 v136, v2
	v_xor_b32_e32 v2, 0x5d, v126
	v_cvt_f32_ubyte0_e32 v137, v2
	v_xor_b32_e32 v2, 0x5c, v126
	v_cvt_f32_ubyte0_e32 v138, v2
	v_xor_b32_e32 v2, 0x5b, v126
	v_cvt_f32_ubyte0_e32 v139, v2
	v_xor_b32_e32 v2, 0x5a, v126
	v_cvt_f32_ubyte0_e32 v140, v2
	v_xor_b32_e32 v2, 0x59, v126
	v_cvt_f32_ubyte0_e32 v141, v2
	v_xor_b32_e32 v2, 0x58, v126
	v_cvt_f32_ubyte0_e32 v142, v2
	v_xor_b32_e32 v2, 63, v126
	v_cvt_f32_ubyte0_e32 v143, v2
	v_xor_b32_e32 v2, 62, v126
	v_cvt_f32_ubyte0_e32 v144, v2
	v_xor_b32_e32 v2, 61, v126
	v_cvt_f32_ubyte0_e32 v145, v2
	v_xor_b32_e32 v2, 60, v126
	v_cvt_f32_ubyte0_e32 v146, v2
	v_xor_b32_e32 v2, 59, v126
	v_cvt_f32_ubyte0_e32 v147, v2
	v_xor_b32_e32 v2, 58, v126
	v_cvt_f32_ubyte0_e32 v148, v2
	v_xor_b32_e32 v2, 57, v126
	v_cvt_f32_ubyte0_e32 v149, v2
	v_xor_b32_e32 v2, 56, v126
	v_cvt_f32_ubyte0_e32 v150, v2
	v_xor_b32_e32 v2, 31, v126
	v_cvt_f32_ubyte0_e32 v151, v2
	v_xor_b32_e32 v2, 30, v126
	v_cvt_f32_ubyte0_e32 v152, v2
	v_xor_b32_e32 v2, 29, v126
	v_cvt_f32_ubyte0_e32 v153, v2
	v_xor_b32_e32 v2, 28, v126
	v_cvt_f32_ubyte0_e32 v154, v2
	v_xor_b32_e32 v2, 27, v126
	v_cvt_f32_ubyte0_e32 v155, v2
	v_xor_b32_e32 v2, 26, v126
	v_cvt_f32_ubyte0_e32 v156, v2
	v_xor_b32_e32 v2, 25, v126
	v_cvt_f32_ubyte0_e32 v157, v2
	v_xor_b32_e32 v2, 24, v126
	v_cvt_f32_ubyte0_e32 v158, v2
	v_ashrrev_i32_e32 v2, 2, v93
	v_bfi_b32 v2, -16, v2, v93
	v_ashrrev_i32_e32 v3, 31, v2
	v_lshlrev_b32_e32 v4, 7, v2
	v_ashrrev_i32_e32 v5, 31, v4
	v_lshlrev_b64 v[2:3], 8, v[2:3]
	v_lshl_add_u64 v[50:51], v[4:5], 1, s[8:9]
	v_lshlrev_b32_e32 v4, 2, v0
	v_lshl_add_u64 v[2:3], s[10:11], 0, v[2:3]
	v_lshlrev_b32_e32 v0, 4, v0
	v_lshl_add_u64 v[52:53], v[2:3], 0, v[0:1]
	v_or_b32_e32 v0, 1, v126
	v_cvt_f32_ubyte0_e32 v159, v0
	v_or_b32_e32 v0, 2, v126
	v_cvt_f32_ubyte0_e32 v160, v0
	v_or_b32_e32 v0, 3, v126
	v_cvt_f32_ubyte0_e32 v161, v0
	v_or_b32_e32 v0, 4, v126
	v_cvt_f32_ubyte0_e32 v178, v0
	v_or_b32_e32 v0, 5, v126
	v_cvt_f32_ubyte0_e32 v182, v0
	v_or_b32_e32 v0, 6, v126
	v_cvt_f32_ubyte0_e32 v184, v0
	v_or_b32_e32 v0, 7, v126
	v_cvt_f32_ubyte0_e32 v185, v0
	v_or_b32_e32 v0, 32, v126
	v_cvt_f32_ubyte0_e32 v186, v0
	v_or_b32_e32 v0, 33, v126
	v_cvt_f32_ubyte0_e32 v187, v0
	v_or_b32_e32 v0, 34, v126
	v_cvt_f32_ubyte0_e32 v188, v0
	v_or_b32_e32 v0, 35, v126
	v_cvt_f32_ubyte0_e32 v189, v0
	v_or_b32_e32 v0, 36, v126
	v_cvt_f32_ubyte0_e32 v190, v0
	v_or_b32_e32 v0, 37, v126
	v_cvt_f32_ubyte0_e32 v191, v0
	v_or_b32_e32 v0, 38, v126
	v_cvt_f32_ubyte0_e32 v192, v0
	v_or_b32_e32 v0, 39, v126
	v_cvt_f32_ubyte0_e32 v193, v0
	v_or_b32_e32 v0, 64, v126
	v_cvt_f32_ubyte0_e32 v194, v0
	v_or_b32_e32 v0, 0x41, v126
	v_cvt_f32_ubyte0_e32 v195, v0
	v_or_b32_e32 v0, 0x42, v126
	v_cvt_f32_ubyte0_e32 v196, v0
	v_or_b32_e32 v0, 0x43, v126
	v_cvt_f32_ubyte0_e32 v197, v0
	v_or_b32_e32 v0, 0x44, v126
	v_cvt_f32_ubyte0_e32 v198, v0
	v_or_b32_e32 v0, 0x45, v126
	v_cvt_f32_ubyte0_e32 v199, v0
	v_or_b32_e32 v0, 0x46, v126
	v_cvt_f32_ubyte0_e32 v200, v0
	v_or_b32_e32 v0, 0x47, v126
	v_cvt_f32_ubyte0_e32 v201, v0
	v_or_b32_e32 v0, 0x60, v126
	v_cvt_f32_ubyte0_e32 v202, v0
	v_or_b32_e32 v0, 0x61, v126
	v_cvt_f32_ubyte0_e32 v203, v0
	v_or_b32_e32 v0, 0x62, v126
	v_cvt_f32_ubyte0_e32 v204, v0
	v_or_b32_e32 v0, 0x63, v126
	s_load_dwordx4 s[4:7], s[78:79], 0x90
	v_cvt_f32_ubyte0_e32 v205, v0
	v_or_b32_e32 v0, 0x64, v126
	v_cvt_f32_ubyte0_e32 v206, v0
	v_or_b32_e32 v0, 0x65, v126
	v_cvt_f32_ubyte0_e32 v207, v0
	v_or_b32_e32 v0, 0x66, v126
	s_add_u32 s2, s80, 0x21eb4000
	v_cvt_f32_ubyte0_e32 v208, v0
	v_or_b32_e32 v0, 0x67, v126
	s_addc_u32 s3, s81, 0
	v_cvt_f32_ubyte0_e32 v209, v0
	v_lshlrev_b32_e32 v0, 1, v4
	v_readlane_b32 s0, v253, 27
	s_and_b32 s8, s33, 7
	s_lshr_b32 s9, s33, 6
	s_lshl_b32 s8, s8, 2
	s_add_i32 s8, s8, s9
	s_bfe_u32 s10, s33, 0x30003
	s_lshl_b32 s8, s8, 3
	s_add_i32 s8, s8, s10
	s_cmp_eq_u32 s42, 0x100
	s_cselect_b32 s1, s8, s33
; __device__ __forceinline__ float log2_gamma(float logit) { return -log1pf(expf(-logit)) * 1.4426950408889634f; }
; __device__ __forceinline__ void r1s_phase(KP p, int G, int bid, int wv) {
;     ...
;     for (int u = bid; u < 256; u += G) {
;         const int bh = u >> 3, s = u & 7, h = bh & 7;
;         float lf = log2_gamma(p->in[18][h]), lb = log2_gamma(p->in[19][h]);
;         asm volatile("" : "+v"(lf), "+v"(lb));
.LBB0_113:
	s_ashr_i32 s10, s1, 3
	s_lshl_b32 s8, s10, 2
	s_and_b32 s8, s8, 28
	v_mov_b32_e32 v18, s8
	s_waitcnt lgkmcnt(0)
	global_load_dword v2, v18, s[4:5]
	v_mov_b32_e32 v219, v246
	s_lshl_b32 s16, s10, 1
	s_ashr_i32 s17, s16, 31
	s_mul_i32 s18, s10, 18
	s_lshl_b64 s[8:9], s[16:17], 19
	s_and_b32 s11, s0, 0x70
	s_ashr_i32 s19, s18, 31
	s_lshl_b32 s46, s11, 1
	v_mov_b32_e32 v83, v1
	s_waitcnt vmcnt(0)
	v_mul_f32_e32 v3, 0xbfb8aa3b, v2
	v_fma_f32 v4, v2, s12, -v3
	v_rndne_f32_e32 v5, v3
	v_fmac_f32_e32 v4, 0xb2a5705f, v2
	v_sub_f32_e32 v3, v3, v5
	v_add_f32_e32 v3, v3, v4
	v_exp_f32_e32 v3, v3
	v_cvt_i32_f32_e32 v4, v5
	v_cmp_nlt_f32_e32 vcc, s93, v2
	v_ldexp_f32 v3, v3, v4
	s_nop 0
	v_cndmask_b32_e32 v3, 0, v3, vcc
	v_cmp_ngt_f32_e32 vcc, s13, v2
	s_nop 1
	v_cndmask_b32_e32 v19, v222, v3, vcc
	v_add_f32_e32 v4, 1.0, v19
	v_add_f32_e32 v2, -1.0, v4
	v_sub_f32_e32 v3, v2, v4
	v_add_f32_e32 v3, 1.0, v3
	v_sub_f32_e32 v2, v19, v2
	v_add_f32_e32 v5, v2, v3
	v_frexp_mant_f32_e32 v2, v4
	v_cmp_gt_f32_e32 vcc, s35, v2
	v_cvt_f64_f32_e32 v[2:3], v4
	v_frexp_exp_i32_f64_e32 v2, v[2:3]
	v_subbrev_co_u32_e32 v10, vcc, 0, v2, vcc
	v_sub_u32_e32 v2, 0, v10
	v_ldexp_f32 v3, v4, v2
	v_add_f32_e32 v4, -1.0, v3
	v_add_f32_e32 v6, 1.0, v3
	v_ldexp_f32 v2, v5, v2
	v_add_f32_e32 v5, 1.0, v4
	v_add_f32_e32 v7, -1.0, v6
	v_sub_f32_e32 v5, v3, v5
	v_sub_f32_e32 v3, v3, v7
	v_add_f32_e32 v5, v2, v5
	v_add_f32_e32 v2, v2, v3
	v_add_f32_e32 v11, v6, v2
	v_rcp_f32_e32 v13, v11
	v_sub_f32_e32 v3, v6, v11
	v_add_f32_e32 v12, v2, v3
	v_add_f32_e32 v3, v4, v5
	v_mul_f32_e32 v15, v3, v13
	v_sub_f32_e32 v2, v4, v3
	v_mul_f32_e32 v4, v11, v15
	v_fma_f32 v6, v15, v11, -v4
	v_fmac_f32_e32 v6, v15, v12
	v_add_f32_e32 v14, v5, v2
	v_add_f32_e32 v2, v4, v6
	v_sub_f32_e32 v5, v3, v2
	v_pk_add_f32 v[8:9], v[2:3], v[4:5] neg_lo:[0,1] neg_hi:[0,1]
	v_mov_b32_e32 v7, v2
	v_pk_add_f32 v[2:3], v[8:9], v[6:7] neg_lo:[0,1] neg_hi:[0,1]
	v_cmp_neq_f32_e32 vcc, s14, v19
	v_add_f32_e32 v3, v14, v3
	v_add_f32_e32 v2, v2, v3
	v_add_f32_e32 v3, v5, v2
	v_mul_f32_e32 v14, v13, v3
	v_mul_f32_e32 v4, v11, v14
	v_fma_f32 v6, v14, v11, -v4
	v_fmac_f32_e32 v6, v14, v12
	v_sub_f32_e32 v5, v5, v3
	v_add_f32_e32 v11, v2, v5
	v_add_f32_e32 v2, v4, v6
	v_sub_f32_e32 v5, v3, v2
	v_pk_add_f32 v[8:9], v[2:3], v[4:5] neg_lo:[0,1] neg_hi:[0,1]
	v_mov_b32_e32 v7, v2
	v_pk_add_f32 v[2:3], v[8:9], v[6:7] neg_lo:[0,1] neg_hi:[0,1]
	s_nop 0
	v_add_f32_e32 v3, v11, v3
	v_add_f32_e32 v2, v2, v3
	v_add_f32_e32 v3, v15, v14
	v_add_f32_e32 v2, v5, v2
	v_sub_f32_e32 v4, v3, v15
	v_mul_f32_e32 v2, v13, v2
	v_sub_f32_e32 v4, v14, v4
	v_add_f32_e32 v4, v4, v2
	v_add_f32_e32 v6, v3, v4
	v_mul_f32_e32 v7, v6, v6
	v_fmamk_f32 v2, v7, 0x3e9b6dac, v246
	v_fmaak_f32 v163, v7, v2, 0x3f2aaada
	v_cvt_f32_i32_e32 v2, v10
	v_sub_f32_e32 v3, v6, v3
	v_sub_f32_e32 v3, v4, v3
	v_ldexp_f32 v8, v3, 1
	v_mul_f32_e32 v3, v6, v7
	v_ldexp_f32 v5, v6, 1
	v_pk_mul_f32 v[6:7], v[2:3], v[162:163]
	s_nop 0
	v_fma_f32 v4, v2, s15, -v6
	v_fmac_f32_e32 v4, 0xb102e308, v2
	v_pk_add_f32 v[2:3], v[6:7], v[4:5]
	s_nop 0
	v_sub_f32_e32 v5, v3, v5
	v_sub_f32_e32 v5, v7, v5
	v_add_f32_e32 v9, v8, v5
	v_mov_b32_e32 v8, v6
	v_pk_add_f32 v[6:7], v[2:3], v[6:7] neg_lo:[0,1] neg_hi:[0,1]
	v_pk_add_f32 v[10:11], v[2:3], v[8:9]
	v_mov_b32_e32 v5, v2
	v_mov_b32_e32 v7, v11
	v_pk_add_f32 v[12:13], v[4:5], v[6:7] neg_lo:[0,1] neg_hi:[0,1]
	v_pk_add_f32 v[4:5], v[4:5], v[6:7]
	v_mov_b32_e32 v16, v3
	v_pk_add_f32 v[6:7], v[4:5], v[2:3] op_sel:[1,0] op_sel_hi:[0,1] neg_lo:[0,1] neg_hi:[0,1]
	v_pk_add_f32 v[14:15], v[10:11], v[6:7] op_sel_hi:[1,0] neg_lo:[0,1] neg_hi:[0,1]
	v_mov_b32_e32 v10, v11
	v_mov_b32_e32 v11, v5
	v_mov_b32_e32 v17, v6
	v_pk_add_f32 v[6:7], v[10:11], v[16:17] neg_lo:[0,1] neg_hi:[0,1]
	v_mov_b32_e32 v8, v9
	v_mov_b32_e32 v9, v2
	v_pk_add_f32 v[2:3], v[8:9], v[6:7] neg_lo:[0,1] neg_hi:[0,1]
	v_mov_b32_e32 v14, v12
	v_pk_add_f32 v[6:7], v[14:15], v[2:3]
	v_mov_b32_e32 v13, v5
	v_pk_add_f32 v[8:9], v[6:7], v[6:7] op_sel:[0,1] op_sel_hi:[1,0]
	s_nop 0
	v_pk_add_f32 v[4:5], v[4:5], v[8:9] op_sel:[1,0] op_sel_hi:[0,1]
	v_mov_b32_e32 v7, v4
	v_pk_add_f32 v[10:11], v[6:7], v[12:13] neg_lo:[0,1] neg_hi:[0,1]
	v_mov_b32_e32 v3, v8
	v_sub_f32_e32 v5, v6, v10
	v_pk_add_f32 v[2:3], v[2:3], v[10:11] neg_lo:[0,1] neg_hi:[0,1]
	v_sub_f32_e32 v5, v12, v5
	v_add_f32_e32 v2, v2, v5
	v_add_f32_e32 v2, v2, v3
	v_add_f32_e32 v2, v4, v2
	v_cndmask_b32_e32 v2, v222, v2, vcc
	v_cmp_lt_f32_e64 vcc, |v19|, s22
	s_nop 1
	v_cndmask_b32_e32 v2, v2, v19, vcc
	v_mul_f32_e32 v19, 0xbfb8aa3b, v2
	global_load_dword v2, v18, s[6:7]
	s_waitcnt vmcnt(0)
; __device__ __forceinline__ float log2_gamma(float logit) { return -log1pf(expf(-logit)) * 1.4426950408889634f; }
; __device__ __forceinline__ void r1s_sweep(const bf16_t* __restrict__ kT, const bf16_t* __restrict__ vT, bf16_t* __restrict__ STd, int bh, int s, int wid, int fr, int fq, float lg, float gC, bool fwd) {
;     float w[4][8];
; #pragma unroll
;     for (int ks = 0; ks < 4; ++ks)
; #pragma unroll
;         for (int e = 0; e < 8; ++e) { const int t = 32 * ks + 8 * fq + e; w[ks][e] = __builtin_amdgcn_exp2f(lg * (float)(fwd ? 127 - t : t)); }
;     f32x4 S = {0.f, 0.f, 0.f, 0.f};
;     const size_t koff = (size_t)(16 * s + fr) * 128 + 8 * fq, voff = (size_t)(16 * wid + fr) * 128 + 8 * fq;
;     bf16_t* dst0 = STd + (16 * wid + fr) * 128 + 16 * s + 4 * fq;
;     ...
;     bf16x8 kA[4], vA[4], kB[4], vB[4];
;     r1s_load(kT, vT, bh, R1S_CC(0), koff, voff, kA, vA);
	v_mul_f32_e32 v3, 0xbfb8aa3b, v2
	v_fma_f32 v4, v2, s12, -v3
	v_rndne_f32_e32 v5, v3
	v_fmac_f32_e32 v4, 0xb2a5705f, v2
	v_sub_f32_e32 v3, v3, v5
	v_add_f32_e32 v3, v3, v4
	v_exp_f32_e32 v3, v3
	v_cvt_i32_f32_e32 v4, v5
	v_cmp_nlt_f32_e32 vcc, s93, v2
	v_ldexp_f32 v3, v3, v4
	s_nop 0
	v_cndmask_b32_e32 v3, 0, v3, vcc
	v_cmp_ngt_f32_e32 vcc, s13, v2
	s_nop 1
	v_cndmask_b32_e32 v18, v222, v3, vcc
	v_add_f32_e32 v4, 1.0, v18
	v_add_f32_e32 v2, -1.0, v4
	v_sub_f32_e32 v3, v2, v4
	v_add_f32_e32 v3, 1.0, v3
	v_sub_f32_e32 v2, v18, v2
	v_add_f32_e32 v5, v2, v3
	v_frexp_mant_f32_e32 v2, v4
	v_cmp_gt_f32_e32 vcc, s35, v2
	v_cvt_f64_f32_e32 v[2:3], v4
	v_frexp_exp_i32_f64_e32 v2, v[2:3]
	v_subbrev_co_u32_e32 v10, vcc, 0, v2, vcc
	v_sub_u32_e32 v2, 0, v10
	v_ldexp_f32 v3, v4, v2
	v_add_f32_e32 v4, -1.0, v3
	v_add_f32_e32 v6, 1.0, v3
	v_ldexp_f32 v2, v5, v2
	v_add_f32_e32 v5, 1.0, v4
	v_add_f32_e32 v7, -1.0, v6
	v_sub_f32_e32 v5, v3, v5
	v_sub_f32_e32 v3, v3, v7
	v_add_f32_e32 v5, v2, v5
	v_add_f32_e32 v2, v2, v3
	v_add_f32_e32 v11, v6, v2
	v_rcp_f32_e32 v13, v11
	v_sub_f32_e32 v3, v6, v11
	v_add_f32_e32 v12, v2, v3
	v_add_f32_e32 v3, v4, v5
	v_mul_f32_e32 v15, v3, v13
	v_sub_f32_e32 v2, v4, v3
	v_mul_f32_e32 v4, v11, v15
	v_fma_f32 v6, v15, v11, -v4
	v_fmac_f32_e32 v6, v15, v12
	v_add_f32_e32 v14, v5, v2
	v_add_f32_e32 v2, v4, v6
	v_sub_f32_e32 v5, v3, v2
	v_pk_add_f32 v[8:9], v[2:3], v[4:5] neg_lo:[0,1] neg_hi:[0,1]
	v_mov_b32_e32 v7, v2
	v_pk_add_f32 v[2:3], v[8:9], v[6:7] neg_lo:[0,1] neg_hi:[0,1]
	v_cmp_neq_f32_e32 vcc, s14, v18
	v_add_f32_e32 v3, v14, v3
	v_add_f32_e32 v2, v2, v3
	v_add_f32_e32 v3, v5, v2
	v_mul_f32_e32 v14, v13, v3
	v_mul_f32_e32 v4, v11, v14
	v_fma_f32 v6, v14, v11, -v4
	v_fmac_f32_e32 v6, v14, v12
	v_sub_f32_e32 v5, v5, v3
	v_add_f32_e32 v11, v2, v5
	v_add_f32_e32 v2, v4, v6
	v_sub_f32_e32 v5, v3, v2
	v_pk_add_f32 v[8:9], v[2:3], v[4:5] neg_lo:[0,1] neg_hi:[0,1]
	v_mov_b32_e32 v7, v2
	v_pk_add_f32 v[2:3], v[8:9], v[6:7] neg_lo:[0,1] neg_hi:[0,1]
	s_nop 0
	v_add_f32_e32 v3, v11, v3
	v_add_f32_e32 v2, v2, v3
	v_add_f32_e32 v3, v15, v14
	v_add_f32_e32 v2, v5, v2
	v_sub_f32_e32 v4, v3, v15
	v_mul_f32_e32 v2, v13, v2
	v_sub_f32_e32 v4, v14, v4
	v_add_f32_e32 v4, v4, v2
	v_add_f32_e32 v6, v3, v4
	v_mul_f32_e32 v7, v6, v6
	v_fmamk_f32 v2, v7, 0x3e9b6dac, v246
	v_fmaak_f32 v163, v7, v2, 0x3f2aaada
	v_cvt_f32_i32_e32 v2, v10
	v_sub_f32_e32 v3, v6, v3
	v_sub_f32_e32 v3, v4, v3
	v_ldexp_f32 v8, v3, 1
	v_mul_f32_e32 v3, v6, v7
	v_ldexp_f32 v5, v6, 1
	v_pk_mul_f32 v[6:7], v[2:3], v[162:163]
	s_nop 0
	v_fma_f32 v4, v2, s15, -v6
	v_fmac_f32_e32 v4, 0xb102e308, v2
	v_pk_add_f32 v[2:3], v[6:7], v[4:5]
	s_nop 0
	v_sub_f32_e32 v5, v3, v5
	v_sub_f32_e32 v5, v7, v5
	v_add_f32_e32 v9, v8, v5
	v_mov_b32_e32 v8, v6
	v_pk_add_f32 v[6:7], v[2:3], v[6:7] neg_lo:[0,1] neg_hi:[0,1]
	v_pk_add_f32 v[10:11], v[2:3], v[8:9]
	v_mov_b32_e32 v5, v2
	v_mov_b32_e32 v7, v11
	v_pk_add_f32 v[12:13], v[4:5], v[6:7] neg_lo:[0,1] neg_hi:[0,1]
	v_pk_add_f32 v[4:5], v[4:5], v[6:7]
	v_mov_b32_e32 v16, v3
	v_pk_add_f32 v[6:7], v[4:5], v[2:3] op_sel:[1,0] op_sel_hi:[0,1] neg_lo:[0,1] neg_hi:[0,1]
	v_pk_add_f32 v[14:15], v[10:11], v[6:7] op_sel_hi:[1,0] neg_lo:[0,1] neg_hi:[0,1]
	v_mov_b32_e32 v10, v11
	v_mov_b32_e32 v11, v5
	v_mov_b32_e32 v17, v6
	v_pk_add_f32 v[6:7], v[10:11], v[16:17] neg_lo:[0,1] neg_hi:[0,1]
	v_mov_b32_e32 v8, v9
	v_mov_b32_e32 v9, v2
	v_pk_add_f32 v[2:3], v[8:9], v[6:7] neg_lo:[0,1] neg_hi:[0,1]
	v_mov_b32_e32 v14, v12
	v_pk_add_f32 v[6:7], v[14:15], v[2:3]
	v_mov_b32_e32 v13, v5
	v_pk_add_f32 v[8:9], v[6:7], v[6:7] op_sel:[0,1] op_sel_hi:[1,0]
	s_nop 0
	v_pk_add_f32 v[4:5], v[4:5], v[8:9] op_sel:[1,0] op_sel_hi:[0,1]
	v_mov_b32_e32 v7, v4
	v_pk_add_f32 v[10:11], v[6:7], v[12:13] neg_lo:[0,1] neg_hi:[0,1]
	v_mov_b32_e32 v3, v8
	v_sub_f32_e32 v5, v6, v10
	v_pk_add_f32 v[2:3], v[2:3], v[10:11] neg_lo:[0,1] neg_hi:[0,1]
	v_sub_f32_e32 v5, v12, v5
	v_add_f32_e32 v2, v2, v5
	v_add_f32_e32 v2, v2, v3
	v_add_f32_e32 v2, v4, v2
	v_cndmask_b32_e32 v2, v222, v2, vcc
	v_cmp_lt_f32_e64 vcc, |v18|, s22
	s_nop 1
	v_cndmask_b32_e32 v2, v2, v18, vcc
	v_mul_f32_e32 v163, 0xbfb8aa3b, v2
	v_and_b32_e32 v164, 15, v221
	v_bfe_u32 v165, v221, 4, 2
	v_lshrrev_b32_e32 v166, 6, v221
	v_lshlrev_b32_e32 v167, 3, v165
	s_and_b32 s8, s1, 7
	s_lshl_b32 s8, s8, 4
	v_add_u32_e32 v168, s8, v164
	v_lshlrev_b32_e32 v168, 8, v168
	v_lshl_add_u32 v170, v165, 4, v168
	v_lshl_add_u32 v168, v166, 4, v164
	v_lshlrev_b32_e32 v169, 8, v168
	v_lshl_add_u32 v171, v165, 4, v169
	v_lshl_add_u32 v172, v165, 3, v169
	s_lshl_b32 s9, s8, 1
	v_add_u32_e32 v172, s9, v172
	s_ashr_i32 s10, s1, 3
	s_mul_i32 s11, s10, 0x90000
	s_add_u32 s16, s2, s11
	s_addc_u32 s17, s3, 0
	s_add_u32 s18, s16, 0x1200000
	s_addc_u32 s19, s17, 0
	s_add_u32 s8, s16, 0x0
	s_addc_u32 s9, s17, 0
	s_add_u32 s10, s18, 0x0
	s_addc_u32 s11, s19, 0
	global_load_dwordx4 v[2:5], v170, s[8:9]
	global_load_dwordx4 v[6:9], v170, s[8:9] offset:64
	global_load_dwordx4 v[10:13], v170, s[8:9] offset:128
	global_load_dwordx4 v[14:17], v170, s[8:9] offset:192
	global_load_dwordx4 v[70:73], v171, s[10:11]
	global_load_dwordx4 v[74:77], v171, s[10:11] offset:64
	global_load_dwordx4 v[78:81], v171, s[10:11] offset:128
	global_load_dwordx4 v[82:85], v171, s[10:11] offset:192
	s_add_u32 s8, s16, 0x8000
	s_addc_u32 s9, s17, 0
	s_add_u32 s10, s18, 0x8000
	s_addc_u32 s11, s19, 0
	global_load_dwordx4 v[20:23], v170, s[8:9]
	global_load_dwordx4 v[24:27], v170, s[8:9] offset:64
	global_load_dwordx4 v[28:31], v170, s[8:9] offset:128
	global_load_dwordx4 v[32:35], v170, s[8:9] offset:192
	global_load_dwordx4 v[94:97], v171, s[10:11]
; __device__ __forceinline__ void r1s_sweep(const bf16_t* __restrict__ kT, const bf16_t* __restrict__ vT, bf16_t* __restrict__ STd, int bh, int s, int wid, int fr, int fq, float lg, float gC, bool fwd) {
;     ...
;     for (int ks = 0; ks < 4; ++ks)
; #pragma unroll
;         for (int e = 0; e < 8; ++e) { const int t = 32 * ks + 8 * fq + e; w[ks][e] = __builtin_amdgcn_exp2f(lg * (float)(fwd ? 127 - t : t)); }
;     f32x4 S = {0.f, 0.f, 0.f, 0.f};
;     const size_t koff = (size_t)(16 * s + fr) * 128 + 8 * fq, voff = (size_t)(16 * wid + fr) * 128 + 8 * fq;
;     bf16_t* dst0 = STd + (16 * wid + fr) * 128 + 16 * s + 4 * fq;
;     ...
;     bf16x8 kA[4], vA[4], kB[4], vB[4];
;     r1s_load(kT, vT, bh, R1S_CC(0), koff, voff, kA, vA);
; #pragma unroll
;     for (int i = 0; i < 18; i += 2) {
;         r1s_load(kT, vT, bh, R1S_CC(i + 1), koff, voff, kB, vB);
;         { const int cc = R1S_CC(i); r1s_step(kA, vA, w, S, gC, cc >= 2, dst0 + (size_t)(cc >= 2 ? cc - 2 : 0) * 16384); }
;         if (i + 2 < 18) r1s_load(kT, vT, bh, R1S_CC(i + 2), koff, voff, kA, vA);
	global_load_dwordx4 v[98:101], v171, s[10:11] offset:64
	global_load_dwordx4 v[102:105], v171, s[10:11] offset:128
	global_load_dwordx4 v[106:109], v171, s[10:11] offset:192
	v_sub_u32_e32 v168, 127, v167
	v_cvt_f32_u32_e32 v168, v168
	v_mul_f32_e32 v168, v19, v168
	v_exp_f32_e32 v224, v168
	v_sub_u32_e32 v168, 126, v167
	v_cvt_f32_u32_e32 v168, v168
	v_mul_f32_e32 v168, v19, v168
	v_exp_f32_e32 v225, v168
	v_sub_u32_e32 v168, 125, v167
	v_cvt_f32_u32_e32 v168, v168
	v_mul_f32_e32 v168, v19, v168
	v_exp_f32_e32 v226, v168
	v_sub_u32_e32 v168, 124, v167
	v_cvt_f32_u32_e32 v168, v168
	v_mul_f32_e32 v168, v19, v168
	v_exp_f32_e32 v227, v168
	v_sub_u32_e32 v168, 123, v167
	v_cvt_f32_u32_e32 v168, v168
	v_mul_f32_e32 v168, v19, v168
	v_exp_f32_e32 v228, v168
	v_sub_u32_e32 v168, 122, v167
	v_cvt_f32_u32_e32 v168, v168
	v_mul_f32_e32 v168, v19, v168
	v_exp_f32_e32 v229, v168
	v_sub_u32_e32 v168, 121, v167
	v_cvt_f32_u32_e32 v168, v168
	v_mul_f32_e32 v168, v19, v168
	v_exp_f32_e32 v230, v168
	v_sub_u32_e32 v168, 120, v167
	v_cvt_f32_u32_e32 v168, v168
	v_mul_f32_e32 v168, v19, v168
	v_exp_f32_e32 v231, v168
	v_sub_u32_e32 v168, 95, v167
	v_cvt_f32_u32_e32 v168, v168
	v_mul_f32_e32 v168, v19, v168
	v_exp_f32_e32 v232, v168
	v_sub_u32_e32 v168, 94, v167
	v_cvt_f32_u32_e32 v168, v168
	v_mul_f32_e32 v168, v19, v168
	v_exp_f32_e32 v233, v168
	v_sub_u32_e32 v168, 93, v167
	v_cvt_f32_u32_e32 v168, v168
	v_mul_f32_e32 v168, v19, v168
	v_exp_f32_e32 v234, v168
	v_sub_u32_e32 v168, 92, v167
	v_cvt_f32_u32_e32 v168, v168
	v_mul_f32_e32 v168, v19, v168
	v_exp_f32_e32 v235, v168
	v_sub_u32_e32 v168, 91, v167
	v_cvt_f32_u32_e32 v168, v168
	v_mul_f32_e32 v168, v19, v168
	v_exp_f32_e32 v236, v168
	v_sub_u32_e32 v168, 90, v167
	v_cvt_f32_u32_e32 v168, v168
	v_mul_f32_e32 v168, v19, v168
	v_exp_f32_e32 v237, v168
	v_sub_u32_e32 v168, 89, v167
	v_cvt_f32_u32_e32 v168, v168
	v_mul_f32_e32 v168, v19, v168
	v_exp_f32_e32 v238, v168
	v_sub_u32_e32 v168, 88, v167
	v_cvt_f32_u32_e32 v168, v168
	v_mul_f32_e32 v168, v19, v168
	v_exp_f32_e32 v239, v168
	v_sub_u32_e32 v168, 63, v167
	v_cvt_f32_u32_e32 v168, v168
	v_mul_f32_e32 v168, v19, v168
	v_exp_f32_e32 v240, v168
	v_sub_u32_e32 v168, 62, v167
	v_cvt_f32_u32_e32 v168, v168
	v_mul_f32_e32 v168, v19, v168
	v_exp_f32_e32 v241, v168
	v_sub_u32_e32 v168, 61, v167
	v_cvt_f32_u32_e32 v168, v168
	v_mul_f32_e32 v168, v19, v168
	v_exp_f32_e32 v242, v168
	v_sub_u32_e32 v168, 60, v167
	v_cvt_f32_u32_e32 v168, v168
	v_mul_f32_e32 v168, v19, v168
	v_exp_f32_e32 v243, v168
	v_sub_u32_e32 v168, 59, v167
	v_cvt_f32_u32_e32 v168, v168
	v_mul_f32_e32 v168, v19, v168
	v_exp_f32_e32 v244, v168
	v_sub_u32_e32 v168, 58, v167
	v_cvt_f32_u32_e32 v168, v168
	v_mul_f32_e32 v168, v19, v168
	v_exp_f32_e32 v245, v168
	v_sub_u32_e32 v168, 57, v167
	v_cvt_f32_u32_e32 v168, v168
	v_mul_f32_e32 v168, v19, v168
	v_exp_f32_e32 v246, v168
	v_sub_u32_e32 v168, 56, v167
	v_cvt_f32_u32_e32 v168, v168
	v_mul_f32_e32 v168, v19, v168
	v_exp_f32_e32 v247, v168
	v_sub_u32_e32 v168, 31, v167
	v_cvt_f32_u32_e32 v168, v168
	v_mul_f32_e32 v168, v19, v168
	v_exp_f32_e32 v248, v168
	v_sub_u32_e32 v168, 30, v167
	v_cvt_f32_u32_e32 v168, v168
	v_mul_f32_e32 v168, v19, v168
	v_exp_f32_e32 v249, v168
	v_sub_u32_e32 v168, 29, v167
	v_cvt_f32_u32_e32 v168, v168
	v_mul_f32_e32 v168, v19, v168
	v_exp_f32_e32 v250, v168
	v_sub_u32_e32 v168, 28, v167
	v_cvt_f32_u32_e32 v168, v168
	v_mul_f32_e32 v168, v19, v168
	v_exp_f32_e32 v251, v168
	v_sub_u32_e32 v168, 27, v167
	v_cvt_f32_u32_e32 v168, v168
	v_mul_f32_e32 v168, v19, v168
	v_exp_f32_e32 v210, v168
	v_sub_u32_e32 v168, 26, v167
	v_cvt_f32_u32_e32 v168, v168
	v_mul_f32_e32 v168, v19, v168
	v_exp_f32_e32 v211, v168
	v_sub_u32_e32 v168, 25, v167
	v_cvt_f32_u32_e32 v168, v168
	v_mul_f32_e32 v168, v19, v168
	v_exp_f32_e32 v212, v168
	v_sub_u32_e32 v168, 24, v167
	v_cvt_f32_u32_e32 v168, v168
	v_mul_f32_e32 v168, v19, v168
	v_exp_f32_e32 v213, v168
	v_mul_f32_e32 v168, 0x43000000, v19
	v_exp_f32_e32 v90, v168
	v_mov_b32_e32 v36, 0
	v_mov_b32_e32 v37, 0
	v_mov_b32_e32 v38, 0
	v_mov_b32_e32 v39, 0
	s_ashr_i32 s20, s1, 3
	s_lshl_b32 s20, s20, 20
	s_add_u32 s20, s20, 0xac00000
	s_add_u32 s20, s2, s20
	s_addc_u32 s21, s3, 0
	s_add_u32 s8, s16, 0x10000
	s_addc_u32 s9, s17, 0
	s_add_u32 s10, s18, 0x10000
	s_addc_u32 s11, s19, 0
	global_load_dwordx4 v[54:57], v170, s[8:9]
	global_load_dwordx4 v[58:61], v170, s[8:9] offset:64
	global_load_dwordx4 v[62:65], v170, s[8:9] offset:128
	global_load_dwordx4 v[66:69], v170, s[8:9] offset:192
	global_load_dwordx4 v[110:113], v171, s[10:11]
	global_load_dwordx4 v[114:117], v171, s[10:11] offset:64
	global_load_dwordx4 v[118:121], v171, s[10:11] offset:128
	global_load_dwordx4 v[122:125], v171, s[10:11] offset:192
	s_waitcnt vmcnt(16)
; __device__ __forceinline__ unsigned cvt_pk_bf16(float lo, float hi) { unsigned r; asm("v_cvt_pk_bf16_f32 %0, %1, %2" : "=v"(r) : "v"(lo), "v"(hi)); return r; }
; __device__ __forceinline__ float bf2f(unsigned b) { return __uint_as_float(b << 16); }
; __device__ __forceinline__ void r1s_step(const bf16x8 (&kk)[4], const bf16x8 (&vv)[4], const float (&w)[4][8], f32x4& S, float gC, bool st, bf16_t* dst) {
;     f32x4 acc = {0.f, 0.f, 0.f, 0.f};
; #pragma unroll
;     for (int ks = 0; ks < 4; ++ks) {
;         float f[8];
; #pragma unroll
;         for (int e = 0; e < 8; ++e) f[e] = bf2f((unsigned)(unsigned short)kk[ks][e]) * w[ks][e];
;         u32x4 wf; wf.x = cvt_pk_bf16(f[0], f[1]); wf.y = cvt_pk_bf16(f[2], f[3]); wf.z = cvt_pk_bf16(f[4], f[5]); wf.w = cvt_pk_bf16(f[6], f[7]);
;         acc = __builtin_amdgcn_mfma_f32_16x16x32_bf16(__builtin_bit_cast(bf16x8, wf), vv[ks], acc, 0, 0, 0);
;     }
;     if (st) { u32x2 o; o.x = cvt_pk_bf16(S[0], S[1]); o.y = cvt_pk_bf16(S[2], S[3]); *(u32x2*)dst = o; }
;     S = S * gC + acc;
; }
; __device__ __forceinline__ void r1s_sweep(const bf16_t* __restrict__ kT, const bf16_t* __restrict__ vT, bf16_t* __restrict__ STd, int bh, int s, int wid, int fr, int fq, float lg, float gC, bool fwd) {
;     ...
; #pragma unroll
;     for (int i = 0; i < 18; i += 2) {
;         r1s_load(kT, vT, bh, R1S_CC(i + 1), koff, voff, kB, vB);
;         { const int cc = R1S_CC(i); r1s_step(kA, vA, w, S, gC, cc >= 2, dst0 + (size_t)(cc >= 2 ? cc - 2 : 0) * 16384); }
;         if (i + 2 < 18) r1s_load(kT, vT, bh, R1S_CC(i + 2), koff, voff, kA, vA);
;         { const int cc = R1S_CC(i + 1); r1s_step(kB, vB, w, S, gC, cc >= 2, dst0 + (size_t)(cc >= 2 ? cc - 2 : 0) * 16384); }
;     }
	v_lshlrev_b32_e32 v44, 16, v2
	v_lshlrev_b32_e32 v45, 16, v3
	v_lshlrev_b32_e32 v46, 16, v4
	v_lshlrev_b32_e32 v47, 16, v5
	v_and_b32_e32 v2, 0xffff0000, v2
	v_and_b32_e32 v3, 0xffff0000, v3
	v_and_b32_e32 v4, 0xffff0000, v4
	v_and_b32_e32 v5, 0xffff0000, v5
	v_mul_f32_e32 v44, v224, v44
	v_mul_f32_e32 v45, v226, v45
	v_mul_f32_e32 v46, v228, v46
	v_mul_f32_e32 v47, v230, v47
	v_mul_f32_e32 v2, v225, v2
	v_mul_f32_e32 v3, v227, v3
	v_mul_f32_e32 v4, v229, v4
	v_mul_f32_e32 v5, v231, v5
	v_cvt_pk_bf16_f32 v44, v44, v2
	v_cvt_pk_bf16_f32 v45, v45, v3
	v_cvt_pk_bf16_f32 v46, v46, v4
	v_cvt_pk_bf16_f32 v47, v47, v5
	v_lshlrev_b32_e32 v86, 16, v6
	v_lshlrev_b32_e32 v87, 16, v7
	v_lshlrev_b32_e32 v88, 16, v8
	v_lshlrev_b32_e32 v89, 16, v9
	v_and_b32_e32 v6, 0xffff0000, v6
	v_and_b32_e32 v7, 0xffff0000, v7
	v_and_b32_e32 v8, 0xffff0000, v8
	v_and_b32_e32 v9, 0xffff0000, v9
	v_mul_f32_e32 v86, v232, v86
	v_mul_f32_e32 v87, v234, v87
	v_mul_f32_e32 v88, v236, v88
	v_mul_f32_e32 v89, v238, v89
	v_mul_f32_e32 v6, v233, v6
	v_mul_f32_e32 v7, v235, v7
	v_mul_f32_e32 v8, v237, v8
	v_mul_f32_e32 v9, v239, v9
	v_cvt_pk_bf16_f32 v86, v86, v6
	v_cvt_pk_bf16_f32 v87, v87, v7
	v_cvt_pk_bf16_f32 v88, v88, v8
	v_cvt_pk_bf16_f32 v89, v89, v9
	s_nop 0
	v_mfma_f32_16x16x32_bf16 v[40:43], v[44:47], v[70:73], 0
	v_lshlrev_b32_e32 v44, 16, v10
	v_lshlrev_b32_e32 v45, 16, v11
	v_lshlrev_b32_e32 v46, 16, v12
	v_lshlrev_b32_e32 v47, 16, v13
	v_and_b32_e32 v10, 0xffff0000, v10
	v_and_b32_e32 v11, 0xffff0000, v11
	v_and_b32_e32 v12, 0xffff0000, v12
	v_and_b32_e32 v13, 0xffff0000, v13
	v_mul_f32_e32 v44, v240, v44
	v_mul_f32_e32 v45, v242, v45
	v_mul_f32_e32 v46, v244, v46
	v_mul_f32_e32 v47, v246, v47
	v_mul_f32_e32 v10, v241, v10
	v_mul_f32_e32 v11, v243, v11
	v_mul_f32_e32 v12, v245, v12
	v_mul_f32_e32 v13, v247, v13
	v_cvt_pk_bf16_f32 v44, v44, v10
	v_cvt_pk_bf16_f32 v45, v45, v11
	v_cvt_pk_bf16_f32 v46, v46, v12
	v_cvt_pk_bf16_f32 v47, v47, v13
	v_mfma_f32_16x16x32_bf16 v[40:43], v[86:89], v[74:77], v[40:43]
	v_lshlrev_b32_e32 v86, 16, v14
	v_lshlrev_b32_e32 v87, 16, v15
	v_lshlrev_b32_e32 v88, 16, v16
	v_lshlrev_b32_e32 v89, 16, v17
	v_and_b32_e32 v14, 0xffff0000, v14
	v_and_b32_e32 v15, 0xffff0000, v15
	v_and_b32_e32 v16, 0xffff0000, v16
	v_and_b32_e32 v17, 0xffff0000, v17
	v_mul_f32_e32 v86, v248, v86
	v_mul_f32_e32 v87, v250, v87
	v_mul_f32_e32 v88, v210, v88
	v_mul_f32_e32 v89, v212, v89
	v_mul_f32_e32 v14, v249, v14
	v_mul_f32_e32 v15, v251, v15
	v_mul_f32_e32 v16, v211, v16
	v_mul_f32_e32 v17, v213, v17
	v_cvt_pk_bf16_f32 v86, v86, v14
	v_cvt_pk_bf16_f32 v87, v87, v15
	v_cvt_pk_bf16_f32 v88, v88, v16
	v_cvt_pk_bf16_f32 v89, v89, v17
	v_mfma_f32_16x16x32_bf16 v[40:43], v[44:47], v[78:81], v[40:43]
	s_nop 1
	v_mfma_f32_16x16x32_bf16 v[40:43], v[86:89], v[82:85], v[40:43]
	s_nop 7
	v_pk_fma_f32 v[36:37], v[90:91], v[36:37], v[40:41] op_sel_hi:[0,1,1]
	v_pk_fma_f32 v[38:39], v[90:91], v[38:39], v[42:43] op_sel_hi:[0,1,1]
	s_add_u32 s8, s16, 0x18000
	s_addc_u32 s9, s17, 0
	s_add_u32 s10, s18, 0x18000
	s_addc_u32 s11, s19, 0
	global_load_dwordx4 v[2:5], v170, s[8:9]
	global_load_dwordx4 v[6:9], v170, s[8:9] offset:64
	global_load_dwordx4 v[10:13], v170, s[8:9] offset:128
	global_load_dwordx4 v[14:17], v170, s[8:9] offset:192
	global_load_dwordx4 v[70:73], v171, s[10:11]
	global_load_dwordx4 v[74:77], v171, s[10:11] offset:64
	global_load_dwordx4 v[78:81], v171, s[10:11] offset:128
	global_load_dwordx4 v[82:85], v171, s[10:11] offset:192
	s_waitcnt vmcnt(16)
	v_lshlrev_b32_e32 v44, 16, v20
	v_lshlrev_b32_e32 v45, 16, v21
	v_lshlrev_b32_e32 v46, 16, v22
	v_lshlrev_b32_e32 v47, 16, v23
	v_and_b32_e32 v20, 0xffff0000, v20
	v_and_b32_e32 v21, 0xffff0000, v21
	v_and_b32_e32 v22, 0xffff0000, v22
	v_and_b32_e32 v23, 0xffff0000, v23
	v_mul_f32_e32 v44, v224, v44
	v_mul_f32_e32 v45, v226, v45
	v_mul_f32_e32 v46, v228, v46
	v_mul_f32_e32 v47, v230, v47
	v_mul_f32_e32 v20, v225, v20
	v_mul_f32_e32 v21, v227, v21
	v_mul_f32_e32 v22, v229, v22
	v_mul_f32_e32 v23, v231, v23
	v_cvt_pk_bf16_f32 v44, v44, v20
	v_cvt_pk_bf16_f32 v45, v45, v21
	v_cvt_pk_bf16_f32 v46, v46, v22
	v_cvt_pk_bf16_f32 v47, v47, v23
	v_lshlrev_b32_e32 v86, 16, v24
	v_lshlrev_b32_e32 v87, 16, v25
	v_lshlrev_b32_e32 v88, 16, v26
	v_lshlrev_b32_e32 v89, 16, v27
	v_and_b32_e32 v24, 0xffff0000, v24
	v_and_b32_e32 v25, 0xffff0000, v25
	v_and_b32_e32 v26, 0xffff0000, v26
	v_and_b32_e32 v27, 0xffff0000, v27
	v_mul_f32_e32 v86, v232, v86
	v_mul_f32_e32 v87, v234, v87
	v_mul_f32_e32 v88, v236, v88
	v_mul_f32_e32 v89, v238, v89
	v_mul_f32_e32 v24, v233, v24
	v_mul_f32_e32 v25, v235, v25
	v_mul_f32_e32 v26, v237, v26
	v_mul_f32_e32 v27, v239, v27
	v_cvt_pk_bf16_f32 v86, v86, v24
	v_cvt_pk_bf16_f32 v87, v87, v25
	v_cvt_pk_bf16_f32 v88, v88, v26
	v_cvt_pk_bf16_f32 v89, v89, v27
	s_nop 0
	v_mfma_f32_16x16x32_bf16 v[40:43], v[44:47], v[94:97], 0
	v_lshlrev_b32_e32 v44, 16, v28
	v_lshlrev_b32_e32 v45, 16, v29
	v_lshlrev_b32_e32 v46, 16, v30
	v_lshlrev_b32_e32 v47, 16, v31
	v_and_b32_e32 v28, 0xffff0000, v28
	v_and_b32_e32 v29, 0xffff0000, v29
	v_and_b32_e32 v30, 0xffff0000, v30
	v_and_b32_e32 v31, 0xffff0000, v31
	v_mul_f32_e32 v44, v240, v44
	v_mul_f32_e32 v45, v242, v45
	v_mul_f32_e32 v46, v244, v46
	v_mul_f32_e32 v47, v246, v47
	v_mul_f32_e32 v28, v241, v28
	v_mul_f32_e32 v29, v243, v29
	v_mul_f32_e32 v30, v245, v30
	v_mul_f32_e32 v31, v247, v31
	v_cvt_pk_bf16_f32 v44, v44, v28
	v_cvt_pk_bf16_f32 v45, v45, v29
	v_cvt_pk_bf16_f32 v46, v46, v30
	v_cvt_pk_bf16_f32 v47, v47, v31
	v_mfma_f32_16x16x32_bf16 v[40:43], v[86:89], v[98:101], v[40:43]
	v_lshlrev_b32_e32 v86, 16, v32
	v_lshlrev_b32_e32 v87, 16, v33
; __device__ __forceinline__ unsigned cvt_pk_bf16(float lo, float hi) { unsigned r; asm("v_cvt_pk_bf16_f32 %0, %1, %2" : "=v"(r) : "v"(lo), "v"(hi)); return r; }
; __device__ __forceinline__ float bf2f(unsigned b) { return __uint_as_float(b << 16); }
; __device__ __forceinline__ void r1s_step(const bf16x8 (&kk)[4], const bf16x8 (&vv)[4], const float (&w)[4][8], f32x4& S, float gC, bool st, bf16_t* dst) {
;     f32x4 acc = {0.f, 0.f, 0.f, 0.f};
; #pragma unroll
;     for (int ks = 0; ks < 4; ++ks) {
;         float f[8];
; #pragma unroll
;         for (int e = 0; e < 8; ++e) f[e] = bf2f((unsigned)(unsigned short)kk[ks][e]) * w[ks][e];
;         u32x4 wf; wf.x = cvt_pk_bf16(f[0], f[1]); wf.y = cvt_pk_bf16(f[2], f[3]); wf.z = cvt_pk_bf16(f[4], f[5]); wf.w = cvt_pk_bf16(f[6], f[7]);
;         acc = __builtin_amdgcn_mfma_f32_16x16x32_bf16(__builtin_bit_cast(bf16x8, wf), vv[ks], acc, 0, 0, 0);
;     }
;     if (st) { u32x2 o; o.x = cvt_pk_bf16(S[0], S[1]); o.y = cvt_pk_bf16(S[2], S[3]); *(u32x2*)dst = o; }
;     S = S * gC + acc;
; }
; __device__ __forceinline__ void r1s_sweep(const bf16_t* __restrict__ kT, const bf16_t* __restrict__ vT, bf16_t* __restrict__ STd, int bh, int s, int wid, int fr, int fq, float lg, float gC, bool fwd) {
;     ...
; #pragma unroll
;     for (int i = 0; i < 18; i += 2) {
;         r1s_load(kT, vT, bh, R1S_CC(i + 1), koff, voff, kB, vB);
;         { const int cc = R1S_CC(i); r1s_step(kA, vA, w, S, gC, cc >= 2, dst0 + (size_t)(cc >= 2 ? cc - 2 : 0) * 16384); }
;         if (i + 2 < 18) r1s_load(kT, vT, bh, R1S_CC(i + 2), koff, voff, kA, vA);
;         { const int cc = R1S_CC(i + 1); r1s_step(kB, vB, w, S, gC, cc >= 2, dst0 + (size_t)(cc >= 2 ? cc - 2 : 0) * 16384); }
;     }
	v_lshlrev_b32_e32 v88, 16, v34
	v_lshlrev_b32_e32 v89, 16, v35
	v_and_b32_e32 v32, 0xffff0000, v32
	v_and_b32_e32 v33, 0xffff0000, v33
	v_and_b32_e32 v34, 0xffff0000, v34
	v_and_b32_e32 v35, 0xffff0000, v35
	v_mul_f32_e32 v86, v248, v86
	v_mul_f32_e32 v87, v250, v87
	v_mul_f32_e32 v88, v210, v88
	v_mul_f32_e32 v89, v212, v89
	v_mul_f32_e32 v32, v249, v32
	v_mul_f32_e32 v33, v251, v33
	v_mul_f32_e32 v34, v211, v34
	v_mul_f32_e32 v35, v213, v35
	v_cvt_pk_bf16_f32 v86, v86, v32
	v_cvt_pk_bf16_f32 v87, v87, v33
	v_cvt_pk_bf16_f32 v88, v88, v34
	v_cvt_pk_bf16_f32 v89, v89, v35
	v_mfma_f32_16x16x32_bf16 v[40:43], v[44:47], v[102:105], v[40:43]
	s_nop 1
	v_mfma_f32_16x16x32_bf16 v[40:43], v[86:89], v[106:109], v[40:43]
	s_nop 7
	v_pk_fma_f32 v[36:37], v[90:91], v[36:37], v[40:41] op_sel_hi:[0,1,1]
	v_pk_fma_f32 v[38:39], v[90:91], v[38:39], v[42:43] op_sel_hi:[0,1,1]
	s_add_u32 s8, s16, 0x20000
	s_addc_u32 s9, s17, 0
	s_add_u32 s10, s18, 0x20000
	s_addc_u32 s11, s19, 0
	global_load_dwordx4 v[20:23], v170, s[8:9]
	global_load_dwordx4 v[24:27], v170, s[8:9] offset:64
	global_load_dwordx4 v[28:31], v170, s[8:9] offset:128
	global_load_dwordx4 v[32:35], v170, s[8:9] offset:192
	global_load_dwordx4 v[94:97], v171, s[10:11]
	global_load_dwordx4 v[98:101], v171, s[10:11] offset:64
	global_load_dwordx4 v[102:105], v171, s[10:11] offset:128
	global_load_dwordx4 v[106:109], v171, s[10:11] offset:192
	s_waitcnt vmcnt(16)
	v_lshlrev_b32_e32 v44, 16, v54
	v_lshlrev_b32_e32 v45, 16, v55
	v_lshlrev_b32_e32 v46, 16, v56
	v_lshlrev_b32_e32 v47, 16, v57
	v_and_b32_e32 v54, 0xffff0000, v54
	v_and_b32_e32 v55, 0xffff0000, v55
	v_and_b32_e32 v56, 0xffff0000, v56
	v_and_b32_e32 v57, 0xffff0000, v57
	v_mul_f32_e32 v44, v224, v44
	v_mul_f32_e32 v45, v226, v45
	v_mul_f32_e32 v46, v228, v46
	v_mul_f32_e32 v47, v230, v47
	v_mul_f32_e32 v54, v225, v54
	v_mul_f32_e32 v55, v227, v55
	v_mul_f32_e32 v56, v229, v56
	v_mul_f32_e32 v57, v231, v57
	v_cvt_pk_bf16_f32 v44, v44, v54
	v_cvt_pk_bf16_f32 v45, v45, v55
	v_cvt_pk_bf16_f32 v46, v46, v56
	v_cvt_pk_bf16_f32 v47, v47, v57
	v_lshlrev_b32_e32 v86, 16, v58
	v_lshlrev_b32_e32 v87, 16, v59
	v_lshlrev_b32_e32 v88, 16, v60
	v_lshlrev_b32_e32 v89, 16, v61
	v_and_b32_e32 v58, 0xffff0000, v58
	v_and_b32_e32 v59, 0xffff0000, v59
	v_and_b32_e32 v60, 0xffff0000, v60
	v_and_b32_e32 v61, 0xffff0000, v61
	v_mul_f32_e32 v86, v232, v86
	v_mul_f32_e32 v87, v234, v87
	v_mul_f32_e32 v88, v236, v88
	v_mul_f32_e32 v89, v238, v89
	v_mul_f32_e32 v58, v233, v58
	v_mul_f32_e32 v59, v235, v59
	v_mul_f32_e32 v60, v237, v60
	v_mul_f32_e32 v61, v239, v61
	v_cvt_pk_bf16_f32 v86, v86, v58
	v_cvt_pk_bf16_f32 v87, v87, v59
	v_cvt_pk_bf16_f32 v88, v88, v60
	v_cvt_pk_bf16_f32 v89, v89, v61
	s_nop 0
	v_mfma_f32_16x16x32_bf16 v[40:43], v[44:47], v[110:113], 0
	v_lshlrev_b32_e32 v44, 16, v62
	v_lshlrev_b32_e32 v45, 16, v63
	v_lshlrev_b32_e32 v46, 16, v64
	v_lshlrev_b32_e32 v47, 16, v65
	v_and_b32_e32 v62, 0xffff0000, v62
	v_and_b32_e32 v63, 0xffff0000, v63
	v_and_b32_e32 v64, 0xffff0000, v64
	v_and_b32_e32 v65, 0xffff0000, v65
	v_mul_f32_e32 v44, v240, v44
	v_mul_f32_e32 v45, v242, v45
	v_mul_f32_e32 v46, v244, v46
	v_mul_f32_e32 v47, v246, v47
	v_mul_f32_e32 v62, v241, v62
	v_mul_f32_e32 v63, v243, v63
	v_mul_f32_e32 v64, v245, v64
	v_mul_f32_e32 v65, v247, v65
	v_cvt_pk_bf16_f32 v44, v44, v62
	v_cvt_pk_bf16_f32 v45, v45, v63
	v_cvt_pk_bf16_f32 v46, v46, v64
	v_cvt_pk_bf16_f32 v47, v47, v65
	v_mfma_f32_16x16x32_bf16 v[40:43], v[86:89], v[114:117], v[40:43]
	v_lshlrev_b32_e32 v86, 16, v66
	v_lshlrev_b32_e32 v87, 16, v67
	v_lshlrev_b32_e32 v88, 16, v68
	v_lshlrev_b32_e32 v89, 16, v69
	v_and_b32_e32 v66, 0xffff0000, v66
	v_and_b32_e32 v67, 0xffff0000, v67
	v_and_b32_e32 v68, 0xffff0000, v68
	v_and_b32_e32 v69, 0xffff0000, v69
	v_mul_f32_e32 v86, v248, v86
	v_mul_f32_e32 v87, v250, v87
	v_mul_f32_e32 v88, v210, v88
	v_mul_f32_e32 v89, v212, v89
	v_mul_f32_e32 v66, v249, v66
	v_mul_f32_e32 v67, v251, v67
	v_mul_f32_e32 v68, v211, v68
	v_mul_f32_e32 v69, v213, v69
	v_cvt_pk_bf16_f32 v86, v86, v66
	v_cvt_pk_bf16_f32 v87, v87, v67
	v_cvt_pk_bf16_f32 v88, v88, v68
	v_cvt_pk_bf16_f32 v89, v89, v69
	v_mfma_f32_16x16x32_bf16 v[40:43], v[44:47], v[118:121], v[40:43]
	s_nop 1
	v_mfma_f32_16x16x32_bf16 v[40:43], v[86:89], v[122:125], v[40:43]
	s_add_u32 s8, s20, 0x0
	s_addc_u32 s9, s21, 0
	v_cvt_pk_bf16_f32 v48, v36, v37
	v_cvt_pk_bf16_f32 v49, v38, v39
	global_store_dwordx2 v172, v[48:49], s[8:9]
	s_nop 7
	v_pk_fma_f32 v[36:37], v[90:91], v[36:37], v[40:41] op_sel_hi:[0,1,1]
	v_pk_fma_f32 v[38:39], v[90:91], v[38:39], v[42:43] op_sel_hi:[0,1,1]
	s_add_u32 s8, s16, 0x28000
	s_addc_u32 s9, s17, 0
	s_add_u32 s10, s18, 0x28000
	s_addc_u32 s11, s19, 0
	global_load_dwordx4 v[54:57], v170, s[8:9]
	global_load_dwordx4 v[58:61], v170, s[8:9] offset:64
	global_load_dwordx4 v[62:65], v170, s[8:9] offset:128
	global_load_dwordx4 v[66:69], v170, s[8:9] offset:192
	global_load_dwordx4 v[110:113], v171, s[10:11]
	global_load_dwordx4 v[114:117], v171, s[10:11] offset:64
	global_load_dwordx4 v[118:121], v171, s[10:11] offset:128
	global_load_dwordx4 v[122:125], v171, s[10:11] offset:192
	s_waitcnt vmcnt(17)
; __device__ __forceinline__ unsigned cvt_pk_bf16(float lo, float hi) { unsigned r; asm("v_cvt_pk_bf16_f32 %0, %1, %2" : "=v"(r) : "v"(lo), "v"(hi)); return r; }
; __device__ __forceinline__ float bf2f(unsigned b) { return __uint_as_float(b << 16); }
; __device__ __forceinline__ void r1s_step(const bf16x8 (&kk)[4], const bf16x8 (&vv)[4], const float (&w)[4][8], f32x4& S, float gC, bool st, bf16_t* dst) {
;     f32x4 acc = {0.f, 0.f, 0.f, 0.f};
; #pragma unroll
;     for (int ks = 0; ks < 4; ++ks) {
;         float f[8];
; #pragma unroll
;         for (int e = 0; e < 8; ++e) f[e] = bf2f((unsigned)(unsigned short)kk[ks][e]) * w[ks][e];
;         u32x4 wf; wf.x = cvt_pk_bf16(f[0], f[1]); wf.y = cvt_pk_bf16(f[2], f[3]); wf.z = cvt_pk_bf16(f[4], f[5]); wf.w = cvt_pk_bf16(f[6], f[7]);
;         acc = __builtin_amdgcn_mfma_f32_16x16x32_bf16(__builtin_bit_cast(bf16x8, wf), vv[ks], acc, 0, 0, 0);
;     }
;     if (st) { u32x2 o; o.x = cvt_pk_bf16(S[0], S[1]); o.y = cvt_pk_bf16(S[2], S[3]); *(u32x2*)dst = o; }
;     S = S * gC + acc;
; }
; __device__ __forceinline__ void r1s_sweep(const bf16_t* __restrict__ kT, const bf16_t* __restrict__ vT, bf16_t* __restrict__ STd, int bh, int s, int wid, int fr, int fq, float lg, float gC, bool fwd) {
;     ...
; #pragma unroll
;     for (int i = 0; i < 18; i += 2) {
;         r1s_load(kT, vT, bh, R1S_CC(i + 1), koff, voff, kB, vB);
;         { const int cc = R1S_CC(i); r1s_step(kA, vA, w, S, gC, cc >= 2, dst0 + (size_t)(cc >= 2 ? cc - 2 : 0) * 16384); }
;         if (i + 2 < 18) r1s_load(kT, vT, bh, R1S_CC(i + 2), koff, voff, kA, vA);
;         { const int cc = R1S_CC(i + 1); r1s_step(kB, vB, w, S, gC, cc >= 2, dst0 + (size_t)(cc >= 2 ? cc - 2 : 0) * 16384); }
;     }
	v_lshlrev_b32_e32 v44, 16, v2
	v_lshlrev_b32_e32 v45, 16, v3
	v_lshlrev_b32_e32 v46, 16, v4
	v_lshlrev_b32_e32 v47, 16, v5
	v_and_b32_e32 v2, 0xffff0000, v2
	v_and_b32_e32 v3, 0xffff0000, v3
	v_and_b32_e32 v4, 0xffff0000, v4
	v_and_b32_e32 v5, 0xffff0000, v5
	v_mul_f32_e32 v44, v224, v44
	v_mul_f32_e32 v45, v226, v45
	v_mul_f32_e32 v46, v228, v46
	v_mul_f32_e32 v47, v230, v47
	v_mul_f32_e32 v2, v225, v2
	v_mul_f32_e32 v3, v227, v3
	v_mul_f32_e32 v4, v229, v4
	v_mul_f32_e32 v5, v231, v5
	v_cvt_pk_bf16_f32 v44, v44, v2
	v_cvt_pk_bf16_f32 v45, v45, v3
	v_cvt_pk_bf16_f32 v46, v46, v4
	v_cvt_pk_bf16_f32 v47, v47, v5
	v_lshlrev_b32_e32 v86, 16, v6
	v_lshlrev_b32_e32 v87, 16, v7
	v_lshlrev_b32_e32 v88, 16, v8
	v_lshlrev_b32_e32 v89, 16, v9
	v_and_b32_e32 v6, 0xffff0000, v6
	v_and_b32_e32 v7, 0xffff0000, v7
	v_and_b32_e32 v8, 0xffff0000, v8
	v_and_b32_e32 v9, 0xffff0000, v9
	v_mul_f32_e32 v86, v232, v86
	v_mul_f32_e32 v87, v234, v87
	v_mul_f32_e32 v88, v236, v88
	v_mul_f32_e32 v89, v238, v89
	v_mul_f32_e32 v6, v233, v6
	v_mul_f32_e32 v7, v235, v7
	v_mul_f32_e32 v8, v237, v8
	v_mul_f32_e32 v9, v239, v9
	v_cvt_pk_bf16_f32 v86, v86, v6
	v_cvt_pk_bf16_f32 v87, v87, v7
	v_cvt_pk_bf16_f32 v88, v88, v8
	v_cvt_pk_bf16_f32 v89, v89, v9
	s_nop 0
	v_mfma_f32_16x16x32_bf16 v[40:43], v[44:47], v[70:73], 0
	v_lshlrev_b32_e32 v44, 16, v10
	v_lshlrev_b32_e32 v45, 16, v11
	v_lshlrev_b32_e32 v46, 16, v12
	v_lshlrev_b32_e32 v47, 16, v13
	v_and_b32_e32 v10, 0xffff0000, v10
	v_and_b32_e32 v11, 0xffff0000, v11
	v_and_b32_e32 v12, 0xffff0000, v12
	v_and_b32_e32 v13, 0xffff0000, v13
	v_mul_f32_e32 v44, v240, v44
	v_mul_f32_e32 v45, v242, v45
	v_mul_f32_e32 v46, v244, v46
	v_mul_f32_e32 v47, v246, v47
	v_mul_f32_e32 v10, v241, v10
	v_mul_f32_e32 v11, v243, v11
	v_mul_f32_e32 v12, v245, v12
	v_mul_f32_e32 v13, v247, v13
	v_cvt_pk_bf16_f32 v44, v44, v10
	v_cvt_pk_bf16_f32 v45, v45, v11
	v_cvt_pk_bf16_f32 v46, v46, v12
	v_cvt_pk_bf16_f32 v47, v47, v13
	v_mfma_f32_16x16x32_bf16 v[40:43], v[86:89], v[74:77], v[40:43]
	v_lshlrev_b32_e32 v86, 16, v14
	v_lshlrev_b32_e32 v87, 16, v15
	v_lshlrev_b32_e32 v88, 16, v16
	v_lshlrev_b32_e32 v89, 16, v17
	v_and_b32_e32 v14, 0xffff0000, v14
	v_and_b32_e32 v15, 0xffff0000, v15
	v_and_b32_e32 v16, 0xffff0000, v16
	v_and_b32_e32 v17, 0xffff0000, v17
	v_mul_f32_e32 v86, v248, v86
	v_mul_f32_e32 v87, v250, v87
	v_mul_f32_e32 v88, v210, v88
	v_mul_f32_e32 v89, v212, v89
	v_mul_f32_e32 v14, v249, v14
	v_mul_f32_e32 v15, v251, v15
	v_mul_f32_e32 v16, v211, v16
	v_mul_f32_e32 v17, v213, v17
	v_cvt_pk_bf16_f32 v86, v86, v14
	v_cvt_pk_bf16_f32 v87, v87, v15
	v_cvt_pk_bf16_f32 v88, v88, v16
	v_cvt_pk_bf16_f32 v89, v89, v17
	v_mfma_f32_16x16x32_bf16 v[40:43], v[44:47], v[78:81], v[40:43]
	s_nop 1
	v_mfma_f32_16x16x32_bf16 v[40:43], v[86:89], v[82:85], v[40:43]
	s_add_u32 s8, s20, 0x8000
	s_addc_u32 s9, s21, 0
	v_cvt_pk_bf16_f32 v48, v36, v37
	v_cvt_pk_bf16_f32 v49, v38, v39
	global_store_dwordx2 v172, v[48:49], s[8:9]
	s_nop 7
	v_pk_fma_f32 v[36:37], v[90:91], v[36:37], v[40:41] op_sel_hi:[0,1,1]
	v_pk_fma_f32 v[38:39], v[90:91], v[38:39], v[42:43] op_sel_hi:[0,1,1]
	s_add_u32 s8, s16, 0x30000
	s_addc_u32 s9, s17, 0
	s_add_u32 s10, s18, 0x30000
	s_addc_u32 s11, s19, 0
	global_load_dwordx4 v[2:5], v170, s[8:9]
	global_load_dwordx4 v[6:9], v170, s[8:9] offset:64
	global_load_dwordx4 v[10:13], v170, s[8:9] offset:128
	global_load_dwordx4 v[14:17], v170, s[8:9] offset:192
	global_load_dwordx4 v[70:73], v171, s[10:11]
	global_load_dwordx4 v[74:77], v171, s[10:11] offset:64
	global_load_dwordx4 v[78:81], v171, s[10:11] offset:128
	global_load_dwordx4 v[82:85], v171, s[10:11] offset:192
	s_waitcnt vmcnt(18)
	v_lshlrev_b32_e32 v44, 16, v20
	v_lshlrev_b32_e32 v45, 16, v21
	v_lshlrev_b32_e32 v46, 16, v22
	v_lshlrev_b32_e32 v47, 16, v23
	v_and_b32_e32 v20, 0xffff0000, v20
	v_and_b32_e32 v21, 0xffff0000, v21
	v_and_b32_e32 v22, 0xffff0000, v22
	v_and_b32_e32 v23, 0xffff0000, v23
	v_mul_f32_e32 v44, v224, v44
	v_mul_f32_e32 v45, v226, v45
	v_mul_f32_e32 v46, v228, v46
	v_mul_f32_e32 v47, v230, v47
	v_mul_f32_e32 v20, v225, v20
	v_mul_f32_e32 v21, v227, v21
	v_mul_f32_e32 v22, v229, v22
	v_mul_f32_e32 v23, v231, v23
	v_cvt_pk_bf16_f32 v44, v44, v20
	v_cvt_pk_bf16_f32 v45, v45, v21
	v_cvt_pk_bf16_f32 v46, v46, v22
	v_cvt_pk_bf16_f32 v47, v47, v23
	v_lshlrev_b32_e32 v86, 16, v24
	v_lshlrev_b32_e32 v87, 16, v25
	v_lshlrev_b32_e32 v88, 16, v26
	v_lshlrev_b32_e32 v89, 16, v27
	v_and_b32_e32 v24, 0xffff0000, v24
	v_and_b32_e32 v25, 0xffff0000, v25
	v_and_b32_e32 v26, 0xffff0000, v26
	v_and_b32_e32 v27, 0xffff0000, v27
	v_mul_f32_e32 v86, v232, v86
	v_mul_f32_e32 v87, v234, v87
	v_mul_f32_e32 v88, v236, v88
	v_mul_f32_e32 v89, v238, v89
	v_mul_f32_e32 v24, v233, v24
	v_mul_f32_e32 v25, v235, v25
	v_mul_f32_e32 v26, v237, v26
	v_mul_f32_e32 v27, v239, v27
	v_cvt_pk_bf16_f32 v86, v86, v24
	v_cvt_pk_bf16_f32 v87, v87, v25
	v_cvt_pk_bf16_f32 v88, v88, v26
	v_cvt_pk_bf16_f32 v89, v89, v27
	s_nop 0
	v_mfma_f32_16x16x32_bf16 v[40:43], v[44:47], v[94:97], 0
	v_lshlrev_b32_e32 v44, 16, v28
	v_lshlrev_b32_e32 v45, 16, v29
	v_lshlrev_b32_e32 v46, 16, v30
	v_lshlrev_b32_e32 v47, 16, v31
	v_and_b32_e32 v28, 0xffff0000, v28
	v_and_b32_e32 v29, 0xffff0000, v29
	v_and_b32_e32 v30, 0xffff0000, v30
	v_and_b32_e32 v31, 0xffff0000, v31
	v_mul_f32_e32 v44, v240, v44
	v_mul_f32_e32 v45, v242, v45
	v_mul_f32_e32 v46, v244, v46
	v_mul_f32_e32 v47, v246, v47
	v_mul_f32_e32 v28, v241, v28
	v_mul_f32_e32 v29, v243, v29
	v_mul_f32_e32 v30, v245, v30
	v_mul_f32_e32 v31, v247, v31
	v_cvt_pk_bf16_f32 v44, v44, v28
	v_cvt_pk_bf16_f32 v45, v45, v29
	v_cvt_pk_bf16_f32 v46, v46, v30
	v_cvt_pk_bf16_f32 v47, v47, v31
; __device__ __forceinline__ unsigned cvt_pk_bf16(float lo, float hi) { unsigned r; asm("v_cvt_pk_bf16_f32 %0, %1, %2" : "=v"(r) : "v"(lo), "v"(hi)); return r; }
; __device__ __forceinline__ float bf2f(unsigned b) { return __uint_as_float(b << 16); }
; __device__ __forceinline__ void r1s_step(const bf16x8 (&kk)[4], const bf16x8 (&vv)[4], const float (&w)[4][8], f32x4& S, float gC, bool st, bf16_t* dst) {
;     f32x4 acc = {0.f, 0.f, 0.f, 0.f};
; #pragma unroll
;     for (int ks = 0; ks < 4; ++ks) {
;         float f[8];
; #pragma unroll
;         for (int e = 0; e < 8; ++e) f[e] = bf2f((unsigned)(unsigned short)kk[ks][e]) * w[ks][e];
;         u32x4 wf; wf.x = cvt_pk_bf16(f[0], f[1]); wf.y = cvt_pk_bf16(f[2], f[3]); wf.z = cvt_pk_bf16(f[4], f[5]); wf.w = cvt_pk_bf16(f[6], f[7]);
;         acc = __builtin_amdgcn_mfma_f32_16x16x32_bf16(__builtin_bit_cast(bf16x8, wf), vv[ks], acc, 0, 0, 0);
;     }
;     if (st) { u32x2 o; o.x = cvt_pk_bf16(S[0], S[1]); o.y = cvt_pk_bf16(S[2], S[3]); *(u32x2*)dst = o; }
;     S = S * gC + acc;
; }
; __device__ __forceinline__ void r1s_sweep(const bf16_t* __restrict__ kT, const bf16_t* __restrict__ vT, bf16_t* __restrict__ STd, int bh, int s, int wid, int fr, int fq, float lg, float gC, bool fwd) {
;     ...
; #pragma unroll
;     for (int i = 0; i < 18; i += 2) {
;         r1s_load(kT, vT, bh, R1S_CC(i + 1), koff, voff, kB, vB);
;         { const int cc = R1S_CC(i); r1s_step(kA, vA, w, S, gC, cc >= 2, dst0 + (size_t)(cc >= 2 ? cc - 2 : 0) * 16384); }
;         if (i + 2 < 18) r1s_load(kT, vT, bh, R1S_CC(i + 2), koff, voff, kA, vA);
;         { const int cc = R1S_CC(i + 1); r1s_step(kB, vB, w, S, gC, cc >= 2, dst0 + (size_t)(cc >= 2 ? cc - 2 : 0) * 16384); }
;     }
	v_mfma_f32_16x16x32_bf16 v[40:43], v[86:89], v[98:101], v[40:43]
	v_lshlrev_b32_e32 v86, 16, v32
	v_lshlrev_b32_e32 v87, 16, v33
	v_lshlrev_b32_e32 v88, 16, v34
	v_lshlrev_b32_e32 v89, 16, v35
	v_and_b32_e32 v32, 0xffff0000, v32
	v_and_b32_e32 v33, 0xffff0000, v33
	v_and_b32_e32 v34, 0xffff0000, v34
	v_and_b32_e32 v35, 0xffff0000, v35
	v_mul_f32_e32 v86, v248, v86
	v_mul_f32_e32 v87, v250, v87
	v_mul_f32_e32 v88, v210, v88
	v_mul_f32_e32 v89, v212, v89
	v_mul_f32_e32 v32, v249, v32
	v_mul_f32_e32 v33, v251, v33
	v_mul_f32_e32 v34, v211, v34
	v_mul_f32_e32 v35, v213, v35
	v_cvt_pk_bf16_f32 v86, v86, v32
	v_cvt_pk_bf16_f32 v87, v87, v33
	v_cvt_pk_bf16_f32 v88, v88, v34
	v_cvt_pk_bf16_f32 v89, v89, v35
	v_mfma_f32_16x16x32_bf16 v[40:43], v[44:47], v[102:105], v[40:43]
	s_nop 1
	v_mfma_f32_16x16x32_bf16 v[40:43], v[86:89], v[106:109], v[40:43]
	s_add_u32 s8, s20, 0x10000
	s_addc_u32 s9, s21, 0
	v_cvt_pk_bf16_f32 v48, v36, v37
	v_cvt_pk_bf16_f32 v49, v38, v39
	global_store_dwordx2 v172, v[48:49], s[8:9]
	s_nop 7
	v_pk_fma_f32 v[36:37], v[90:91], v[36:37], v[40:41] op_sel_hi:[0,1,1]
	v_pk_fma_f32 v[38:39], v[90:91], v[38:39], v[42:43] op_sel_hi:[0,1,1]
	s_add_u32 s8, s16, 0x38000
	s_addc_u32 s9, s17, 0
	s_add_u32 s10, s18, 0x38000
	s_addc_u32 s11, s19, 0
	global_load_dwordx4 v[20:23], v170, s[8:9]
	global_load_dwordx4 v[24:27], v170, s[8:9] offset:64
	global_load_dwordx4 v[28:31], v170, s[8:9] offset:128
	global_load_dwordx4 v[32:35], v170, s[8:9] offset:192
	global_load_dwordx4 v[94:97], v171, s[10:11]
	global_load_dwordx4 v[98:101], v171, s[10:11] offset:64
	global_load_dwordx4 v[102:105], v171, s[10:11] offset:128
	global_load_dwordx4 v[106:109], v171, s[10:11] offset:192
	s_waitcnt vmcnt(18)
	v_lshlrev_b32_e32 v44, 16, v54
	v_lshlrev_b32_e32 v45, 16, v55
	v_lshlrev_b32_e32 v46, 16, v56
	v_lshlrev_b32_e32 v47, 16, v57
	v_and_b32_e32 v54, 0xffff0000, v54
	v_and_b32_e32 v55, 0xffff0000, v55
	v_and_b32_e32 v56, 0xffff0000, v56
	v_and_b32_e32 v57, 0xffff0000, v57
	v_mul_f32_e32 v44, v224, v44
	v_mul_f32_e32 v45, v226, v45
	v_mul_f32_e32 v46, v228, v46
	v_mul_f32_e32 v47, v230, v47
	v_mul_f32_e32 v54, v225, v54
	v_mul_f32_e32 v55, v227, v55
	v_mul_f32_e32 v56, v229, v56
	v_mul_f32_e32 v57, v231, v57
	v_cvt_pk_bf16_f32 v44, v44, v54
	v_cvt_pk_bf16_f32 v45, v45, v55
	v_cvt_pk_bf16_f32 v46, v46, v56
	v_cvt_pk_bf16_f32 v47, v47, v57
	v_lshlrev_b32_e32 v86, 16, v58
	v_lshlrev_b32_e32 v87, 16, v59
	v_lshlrev_b32_e32 v88, 16, v60
	v_lshlrev_b32_e32 v89, 16, v61
	v_and_b32_e32 v58, 0xffff0000, v58
	v_and_b32_e32 v59, 0xffff0000, v59
	v_and_b32_e32 v60, 0xffff0000, v60
	v_and_b32_e32 v61, 0xffff0000, v61
	v_mul_f32_e32 v86, v232, v86
	v_mul_f32_e32 v87, v234, v87
	v_mul_f32_e32 v88, v236, v88
	v_mul_f32_e32 v89, v238, v89
	v_mul_f32_e32 v58, v233, v58
	v_mul_f32_e32 v59, v235, v59
	v_mul_f32_e32 v60, v237, v60
	v_mul_f32_e32 v61, v239, v61
	v_cvt_pk_bf16_f32 v86, v86, v58
	v_cvt_pk_bf16_f32 v87, v87, v59
	v_cvt_pk_bf16_f32 v88, v88, v60
	v_cvt_pk_bf16_f32 v89, v89, v61
	s_nop 0
	v_mfma_f32_16x16x32_bf16 v[40:43], v[44:47], v[110:113], 0
	v_lshlrev_b32_e32 v44, 16, v62
	v_lshlrev_b32_e32 v45, 16, v63
	v_lshlrev_b32_e32 v46, 16, v64
	v_lshlrev_b32_e32 v47, 16, v65
	v_and_b32_e32 v62, 0xffff0000, v62
	v_and_b32_e32 v63, 0xffff0000, v63
	v_and_b32_e32 v64, 0xffff0000, v64
	v_and_b32_e32 v65, 0xffff0000, v65
	v_mul_f32_e32 v44, v240, v44
	v_mul_f32_e32 v45, v242, v45
	v_mul_f32_e32 v46, v244, v46
	v_mul_f32_e32 v47, v246, v47
	v_mul_f32_e32 v62, v241, v62
	v_mul_f32_e32 v63, v243, v63
	v_mul_f32_e32 v64, v245, v64
	v_mul_f32_e32 v65, v247, v65
	v_cvt_pk_bf16_f32 v44, v44, v62
	v_cvt_pk_bf16_f32 v45, v45, v63
	v_cvt_pk_bf16_f32 v46, v46, v64
	v_cvt_pk_bf16_f32 v47, v47, v65
	v_mfma_f32_16x16x32_bf16 v[40:43], v[86:89], v[114:117], v[40:43]
	v_lshlrev_b32_e32 v86, 16, v66
	v_lshlrev_b32_e32 v87, 16, v67
	v_lshlrev_b32_e32 v88, 16, v68
	v_lshlrev_b32_e32 v89, 16, v69
	v_and_b32_e32 v66, 0xffff0000, v66
	v_and_b32_e32 v67, 0xffff0000, v67
	v_and_b32_e32 v68, 0xffff0000, v68
	v_and_b32_e32 v69, 0xffff0000, v69
	v_mul_f32_e32 v86, v248, v86
	v_mul_f32_e32 v87, v250, v87
	v_mul_f32_e32 v88, v210, v88
	v_mul_f32_e32 v89, v212, v89
	v_mul_f32_e32 v66, v249, v66
	v_mul_f32_e32 v67, v251, v67
	v_mul_f32_e32 v68, v211, v68
	v_mul_f32_e32 v69, v213, v69
	v_cvt_pk_bf16_f32 v86, v86, v66
	v_cvt_pk_bf16_f32 v87, v87, v67
	v_cvt_pk_bf16_f32 v88, v88, v68
	v_cvt_pk_bf16_f32 v89, v89, v69
	v_mfma_f32_16x16x32_bf16 v[40:43], v[44:47], v[118:121], v[40:43]
	s_nop 1
	v_mfma_f32_16x16x32_bf16 v[40:43], v[86:89], v[122:125], v[40:43]
	s_add_u32 s8, s20, 0x18000
	s_addc_u32 s9, s21, 0
	v_cvt_pk_bf16_f32 v48, v36, v37
	v_cvt_pk_bf16_f32 v49, v38, v39
	global_store_dwordx2 v172, v[48:49], s[8:9]
	s_nop 7
	v_pk_fma_f32 v[36:37], v[90:91], v[36:37], v[40:41] op_sel_hi:[0,1,1]
	v_pk_fma_f32 v[38:39], v[90:91], v[38:39], v[42:43] op_sel_hi:[0,1,1]
	s_add_u32 s8, s16, 0x40000
	s_addc_u32 s9, s17, 0
	s_add_u32 s10, s18, 0x40000
	s_addc_u32 s11, s19, 0
	global_load_dwordx4 v[54:57], v170, s[8:9]
	global_load_dwordx4 v[58:61], v170, s[8:9] offset:64
	global_load_dwordx4 v[62:65], v170, s[8:9] offset:128
	global_load_dwordx4 v[66:69], v170, s[8:9] offset:192
	global_load_dwordx4 v[110:113], v171, s[10:11]
	global_load_dwordx4 v[114:117], v171, s[10:11] offset:64
	global_load_dwordx4 v[118:121], v171, s[10:11] offset:128
	global_load_dwordx4 v[122:125], v171, s[10:11] offset:192
	s_waitcnt vmcnt(18)
; __device__ __forceinline__ unsigned cvt_pk_bf16(float lo, float hi) { unsigned r; asm("v_cvt_pk_bf16_f32 %0, %1, %2" : "=v"(r) : "v"(lo), "v"(hi)); return r; }
; __device__ __forceinline__ float bf2f(unsigned b) { return __uint_as_float(b << 16); }
; __device__ __forceinline__ void r1s_load(const bf16_t* __restrict__ kT, const bf16_t* __restrict__ vT, int bh, int cc, size_t koff, size_t voff, bf16x8 (&kk)[4], bf16x8 (&vv)[4]) {
;     const bf16_t* kt = kT + (size_t)(bh * 18 + cc) * 16384 + koff; const bf16_t* vt = vT + (size_t)(bh * 18 + cc) * 16384 + voff;
; #pragma unroll
;     for (int ks = 0; ks < 4; ++ks) { kk[ks] = *(const bf16x8*)(kt + 32 * ks); vv[ks] = *(const bf16x8*)(vt + 32 * ks); }
; }
; __device__ __forceinline__ void r1s_step(const bf16x8 (&kk)[4], const bf16x8 (&vv)[4], const float (&w)[4][8], f32x4& S, float gC, bool st, bf16_t* dst) {
;     f32x4 acc = {0.f, 0.f, 0.f, 0.f};
; #pragma unroll
;     for (int ks = 0; ks < 4; ++ks) {
;         float f[8];
; #pragma unroll
;         for (int e = 0; e < 8; ++e) f[e] = bf2f((unsigned)(unsigned short)kk[ks][e]) * w[ks][e];
;         u32x4 wf; wf.x = cvt_pk_bf16(f[0], f[1]); wf.y = cvt_pk_bf16(f[2], f[3]); wf.z = cvt_pk_bf16(f[4], f[5]); wf.w = cvt_pk_bf16(f[6], f[7]);
;         acc = __builtin_amdgcn_mfma_f32_16x16x32_bf16(__builtin_bit_cast(bf16x8, wf), vv[ks], acc, 0, 0, 0);
;     }
;     if (st) { u32x2 o; o.x = cvt_pk_bf16(S[0], S[1]); o.y = cvt_pk_bf16(S[2], S[3]); *(u32x2*)dst = o; }
;     S = S * gC + acc;
; }
	v_lshlrev_b32_e32 v44, 16, v2
	v_lshlrev_b32_e32 v45, 16, v3
	v_lshlrev_b32_e32 v46, 16, v4
	v_lshlrev_b32_e32 v47, 16, v5
	v_and_b32_e32 v2, 0xffff0000, v2
	v_and_b32_e32 v3, 0xffff0000, v3
	v_and_b32_e32 v4, 0xffff0000, v4
	v_and_b32_e32 v5, 0xffff0000, v5
	v_mul_f32_e32 v44, v224, v44
	v_mul_f32_e32 v45, v226, v45
	v_mul_f32_e32 v46, v228, v46
	v_mul_f32_e32 v47, v230, v47
	v_mul_f32_e32 v2, v225, v2
	v_mul_f32_e32 v3, v227, v3
	v_mul_f32_e32 v4, v229, v4
	v_mul_f32_e32 v5, v231, v5
	v_cvt_pk_bf16_f32 v44, v44, v2
	v_cvt_pk_bf16_f32 v45, v45, v3
	v_cvt_pk_bf16_f32 v46, v46, v4
	v_cvt_pk_bf16_f32 v47, v47, v5
	v_lshlrev_b32_e32 v86, 16, v6
	v_lshlrev_b32_e32 v87, 16, v7
	v_lshlrev_b32_e32 v88, 16, v8
	v_lshlrev_b32_e32 v89, 16, v9
	v_and_b32_e32 v6, 0xffff0000, v6
	v_and_b32_e32 v7, 0xffff0000, v7
	v_and_b32_e32 v8, 0xffff0000, v8
	v_and_b32_e32 v9, 0xffff0000, v9
	v_mul_f32_e32 v86, v232, v86
	v_mul_f32_e32 v87, v234, v87
	v_mul_f32_e32 v88, v236, v88
	v_mul_f32_e32 v89, v238, v89
	v_mul_f32_e32 v6, v233, v6
	v_mul_f32_e32 v7, v235, v7
	v_mul_f32_e32 v8, v237, v8
	v_mul_f32_e32 v9, v239, v9
	v_cvt_pk_bf16_f32 v86, v86, v6
	v_cvt_pk_bf16_f32 v87, v87, v7
	v_cvt_pk_bf16_f32 v88, v88, v8
	v_cvt_pk_bf16_f32 v89, v89, v9
	s_nop 0
	v_mfma_f32_16x16x32_bf16 v[40:43], v[44:47], v[70:73], 0
	v_lshlrev_b32_e32 v44, 16, v10
	v_lshlrev_b32_e32 v45, 16, v11
	v_lshlrev_b32_e32 v46, 16, v12
	v_lshlrev_b32_e32 v47, 16, v13
	v_and_b32_e32 v10, 0xffff0000, v10
	v_and_b32_e32 v11, 0xffff0000, v11
	v_and_b32_e32 v12, 0xffff0000, v12
	v_and_b32_e32 v13, 0xffff0000, v13
	v_mul_f32_e32 v44, v240, v44
	v_mul_f32_e32 v45, v242, v45
	v_mul_f32_e32 v46, v244, v46
	v_mul_f32_e32 v47, v246, v47
	v_mul_f32_e32 v10, v241, v10
	v_mul_f32_e32 v11, v243, v11
	v_mul_f32_e32 v12, v245, v12
	v_mul_f32_e32 v13, v247, v13
	v_cvt_pk_bf16_f32 v44, v44, v10
	v_cvt_pk_bf16_f32 v45, v45, v11
	v_cvt_pk_bf16_f32 v46, v46, v12
	v_cvt_pk_bf16_f32 v47, v47, v13
	v_mfma_f32_16x16x32_bf16 v[40:43], v[86:89], v[74:77], v[40:43]
	v_lshlrev_b32_e32 v86, 16, v14
	v_lshlrev_b32_e32 v87, 16, v15
	v_lshlrev_b32_e32 v88, 16, v16
	v_lshlrev_b32_e32 v89, 16, v17
	v_and_b32_e32 v14, 0xffff0000, v14
	v_and_b32_e32 v15, 0xffff0000, v15
	v_and_b32_e32 v16, 0xffff0000, v16
	v_and_b32_e32 v17, 0xffff0000, v17
	v_mul_f32_e32 v86, v248, v86
	v_mul_f32_e32 v87, v250, v87
	v_mul_f32_e32 v88, v210, v88
	v_mul_f32_e32 v89, v212, v89
	v_mul_f32_e32 v14, v249, v14
	v_mul_f32_e32 v15, v251, v15
	v_mul_f32_e32 v16, v211, v16
	v_mul_f32_e32 v17, v213, v17
	v_cvt_pk_bf16_f32 v86, v86, v14
	v_cvt_pk_bf16_f32 v87, v87, v15
	v_cvt_pk_bf16_f32 v88, v88, v16
	v_cvt_pk_bf16_f32 v89, v89, v17
	v_mfma_f32_16x16x32_bf16 v[40:43], v[44:47], v[78:81], v[40:43]
	s_nop 1
	v_mfma_f32_16x16x32_bf16 v[40:43], v[86:89], v[82:85], v[40:43]
	s_add_u32 s8, s20, 0x20000
	s_addc_u32 s9, s21, 0
	v_cvt_pk_bf16_f32 v48, v36, v37
	v_cvt_pk_bf16_f32 v49, v38, v39
	global_store_dwordx2 v172, v[48:49], s[8:9]
	s_nop 7
	v_pk_fma_f32 v[36:37], v[90:91], v[36:37], v[40:41] op_sel_hi:[0,1,1]
	v_pk_fma_f32 v[38:39], v[90:91], v[38:39], v[42:43] op_sel_hi:[0,1,1]
	s_add_u32 s8, s16, 0x48000
	s_addc_u32 s9, s17, 0
	s_add_u32 s10, s18, 0x48000
	s_addc_u32 s11, s19, 0
	global_load_dwordx4 v[2:5], v170, s[8:9]
	global_load_dwordx4 v[6:9], v170, s[8:9] offset:64
	global_load_dwordx4 v[10:13], v170, s[8:9] offset:128
	global_load_dwordx4 v[14:17], v170, s[8:9] offset:192
	global_load_dwordx4 v[70:73], v171, s[10:11]
	global_load_dwordx4 v[74:77], v171, s[10:11] offset:64
	global_load_dwordx4 v[78:81], v171, s[10:11] offset:128
	global_load_dwordx4 v[82:85], v171, s[10:11] offset:192
	s_waitcnt vmcnt(18)
	v_lshlrev_b32_e32 v44, 16, v20
	v_lshlrev_b32_e32 v45, 16, v21
	v_lshlrev_b32_e32 v46, 16, v22
	v_lshlrev_b32_e32 v47, 16, v23
	v_and_b32_e32 v20, 0xffff0000, v20
	v_and_b32_e32 v21, 0xffff0000, v21
	v_and_b32_e32 v22, 0xffff0000, v22
	v_and_b32_e32 v23, 0xffff0000, v23
	v_mul_f32_e32 v44, v224, v44
	v_mul_f32_e32 v45, v226, v45
	v_mul_f32_e32 v46, v228, v46
	v_mul_f32_e32 v47, v230, v47
	v_mul_f32_e32 v20, v225, v20
	v_mul_f32_e32 v21, v227, v21
	v_mul_f32_e32 v22, v229, v22
	v_mul_f32_e32 v23, v231, v23
	v_cvt_pk_bf16_f32 v44, v44, v20
	v_cvt_pk_bf16_f32 v45, v45, v21
	v_cvt_pk_bf16_f32 v46, v46, v22
	v_cvt_pk_bf16_f32 v47, v47, v23
	v_lshlrev_b32_e32 v86, 16, v24
	v_lshlrev_b32_e32 v87, 16, v25
	v_lshlrev_b32_e32 v88, 16, v26
	v_lshlrev_b32_e32 v89, 16, v27
	v_and_b32_e32 v24, 0xffff0000, v24
	v_and_b32_e32 v25, 0xffff0000, v25
	v_and_b32_e32 v26, 0xffff0000, v26
	v_and_b32_e32 v27, 0xffff0000, v27
	v_mul_f32_e32 v86, v232, v86
	v_mul_f32_e32 v87, v234, v87
	v_mul_f32_e32 v88, v236, v88
	v_mul_f32_e32 v89, v238, v89
	v_mul_f32_e32 v24, v233, v24
	v_mul_f32_e32 v25, v235, v25
	v_mul_f32_e32 v26, v237, v26
	v_mul_f32_e32 v27, v239, v27
	v_cvt_pk_bf16_f32 v86, v86, v24
	v_cvt_pk_bf16_f32 v87, v87, v25
	v_cvt_pk_bf16_f32 v88, v88, v26
	v_cvt_pk_bf16_f32 v89, v89, v27
	s_nop 0
	v_mfma_f32_16x16x32_bf16 v[40:43], v[44:47], v[94:97], 0
	v_lshlrev_b32_e32 v44, 16, v28
	v_lshlrev_b32_e32 v45, 16, v29
	v_lshlrev_b32_e32 v46, 16, v30
	v_lshlrev_b32_e32 v47, 16, v31
	v_and_b32_e32 v28, 0xffff0000, v28
	v_and_b32_e32 v29, 0xffff0000, v29
	v_and_b32_e32 v30, 0xffff0000, v30
	v_and_b32_e32 v31, 0xffff0000, v31
	v_mul_f32_e32 v44, v240, v44
	v_mul_f32_e32 v45, v242, v45
	v_mul_f32_e32 v46, v244, v46
	v_mul_f32_e32 v47, v246, v47
	v_mul_f32_e32 v28, v241, v28
	v_mul_f32_e32 v29, v243, v29
	v_mul_f32_e32 v30, v245, v30
	v_mul_f32_e32 v31, v247, v31
	v_cvt_pk_bf16_f32 v44, v44, v28
	v_cvt_pk_bf16_f32 v45, v45, v29
	v_cvt_pk_bf16_f32 v46, v46, v30
	v_cvt_pk_bf16_f32 v47, v47, v31
; __device__ __forceinline__ unsigned cvt_pk_bf16(float lo, float hi) { unsigned r; asm("v_cvt_pk_bf16_f32 %0, %1, %2" : "=v"(r) : "v"(lo), "v"(hi)); return r; }
; __device__ __forceinline__ float bf2f(unsigned b) { return __uint_as_float(b << 16); }
; __device__ __forceinline__ void r1s_load(const bf16_t* __restrict__ kT, const bf16_t* __restrict__ vT, int bh, int cc, size_t koff, size_t voff, bf16x8 (&kk)[4], bf16x8 (&vv)[4]) {
;     const bf16_t* kt = kT + (size_t)(bh * 18 + cc) * 16384 + koff; const bf16_t* vt = vT + (size_t)(bh * 18 + cc) * 16384 + voff;
; #pragma unroll
;     for (int ks = 0; ks < 4; ++ks) { kk[ks] = *(const bf16x8*)(kt + 32 * ks); vv[ks] = *(const bf16x8*)(vt + 32 * ks); }
; }
; __device__ __forceinline__ void r1s_step(const bf16x8 (&kk)[4], const bf16x8 (&vv)[4], const float (&w)[4][8], f32x4& S, float gC, bool st, bf16_t* dst) {
;     f32x4 acc = {0.f, 0.f, 0.f, 0.f};
; #pragma unroll
;     for (int ks = 0; ks < 4; ++ks) {
;         float f[8];
; #pragma unroll
;         for (int e = 0; e < 8; ++e) f[e] = bf2f((unsigned)(unsigned short)kk[ks][e]) * w[ks][e];
;         u32x4 wf; wf.x = cvt_pk_bf16(f[0], f[1]); wf.y = cvt_pk_bf16(f[2], f[3]); wf.z = cvt_pk_bf16(f[4], f[5]); wf.w = cvt_pk_bf16(f[6], f[7]);
;         acc = __builtin_amdgcn_mfma_f32_16x16x32_bf16(__builtin_bit_cast(bf16x8, wf), vv[ks], acc, 0, 0, 0);
;     }
;     if (st) { u32x2 o; o.x = cvt_pk_bf16(S[0], S[1]); o.y = cvt_pk_bf16(S[2], S[3]); *(u32x2*)dst = o; }
;     S = S * gC + acc;
; }
	v_mfma_f32_16x16x32_bf16 v[40:43], v[86:89], v[98:101], v[40:43]
	v_lshlrev_b32_e32 v86, 16, v32
	v_lshlrev_b32_e32 v87, 16, v33
	v_lshlrev_b32_e32 v88, 16, v34
	v_lshlrev_b32_e32 v89, 16, v35
	v_and_b32_e32 v32, 0xffff0000, v32
	v_and_b32_e32 v33, 0xffff0000, v33
	v_and_b32_e32 v34, 0xffff0000, v34
	v_and_b32_e32 v35, 0xffff0000, v35
	v_mul_f32_e32 v86, v248, v86
	v_mul_f32_e32 v87, v250, v87
	v_mul_f32_e32 v88, v210, v88
	v_mul_f32_e32 v89, v212, v89
	v_mul_f32_e32 v32, v249, v32
	v_mul_f32_e32 v33, v251, v33
	v_mul_f32_e32 v34, v211, v34
	v_mul_f32_e32 v35, v213, v35
	v_cvt_pk_bf16_f32 v86, v86, v32
	v_cvt_pk_bf16_f32 v87, v87, v33
	v_cvt_pk_bf16_f32 v88, v88, v34
	v_cvt_pk_bf16_f32 v89, v89, v35
	v_mfma_f32_16x16x32_bf16 v[40:43], v[44:47], v[102:105], v[40:43]
	s_nop 1
	v_mfma_f32_16x16x32_bf16 v[40:43], v[86:89], v[106:109], v[40:43]
	s_add_u32 s8, s20, 0x28000
	s_addc_u32 s9, s21, 0
	v_cvt_pk_bf16_f32 v48, v36, v37
	v_cvt_pk_bf16_f32 v49, v38, v39
	global_store_dwordx2 v172, v[48:49], s[8:9]
	s_nop 7
	v_pk_fma_f32 v[36:37], v[90:91], v[36:37], v[40:41] op_sel_hi:[0,1,1]
	v_pk_fma_f32 v[38:39], v[90:91], v[38:39], v[42:43] op_sel_hi:[0,1,1]
	s_add_u32 s8, s16, 0x50000
	s_addc_u32 s9, s17, 0
	s_add_u32 s10, s18, 0x50000
	s_addc_u32 s11, s19, 0
	global_load_dwordx4 v[20:23], v170, s[8:9]
	global_load_dwordx4 v[24:27], v170, s[8:9] offset:64
	global_load_dwordx4 v[28:31], v170, s[8:9] offset:128
	global_load_dwordx4 v[32:35], v170, s[8:9] offset:192
	global_load_dwordx4 v[94:97], v171, s[10:11]
	global_load_dwordx4 v[98:101], v171, s[10:11] offset:64
	global_load_dwordx4 v[102:105], v171, s[10:11] offset:128
	global_load_dwordx4 v[106:109], v171, s[10:11] offset:192
	s_waitcnt vmcnt(18)
	v_lshlrev_b32_e32 v44, 16, v54
	v_lshlrev_b32_e32 v45, 16, v55
	v_lshlrev_b32_e32 v46, 16, v56
	v_lshlrev_b32_e32 v47, 16, v57
	v_and_b32_e32 v54, 0xffff0000, v54
	v_and_b32_e32 v55, 0xffff0000, v55
	v_and_b32_e32 v56, 0xffff0000, v56
	v_and_b32_e32 v57, 0xffff0000, v57
	v_mul_f32_e32 v44, v224, v44
	v_mul_f32_e32 v45, v226, v45
	v_mul_f32_e32 v46, v228, v46
	v_mul_f32_e32 v47, v230, v47
	v_mul_f32_e32 v54, v225, v54
	v_mul_f32_e32 v55, v227, v55
	v_mul_f32_e32 v56, v229, v56
	v_mul_f32_e32 v57, v231, v57
	v_cvt_pk_bf16_f32 v44, v44, v54
	v_cvt_pk_bf16_f32 v45, v45, v55
	v_cvt_pk_bf16_f32 v46, v46, v56
	v_cvt_pk_bf16_f32 v47, v47, v57
	v_lshlrev_b32_e32 v86, 16, v58
	v_lshlrev_b32_e32 v87, 16, v59
	v_lshlrev_b32_e32 v88, 16, v60
	v_lshlrev_b32_e32 v89, 16, v61
	v_and_b32_e32 v58, 0xffff0000, v58
	v_and_b32_e32 v59, 0xffff0000, v59
	v_and_b32_e32 v60, 0xffff0000, v60
	v_and_b32_e32 v61, 0xffff0000, v61
	v_mul_f32_e32 v86, v232, v86
	v_mul_f32_e32 v87, v234, v87
	v_mul_f32_e32 v88, v236, v88
	v_mul_f32_e32 v89, v238, v89
	v_mul_f32_e32 v58, v233, v58
	v_mul_f32_e32 v59, v235, v59
	v_mul_f32_e32 v60, v237, v60
	v_mul_f32_e32 v61, v239, v61
	v_cvt_pk_bf16_f32 v86, v86, v58
	v_cvt_pk_bf16_f32 v87, v87, v59
	v_cvt_pk_bf16_f32 v88, v88, v60
	v_cvt_pk_bf16_f32 v89, v89, v61
	s_nop 0
	v_mfma_f32_16x16x32_bf16 v[40:43], v[44:47], v[110:113], 0
	v_lshlrev_b32_e32 v44, 16, v62
	v_lshlrev_b32_e32 v45, 16, v63
	v_lshlrev_b32_e32 v46, 16, v64
	v_lshlrev_b32_e32 v47, 16, v65
	v_and_b32_e32 v62, 0xffff0000, v62
	v_and_b32_e32 v63, 0xffff0000, v63
	v_and_b32_e32 v64, 0xffff0000, v64
	v_and_b32_e32 v65, 0xffff0000, v65
	v_mul_f32_e32 v44, v240, v44
	v_mul_f32_e32 v45, v242, v45
	v_mul_f32_e32 v46, v244, v46
	v_mul_f32_e32 v47, v246, v47
	v_mul_f32_e32 v62, v241, v62
	v_mul_f32_e32 v63, v243, v63
	v_mul_f32_e32 v64, v245, v64
	v_mul_f32_e32 v65, v247, v65
	v_cvt_pk_bf16_f32 v44, v44, v62
	v_cvt_pk_bf16_f32 v45, v45, v63
	v_cvt_pk_bf16_f32 v46, v46, v64
	v_cvt_pk_bf16_f32 v47, v47, v65
	v_mfma_f32_16x16x32_bf16 v[40:43], v[86:89], v[114:117], v[40:43]
	v_lshlrev_b32_e32 v86, 16, v66
	v_lshlrev_b32_e32 v87, 16, v67
	v_lshlrev_b32_e32 v88, 16, v68
	v_lshlrev_b32_e32 v89, 16, v69
	v_and_b32_e32 v66, 0xffff0000, v66
	v_and_b32_e32 v67, 0xffff0000, v67
	v_and_b32_e32 v68, 0xffff0000, v68
	v_and_b32_e32 v69, 0xffff0000, v69
	v_mul_f32_e32 v86, v248, v86
	v_mul_f32_e32 v87, v250, v87
	v_mul_f32_e32 v88, v210, v88
	v_mul_f32_e32 v89, v212, v89
	v_mul_f32_e32 v66, v249, v66
	v_mul_f32_e32 v67, v251, v67
	v_mul_f32_e32 v68, v211, v68
	v_mul_f32_e32 v69, v213, v69
	v_cvt_pk_bf16_f32 v86, v86, v66
	v_cvt_pk_bf16_f32 v87, v87, v67
	v_cvt_pk_bf16_f32 v88, v88, v68
	v_cvt_pk_bf16_f32 v89, v89, v69
	v_mfma_f32_16x16x32_bf16 v[40:43], v[44:47], v[118:121], v[40:43]
	s_nop 1
	v_mfma_f32_16x16x32_bf16 v[40:43], v[86:89], v[122:125], v[40:43]
	s_add_u32 s8, s20, 0x30000
	s_addc_u32 s9, s21, 0
	v_cvt_pk_bf16_f32 v48, v36, v37
	v_cvt_pk_bf16_f32 v49, v38, v39
	global_store_dwordx2 v172, v[48:49], s[8:9]
	s_nop 7
	v_pk_fma_f32 v[36:37], v[90:91], v[36:37], v[40:41] op_sel_hi:[0,1,1]
	v_pk_fma_f32 v[38:39], v[90:91], v[38:39], v[42:43] op_sel_hi:[0,1,1]
	s_add_u32 s8, s16, 0x58000
	s_addc_u32 s9, s17, 0
	s_add_u32 s10, s18, 0x58000
	s_addc_u32 s11, s19, 0
	global_load_dwordx4 v[54:57], v170, s[8:9]
	global_load_dwordx4 v[58:61], v170, s[8:9] offset:64
	global_load_dwordx4 v[62:65], v170, s[8:9] offset:128
	global_load_dwordx4 v[66:69], v170, s[8:9] offset:192
	global_load_dwordx4 v[110:113], v171, s[10:11]
	global_load_dwordx4 v[114:117], v171, s[10:11] offset:64
	global_load_dwordx4 v[118:121], v171, s[10:11] offset:128
	global_load_dwordx4 v[122:125], v171, s[10:11] offset:192
	s_waitcnt vmcnt(18)
; __device__ __forceinline__ unsigned cvt_pk_bf16(float lo, float hi) { unsigned r; asm("v_cvt_pk_bf16_f32 %0, %1, %2" : "=v"(r) : "v"(lo), "v"(hi)); return r; }
; __device__ __forceinline__ float bf2f(unsigned b) { return __uint_as_float(b << 16); }
; __device__ __forceinline__ void r1s_load(const bf16_t* __restrict__ kT, const bf16_t* __restrict__ vT, int bh, int cc, size_t koff, size_t voff, bf16x8 (&kk)[4], bf16x8 (&vv)[4]) {
;     const bf16_t* kt = kT + (size_t)(bh * 18 + cc) * 16384 + koff; const bf16_t* vt = vT + (size_t)(bh * 18 + cc) * 16384 + voff;
; #pragma unroll
;     for (int ks = 0; ks < 4; ++ks) { kk[ks] = *(const bf16x8*)(kt + 32 * ks); vv[ks] = *(const bf16x8*)(vt + 32 * ks); }
; }
; __device__ __forceinline__ void r1s_step(const bf16x8 (&kk)[4], const bf16x8 (&vv)[4], const float (&w)[4][8], f32x4& S, float gC, bool st, bf16_t* dst) {
;     f32x4 acc = {0.f, 0.f, 0.f, 0.f};
; #pragma unroll
;     for (int ks = 0; ks < 4; ++ks) {
;         float f[8];
; #pragma unroll
;         for (int e = 0; e < 8; ++e) f[e] = bf2f((unsigned)(unsigned short)kk[ks][e]) * w[ks][e];
;         u32x4 wf; wf.x = cvt_pk_bf16(f[0], f[1]); wf.y = cvt_pk_bf16(f[2], f[3]); wf.z = cvt_pk_bf16(f[4], f[5]); wf.w = cvt_pk_bf16(f[6], f[7]);
;         acc = __builtin_amdgcn_mfma_f32_16x16x32_bf16(__builtin_bit_cast(bf16x8, wf), vv[ks], acc, 0, 0, 0);
;     }
;     if (st) { u32x2 o; o.x = cvt_pk_bf16(S[0], S[1]); o.y = cvt_pk_bf16(S[2], S[3]); *(u32x2*)dst = o; }
;     S = S * gC + acc;
; }
	v_lshlrev_b32_e32 v44, 16, v2
	v_lshlrev_b32_e32 v45, 16, v3
	v_lshlrev_b32_e32 v46, 16, v4
	v_lshlrev_b32_e32 v47, 16, v5
	v_and_b32_e32 v2, 0xffff0000, v2
	v_and_b32_e32 v3, 0xffff0000, v3
	v_and_b32_e32 v4, 0xffff0000, v4
	v_and_b32_e32 v5, 0xffff0000, v5
	v_mul_f32_e32 v44, v224, v44
	v_mul_f32_e32 v45, v226, v45
	v_mul_f32_e32 v46, v228, v46
	v_mul_f32_e32 v47, v230, v47
	v_mul_f32_e32 v2, v225, v2
	v_mul_f32_e32 v3, v227, v3
	v_mul_f32_e32 v4, v229, v4
	v_mul_f32_e32 v5, v231, v5
	v_cvt_pk_bf16_f32 v44, v44, v2
	v_cvt_pk_bf16_f32 v45, v45, v3
	v_cvt_pk_bf16_f32 v46, v46, v4
	v_cvt_pk_bf16_f32 v47, v47, v5
	v_lshlrev_b32_e32 v86, 16, v6
	v_lshlrev_b32_e32 v87, 16, v7
	v_lshlrev_b32_e32 v88, 16, v8
	v_lshlrev_b32_e32 v89, 16, v9
	v_and_b32_e32 v6, 0xffff0000, v6
	v_and_b32_e32 v7, 0xffff0000, v7
	v_and_b32_e32 v8, 0xffff0000, v8
	v_and_b32_e32 v9, 0xffff0000, v9
	v_mul_f32_e32 v86, v232, v86
	v_mul_f32_e32 v87, v234, v87
	v_mul_f32_e32 v88, v236, v88
	v_mul_f32_e32 v89, v238, v89
	v_mul_f32_e32 v6, v233, v6
	v_mul_f32_e32 v7, v235, v7
	v_mul_f32_e32 v8, v237, v8
	v_mul_f32_e32 v9, v239, v9
	v_cvt_pk_bf16_f32 v86, v86, v6
	v_cvt_pk_bf16_f32 v87, v87, v7
	v_cvt_pk_bf16_f32 v88, v88, v8
	v_cvt_pk_bf16_f32 v89, v89, v9
	s_nop 0
	v_mfma_f32_16x16x32_bf16 v[40:43], v[44:47], v[70:73], 0
	v_lshlrev_b32_e32 v44, 16, v10
	v_lshlrev_b32_e32 v45, 16, v11
	v_lshlrev_b32_e32 v46, 16, v12
	v_lshlrev_b32_e32 v47, 16, v13
	v_and_b32_e32 v10, 0xffff0000, v10
	v_and_b32_e32 v11, 0xffff0000, v11
	v_and_b32_e32 v12, 0xffff0000, v12
	v_and_b32_e32 v13, 0xffff0000, v13
	v_mul_f32_e32 v44, v240, v44
	v_mul_f32_e32 v45, v242, v45
	v_mul_f32_e32 v46, v244, v46
	v_mul_f32_e32 v47, v246, v47
	v_mul_f32_e32 v10, v241, v10
	v_mul_f32_e32 v11, v243, v11
	v_mul_f32_e32 v12, v245, v12
	v_mul_f32_e32 v13, v247, v13
	v_cvt_pk_bf16_f32 v44, v44, v10
	v_cvt_pk_bf16_f32 v45, v45, v11
	v_cvt_pk_bf16_f32 v46, v46, v12
	v_cvt_pk_bf16_f32 v47, v47, v13
	v_mfma_f32_16x16x32_bf16 v[40:43], v[86:89], v[74:77], v[40:43]
	v_lshlrev_b32_e32 v86, 16, v14
	v_lshlrev_b32_e32 v87, 16, v15
	v_lshlrev_b32_e32 v88, 16, v16
	v_lshlrev_b32_e32 v89, 16, v17
	v_and_b32_e32 v14, 0xffff0000, v14
	v_and_b32_e32 v15, 0xffff0000, v15
	v_and_b32_e32 v16, 0xffff0000, v16
	v_and_b32_e32 v17, 0xffff0000, v17
	v_mul_f32_e32 v86, v248, v86
	v_mul_f32_e32 v87, v250, v87
	v_mul_f32_e32 v88, v210, v88
	v_mul_f32_e32 v89, v212, v89
	v_mul_f32_e32 v14, v249, v14
	v_mul_f32_e32 v15, v251, v15
	v_mul_f32_e32 v16, v211, v16
	v_mul_f32_e32 v17, v213, v17
	v_cvt_pk_bf16_f32 v86, v86, v14
	v_cvt_pk_bf16_f32 v87, v87, v15
	v_cvt_pk_bf16_f32 v88, v88, v16
	v_cvt_pk_bf16_f32 v89, v89, v17
	v_mfma_f32_16x16x32_bf16 v[40:43], v[44:47], v[78:81], v[40:43]
	s_nop 1
	v_mfma_f32_16x16x32_bf16 v[40:43], v[86:89], v[82:85], v[40:43]
	s_add_u32 s8, s20, 0x38000
	s_addc_u32 s9, s21, 0
	v_cvt_pk_bf16_f32 v48, v36, v37
	v_cvt_pk_bf16_f32 v49, v38, v39
	global_store_dwordx2 v172, v[48:49], s[8:9]
	s_nop 7
	v_pk_fma_f32 v[36:37], v[90:91], v[36:37], v[40:41] op_sel_hi:[0,1,1]
	v_pk_fma_f32 v[38:39], v[90:91], v[38:39], v[42:43] op_sel_hi:[0,1,1]
	s_add_u32 s8, s16, 0x60000
	s_addc_u32 s9, s17, 0
	s_add_u32 s10, s18, 0x60000
	s_addc_u32 s11, s19, 0
	global_load_dwordx4 v[2:5], v170, s[8:9]
	global_load_dwordx4 v[6:9], v170, s[8:9] offset:64
	global_load_dwordx4 v[10:13], v170, s[8:9] offset:128
	global_load_dwordx4 v[14:17], v170, s[8:9] offset:192
	global_load_dwordx4 v[70:73], v171, s[10:11]
	global_load_dwordx4 v[74:77], v171, s[10:11] offset:64
	global_load_dwordx4 v[78:81], v171, s[10:11] offset:128
	global_load_dwordx4 v[82:85], v171, s[10:11] offset:192
	s_waitcnt vmcnt(18)
	v_lshlrev_b32_e32 v44, 16, v20
	v_lshlrev_b32_e32 v45, 16, v21
	v_lshlrev_b32_e32 v46, 16, v22
	v_lshlrev_b32_e32 v47, 16, v23
	v_and_b32_e32 v20, 0xffff0000, v20
	v_and_b32_e32 v21, 0xffff0000, v21
	v_and_b32_e32 v22, 0xffff0000, v22
	v_and_b32_e32 v23, 0xffff0000, v23
	v_mul_f32_e32 v44, v224, v44
	v_mul_f32_e32 v45, v226, v45
	v_mul_f32_e32 v46, v228, v46
	v_mul_f32_e32 v47, v230, v47
	v_mul_f32_e32 v20, v225, v20
	v_mul_f32_e32 v21, v227, v21
	v_mul_f32_e32 v22, v229, v22
	v_mul_f32_e32 v23, v231, v23
	v_cvt_pk_bf16_f32 v44, v44, v20
	v_cvt_pk_bf16_f32 v45, v45, v21
	v_cvt_pk_bf16_f32 v46, v46, v22
	v_cvt_pk_bf16_f32 v47, v47, v23
	v_lshlrev_b32_e32 v86, 16, v24
	v_lshlrev_b32_e32 v87, 16, v25
	v_lshlrev_b32_e32 v88, 16, v26
	v_lshlrev_b32_e32 v89, 16, v27
	v_and_b32_e32 v24, 0xffff0000, v24
	v_and_b32_e32 v25, 0xffff0000, v25
	v_and_b32_e32 v26, 0xffff0000, v26
	v_and_b32_e32 v27, 0xffff0000, v27
	v_mul_f32_e32 v86, v232, v86
	v_mul_f32_e32 v87, v234, v87
	v_mul_f32_e32 v88, v236, v88
	v_mul_f32_e32 v89, v238, v89
	v_mul_f32_e32 v24, v233, v24
	v_mul_f32_e32 v25, v235, v25
	v_mul_f32_e32 v26, v237, v26
	v_mul_f32_e32 v27, v239, v27
	v_cvt_pk_bf16_f32 v86, v86, v24
	v_cvt_pk_bf16_f32 v87, v87, v25
	v_cvt_pk_bf16_f32 v88, v88, v26
	v_cvt_pk_bf16_f32 v89, v89, v27
	s_nop 0
	v_mfma_f32_16x16x32_bf16 v[40:43], v[44:47], v[94:97], 0
	v_lshlrev_b32_e32 v44, 16, v28
	v_lshlrev_b32_e32 v45, 16, v29
	v_lshlrev_b32_e32 v46, 16, v30
	v_lshlrev_b32_e32 v47, 16, v31
	v_and_b32_e32 v28, 0xffff0000, v28
	v_and_b32_e32 v29, 0xffff0000, v29
	v_and_b32_e32 v30, 0xffff0000, v30
	v_and_b32_e32 v31, 0xffff0000, v31
	v_mul_f32_e32 v44, v240, v44
	v_mul_f32_e32 v45, v242, v45
	v_mul_f32_e32 v46, v244, v46
	v_mul_f32_e32 v47, v246, v47
	v_mul_f32_e32 v28, v241, v28
	v_mul_f32_e32 v29, v243, v29
	v_mul_f32_e32 v30, v245, v30
	v_mul_f32_e32 v31, v247, v31
	v_cvt_pk_bf16_f32 v44, v44, v28
	v_cvt_pk_bf16_f32 v45, v45, v29
	v_cvt_pk_bf16_f32 v46, v46, v30
	v_cvt_pk_bf16_f32 v47, v47, v31
; __device__ __forceinline__ unsigned cvt_pk_bf16(float lo, float hi) { unsigned r; asm("v_cvt_pk_bf16_f32 %0, %1, %2" : "=v"(r) : "v"(lo), "v"(hi)); return r; }
; __device__ __forceinline__ float bf2f(unsigned b) { return __uint_as_float(b << 16); }
; __device__ __forceinline__ void r1s_load(const bf16_t* __restrict__ kT, const bf16_t* __restrict__ vT, int bh, int cc, size_t koff, size_t voff, bf16x8 (&kk)[4], bf16x8 (&vv)[4]) {
;     const bf16_t* kt = kT + (size_t)(bh * 18 + cc) * 16384 + koff; const bf16_t* vt = vT + (size_t)(bh * 18 + cc) * 16384 + voff;
; #pragma unroll
;     for (int ks = 0; ks < 4; ++ks) { kk[ks] = *(const bf16x8*)(kt + 32 * ks); vv[ks] = *(const bf16x8*)(vt + 32 * ks); }
; }
; __device__ __forceinline__ void r1s_step(const bf16x8 (&kk)[4], const bf16x8 (&vv)[4], const float (&w)[4][8], f32x4& S, float gC, bool st, bf16_t* dst) {
;     f32x4 acc = {0.f, 0.f, 0.f, 0.f};
; #pragma unroll
;     for (int ks = 0; ks < 4; ++ks) {
;         float f[8];
; #pragma unroll
;         for (int e = 0; e < 8; ++e) f[e] = bf2f((unsigned)(unsigned short)kk[ks][e]) * w[ks][e];
;         u32x4 wf; wf.x = cvt_pk_bf16(f[0], f[1]); wf.y = cvt_pk_bf16(f[2], f[3]); wf.z = cvt_pk_bf16(f[4], f[5]); wf.w = cvt_pk_bf16(f[6], f[7]);
;         acc = __builtin_amdgcn_mfma_f32_16x16x32_bf16(__builtin_bit_cast(bf16x8, wf), vv[ks], acc, 0, 0, 0);
;     }
;     if (st) { u32x2 o; o.x = cvt_pk_bf16(S[0], S[1]); o.y = cvt_pk_bf16(S[2], S[3]); *(u32x2*)dst = o; }
;     S = S * gC + acc;
; }
	v_mfma_f32_16x16x32_bf16 v[40:43], v[86:89], v[98:101], v[40:43]
	v_lshlrev_b32_e32 v86, 16, v32
	v_lshlrev_b32_e32 v87, 16, v33
	v_lshlrev_b32_e32 v88, 16, v34
	v_lshlrev_b32_e32 v89, 16, v35
	v_and_b32_e32 v32, 0xffff0000, v32
	v_and_b32_e32 v33, 0xffff0000, v33
	v_and_b32_e32 v34, 0xffff0000, v34
	v_and_b32_e32 v35, 0xffff0000, v35
	v_mul_f32_e32 v86, v248, v86
	v_mul_f32_e32 v87, v250, v87
	v_mul_f32_e32 v88, v210, v88
	v_mul_f32_e32 v89, v212, v89
	v_mul_f32_e32 v32, v249, v32
	v_mul_f32_e32 v33, v251, v33
	v_mul_f32_e32 v34, v211, v34
	v_mul_f32_e32 v35, v213, v35
	v_cvt_pk_bf16_f32 v86, v86, v32
	v_cvt_pk_bf16_f32 v87, v87, v33
	v_cvt_pk_bf16_f32 v88, v88, v34
	v_cvt_pk_bf16_f32 v89, v89, v35
	v_mfma_f32_16x16x32_bf16 v[40:43], v[44:47], v[102:105], v[40:43]
	s_nop 1
	v_mfma_f32_16x16x32_bf16 v[40:43], v[86:89], v[106:109], v[40:43]
	s_add_u32 s8, s20, 0x40000
	s_addc_u32 s9, s21, 0
	v_cvt_pk_bf16_f32 v48, v36, v37
	v_cvt_pk_bf16_f32 v49, v38, v39
	global_store_dwordx2 v172, v[48:49], s[8:9]
	s_nop 7
	v_pk_fma_f32 v[36:37], v[90:91], v[36:37], v[40:41] op_sel_hi:[0,1,1]
	v_pk_fma_f32 v[38:39], v[90:91], v[38:39], v[42:43] op_sel_hi:[0,1,1]
	s_add_u32 s8, s16, 0x68000
	s_addc_u32 s9, s17, 0
	s_add_u32 s10, s18, 0x68000
	s_addc_u32 s11, s19, 0
	global_load_dwordx4 v[20:23], v170, s[8:9]
	global_load_dwordx4 v[24:27], v170, s[8:9] offset:64
	global_load_dwordx4 v[28:31], v170, s[8:9] offset:128
	global_load_dwordx4 v[32:35], v170, s[8:9] offset:192
	global_load_dwordx4 v[94:97], v171, s[10:11]
	global_load_dwordx4 v[98:101], v171, s[10:11] offset:64
	global_load_dwordx4 v[102:105], v171, s[10:11] offset:128
	global_load_dwordx4 v[106:109], v171, s[10:11] offset:192
	s_waitcnt vmcnt(18)
	v_lshlrev_b32_e32 v44, 16, v54
	v_lshlrev_b32_e32 v45, 16, v55
	v_lshlrev_b32_e32 v46, 16, v56
	v_lshlrev_b32_e32 v47, 16, v57
	v_and_b32_e32 v54, 0xffff0000, v54
	v_and_b32_e32 v55, 0xffff0000, v55
	v_and_b32_e32 v56, 0xffff0000, v56
	v_and_b32_e32 v57, 0xffff0000, v57
	v_mul_f32_e32 v44, v224, v44
	v_mul_f32_e32 v45, v226, v45
	v_mul_f32_e32 v46, v228, v46
	v_mul_f32_e32 v47, v230, v47
	v_mul_f32_e32 v54, v225, v54
	v_mul_f32_e32 v55, v227, v55
	v_mul_f32_e32 v56, v229, v56
	v_mul_f32_e32 v57, v231, v57
	v_cvt_pk_bf16_f32 v44, v44, v54
	v_cvt_pk_bf16_f32 v45, v45, v55
	v_cvt_pk_bf16_f32 v46, v46, v56
	v_cvt_pk_bf16_f32 v47, v47, v57
	v_lshlrev_b32_e32 v86, 16, v58
	v_lshlrev_b32_e32 v87, 16, v59
	v_lshlrev_b32_e32 v88, 16, v60
	v_lshlrev_b32_e32 v89, 16, v61
	v_and_b32_e32 v58, 0xffff0000, v58
	v_and_b32_e32 v59, 0xffff0000, v59
	v_and_b32_e32 v60, 0xffff0000, v60
	v_and_b32_e32 v61, 0xffff0000, v61
	v_mul_f32_e32 v86, v232, v86
	v_mul_f32_e32 v87, v234, v87
	v_mul_f32_e32 v88, v236, v88
	v_mul_f32_e32 v89, v238, v89
	v_mul_f32_e32 v58, v233, v58
	v_mul_f32_e32 v59, v235, v59
	v_mul_f32_e32 v60, v237, v60
	v_mul_f32_e32 v61, v239, v61
	v_cvt_pk_bf16_f32 v86, v86, v58
	v_cvt_pk_bf16_f32 v87, v87, v59
	v_cvt_pk_bf16_f32 v88, v88, v60
	v_cvt_pk_bf16_f32 v89, v89, v61
	s_nop 0
	v_mfma_f32_16x16x32_bf16 v[40:43], v[44:47], v[110:113], 0
	v_lshlrev_b32_e32 v44, 16, v62
	v_lshlrev_b32_e32 v45, 16, v63
	v_lshlrev_b32_e32 v46, 16, v64
	v_lshlrev_b32_e32 v47, 16, v65
	v_and_b32_e32 v62, 0xffff0000, v62
	v_and_b32_e32 v63, 0xffff0000, v63
	v_and_b32_e32 v64, 0xffff0000, v64
	v_and_b32_e32 v65, 0xffff0000, v65
	v_mul_f32_e32 v44, v240, v44
	v_mul_f32_e32 v45, v242, v45
	v_mul_f32_e32 v46, v244, v46
	v_mul_f32_e32 v47, v246, v47
	v_mul_f32_e32 v62, v241, v62
	v_mul_f32_e32 v63, v243, v63
	v_mul_f32_e32 v64, v245, v64
	v_mul_f32_e32 v65, v247, v65
	v_cvt_pk_bf16_f32 v44, v44, v62
	v_cvt_pk_bf16_f32 v45, v45, v63
	v_cvt_pk_bf16_f32 v46, v46, v64
	v_cvt_pk_bf16_f32 v47, v47, v65
	v_mfma_f32_16x16x32_bf16 v[40:43], v[86:89], v[114:117], v[40:43]
	v_lshlrev_b32_e32 v86, 16, v66
	v_lshlrev_b32_e32 v87, 16, v67
	v_lshlrev_b32_e32 v88, 16, v68
	v_lshlrev_b32_e32 v89, 16, v69
	v_and_b32_e32 v66, 0xffff0000, v66
	v_and_b32_e32 v67, 0xffff0000, v67
	v_and_b32_e32 v68, 0xffff0000, v68
	v_and_b32_e32 v69, 0xffff0000, v69
	v_mul_f32_e32 v86, v248, v86
	v_mul_f32_e32 v87, v250, v87
	v_mul_f32_e32 v88, v210, v88
	v_mul_f32_e32 v89, v212, v89
	v_mul_f32_e32 v66, v249, v66
	v_mul_f32_e32 v67, v251, v67
	v_mul_f32_e32 v68, v211, v68
	v_mul_f32_e32 v69, v213, v69
	v_cvt_pk_bf16_f32 v86, v86, v66
	v_cvt_pk_bf16_f32 v87, v87, v67
	v_cvt_pk_bf16_f32 v88, v88, v68
	v_cvt_pk_bf16_f32 v89, v89, v69
	v_mfma_f32_16x16x32_bf16 v[40:43], v[44:47], v[118:121], v[40:43]
	s_nop 1
	v_mfma_f32_16x16x32_bf16 v[40:43], v[86:89], v[122:125], v[40:43]
	s_add_u32 s8, s20, 0x48000
	s_addc_u32 s9, s21, 0
	v_cvt_pk_bf16_f32 v48, v36, v37
	v_cvt_pk_bf16_f32 v49, v38, v39
	global_store_dwordx2 v172, v[48:49], s[8:9]
	s_nop 7
	v_pk_fma_f32 v[36:37], v[90:91], v[36:37], v[40:41] op_sel_hi:[0,1,1]
	v_pk_fma_f32 v[38:39], v[90:91], v[38:39], v[42:43] op_sel_hi:[0,1,1]
	s_add_u32 s8, s16, 0x70000
	s_addc_u32 s9, s17, 0
	s_add_u32 s10, s18, 0x70000
	s_addc_u32 s11, s19, 0
	global_load_dwordx4 v[54:57], v170, s[8:9]
	global_load_dwordx4 v[58:61], v170, s[8:9] offset:64
	global_load_dwordx4 v[62:65], v170, s[8:9] offset:128
	global_load_dwordx4 v[66:69], v170, s[8:9] offset:192
	global_load_dwordx4 v[110:113], v171, s[10:11]
	global_load_dwordx4 v[114:117], v171, s[10:11] offset:64
	global_load_dwordx4 v[118:121], v171, s[10:11] offset:128
	global_load_dwordx4 v[122:125], v171, s[10:11] offset:192
	s_waitcnt vmcnt(18)
; __device__ __forceinline__ unsigned cvt_pk_bf16(float lo, float hi) { unsigned r; asm("v_cvt_pk_bf16_f32 %0, %1, %2" : "=v"(r) : "v"(lo), "v"(hi)); return r; }
; __device__ __forceinline__ float bf2f(unsigned b) { return __uint_as_float(b << 16); }
; __device__ __forceinline__ void r1s_load(const bf16_t* __restrict__ kT, const bf16_t* __restrict__ vT, int bh, int cc, size_t koff, size_t voff, bf16x8 (&kk)[4], bf16x8 (&vv)[4]) {
;     const bf16_t* kt = kT + (size_t)(bh * 18 + cc) * 16384 + koff; const bf16_t* vt = vT + (size_t)(bh * 18 + cc) * 16384 + voff;
; #pragma unroll
;     for (int ks = 0; ks < 4; ++ks) { kk[ks] = *(const bf16x8*)(kt + 32 * ks); vv[ks] = *(const bf16x8*)(vt + 32 * ks); }
; }
; __device__ __forceinline__ void r1s_step(const bf16x8 (&kk)[4], const bf16x8 (&vv)[4], const float (&w)[4][8], f32x4& S, float gC, bool st, bf16_t* dst) {
;     f32x4 acc = {0.f, 0.f, 0.f, 0.f};
; #pragma unroll
;     for (int ks = 0; ks < 4; ++ks) {
;         float f[8];
; #pragma unroll
;         for (int e = 0; e < 8; ++e) f[e] = bf2f((unsigned)(unsigned short)kk[ks][e]) * w[ks][e];
;         u32x4 wf; wf.x = cvt_pk_bf16(f[0], f[1]); wf.y = cvt_pk_bf16(f[2], f[3]); wf.z = cvt_pk_bf16(f[4], f[5]); wf.w = cvt_pk_bf16(f[6], f[7]);
;         acc = __builtin_amdgcn_mfma_f32_16x16x32_bf16(__builtin_bit_cast(bf16x8, wf), vv[ks], acc, 0, 0, 0);
;     }
;     if (st) { u32x2 o; o.x = cvt_pk_bf16(S[0], S[1]); o.y = cvt_pk_bf16(S[2], S[3]); *(u32x2*)dst = o; }
;     S = S * gC + acc;
; }
	v_lshlrev_b32_e32 v44, 16, v2
	v_lshlrev_b32_e32 v45, 16, v3
	v_lshlrev_b32_e32 v46, 16, v4
	v_lshlrev_b32_e32 v47, 16, v5
	v_and_b32_e32 v2, 0xffff0000, v2
	v_and_b32_e32 v3, 0xffff0000, v3
	v_and_b32_e32 v4, 0xffff0000, v4
	v_and_b32_e32 v5, 0xffff0000, v5
	v_mul_f32_e32 v44, v224, v44
	v_mul_f32_e32 v45, v226, v45
	v_mul_f32_e32 v46, v228, v46
	v_mul_f32_e32 v47, v230, v47
	v_mul_f32_e32 v2, v225, v2
	v_mul_f32_e32 v3, v227, v3
	v_mul_f32_e32 v4, v229, v4
	v_mul_f32_e32 v5, v231, v5
	v_cvt_pk_bf16_f32 v44, v44, v2
	v_cvt_pk_bf16_f32 v45, v45, v3
	v_cvt_pk_bf16_f32 v46, v46, v4
	v_cvt_pk_bf16_f32 v47, v47, v5
	v_lshlrev_b32_e32 v86, 16, v6
	v_lshlrev_b32_e32 v87, 16, v7
	v_lshlrev_b32_e32 v88, 16, v8
	v_lshlrev_b32_e32 v89, 16, v9
	v_and_b32_e32 v6, 0xffff0000, v6
	v_and_b32_e32 v7, 0xffff0000, v7
	v_and_b32_e32 v8, 0xffff0000, v8
	v_and_b32_e32 v9, 0xffff0000, v9
	v_mul_f32_e32 v86, v232, v86
	v_mul_f32_e32 v87, v234, v87
	v_mul_f32_e32 v88, v236, v88
	v_mul_f32_e32 v89, v238, v89
	v_mul_f32_e32 v6, v233, v6
	v_mul_f32_e32 v7, v235, v7
	v_mul_f32_e32 v8, v237, v8
	v_mul_f32_e32 v9, v239, v9
	v_cvt_pk_bf16_f32 v86, v86, v6
	v_cvt_pk_bf16_f32 v87, v87, v7
	v_cvt_pk_bf16_f32 v88, v88, v8
	v_cvt_pk_bf16_f32 v89, v89, v9
	s_nop 0
	v_mfma_f32_16x16x32_bf16 v[40:43], v[44:47], v[70:73], 0
	v_lshlrev_b32_e32 v44, 16, v10
	v_lshlrev_b32_e32 v45, 16, v11
	v_lshlrev_b32_e32 v46, 16, v12
	v_lshlrev_b32_e32 v47, 16, v13
	v_and_b32_e32 v10, 0xffff0000, v10
	v_and_b32_e32 v11, 0xffff0000, v11
	v_and_b32_e32 v12, 0xffff0000, v12
	v_and_b32_e32 v13, 0xffff0000, v13
	v_mul_f32_e32 v44, v240, v44
	v_mul_f32_e32 v45, v242, v45
	v_mul_f32_e32 v46, v244, v46
	v_mul_f32_e32 v47, v246, v47
	v_mul_f32_e32 v10, v241, v10
	v_mul_f32_e32 v11, v243, v11
	v_mul_f32_e32 v12, v245, v12
	v_mul_f32_e32 v13, v247, v13
	v_cvt_pk_bf16_f32 v44, v44, v10
	v_cvt_pk_bf16_f32 v45, v45, v11
	v_cvt_pk_bf16_f32 v46, v46, v12
	v_cvt_pk_bf16_f32 v47, v47, v13
	v_mfma_f32_16x16x32_bf16 v[40:43], v[86:89], v[74:77], v[40:43]
	v_lshlrev_b32_e32 v86, 16, v14
	v_lshlrev_b32_e32 v87, 16, v15
	v_lshlrev_b32_e32 v88, 16, v16
	v_lshlrev_b32_e32 v89, 16, v17
	v_and_b32_e32 v14, 0xffff0000, v14
	v_and_b32_e32 v15, 0xffff0000, v15
	v_and_b32_e32 v16, 0xffff0000, v16
	v_and_b32_e32 v17, 0xffff0000, v17
	v_mul_f32_e32 v86, v248, v86
	v_mul_f32_e32 v87, v250, v87
	v_mul_f32_e32 v88, v210, v88
	v_mul_f32_e32 v89, v212, v89
	v_mul_f32_e32 v14, v249, v14
	v_mul_f32_e32 v15, v251, v15
	v_mul_f32_e32 v16, v211, v16
	v_mul_f32_e32 v17, v213, v17
	v_cvt_pk_bf16_f32 v86, v86, v14
	v_cvt_pk_bf16_f32 v87, v87, v15
	v_cvt_pk_bf16_f32 v88, v88, v16
	v_cvt_pk_bf16_f32 v89, v89, v17
	v_mfma_f32_16x16x32_bf16 v[40:43], v[44:47], v[78:81], v[40:43]
	s_nop 1
	v_mfma_f32_16x16x32_bf16 v[40:43], v[86:89], v[82:85], v[40:43]
	s_add_u32 s8, s20, 0x50000
	s_addc_u32 s9, s21, 0
	v_cvt_pk_bf16_f32 v48, v36, v37
	v_cvt_pk_bf16_f32 v49, v38, v39
	global_store_dwordx2 v172, v[48:49], s[8:9]
	s_nop 7
	v_pk_fma_f32 v[36:37], v[90:91], v[36:37], v[40:41] op_sel_hi:[0,1,1]
	v_pk_fma_f32 v[38:39], v[90:91], v[38:39], v[42:43] op_sel_hi:[0,1,1]
	s_add_u32 s8, s16, 0x78000
	s_addc_u32 s9, s17, 0
	s_add_u32 s10, s18, 0x78000
	s_addc_u32 s11, s19, 0
	global_load_dwordx4 v[2:5], v170, s[8:9]
	global_load_dwordx4 v[6:9], v170, s[8:9] offset:64
	global_load_dwordx4 v[10:13], v170, s[8:9] offset:128
	global_load_dwordx4 v[14:17], v170, s[8:9] offset:192
	global_load_dwordx4 v[70:73], v171, s[10:11]
	global_load_dwordx4 v[74:77], v171, s[10:11] offset:64
	global_load_dwordx4 v[78:81], v171, s[10:11] offset:128
	global_load_dwordx4 v[82:85], v171, s[10:11] offset:192
	s_waitcnt vmcnt(18)
	v_lshlrev_b32_e32 v44, 16, v20
	v_lshlrev_b32_e32 v45, 16, v21
	v_lshlrev_b32_e32 v46, 16, v22
	v_lshlrev_b32_e32 v47, 16, v23
	v_and_b32_e32 v20, 0xffff0000, v20
	v_and_b32_e32 v21, 0xffff0000, v21
	v_and_b32_e32 v22, 0xffff0000, v22
	v_and_b32_e32 v23, 0xffff0000, v23
	v_mul_f32_e32 v44, v224, v44
	v_mul_f32_e32 v45, v226, v45
	v_mul_f32_e32 v46, v228, v46
	v_mul_f32_e32 v47, v230, v47
	v_mul_f32_e32 v20, v225, v20
	v_mul_f32_e32 v21, v227, v21
	v_mul_f32_e32 v22, v229, v22
	v_mul_f32_e32 v23, v231, v23
	v_cvt_pk_bf16_f32 v44, v44, v20
	v_cvt_pk_bf16_f32 v45, v45, v21
	v_cvt_pk_bf16_f32 v46, v46, v22
	v_cvt_pk_bf16_f32 v47, v47, v23
	v_lshlrev_b32_e32 v86, 16, v24
	v_lshlrev_b32_e32 v87, 16, v25
	v_lshlrev_b32_e32 v88, 16, v26
	v_lshlrev_b32_e32 v89, 16, v27
	v_and_b32_e32 v24, 0xffff0000, v24
	v_and_b32_e32 v25, 0xffff0000, v25
	v_and_b32_e32 v26, 0xffff0000, v26
	v_and_b32_e32 v27, 0xffff0000, v27
	v_mul_f32_e32 v86, v232, v86
	v_mul_f32_e32 v87, v234, v87
	v_mul_f32_e32 v88, v236, v88
	v_mul_f32_e32 v89, v238, v89
	v_mul_f32_e32 v24, v233, v24
	v_mul_f32_e32 v25, v235, v25
	v_mul_f32_e32 v26, v237, v26
	v_mul_f32_e32 v27, v239, v27
	v_cvt_pk_bf16_f32 v86, v86, v24
	v_cvt_pk_bf16_f32 v87, v87, v25
	v_cvt_pk_bf16_f32 v88, v88, v26
	v_cvt_pk_bf16_f32 v89, v89, v27
	s_nop 0
	v_mfma_f32_16x16x32_bf16 v[40:43], v[44:47], v[94:97], 0
	v_lshlrev_b32_e32 v44, 16, v28
	v_lshlrev_b32_e32 v45, 16, v29
	v_lshlrev_b32_e32 v46, 16, v30
	v_lshlrev_b32_e32 v47, 16, v31
	v_and_b32_e32 v28, 0xffff0000, v28
	v_and_b32_e32 v29, 0xffff0000, v29
	v_and_b32_e32 v30, 0xffff0000, v30
	v_and_b32_e32 v31, 0xffff0000, v31
	v_mul_f32_e32 v44, v240, v44
	v_mul_f32_e32 v45, v242, v45
	v_mul_f32_e32 v46, v244, v46
	v_mul_f32_e32 v47, v246, v47
	v_mul_f32_e32 v28, v241, v28
	v_mul_f32_e32 v29, v243, v29
	v_mul_f32_e32 v30, v245, v30
	v_mul_f32_e32 v31, v247, v31
	v_cvt_pk_bf16_f32 v44, v44, v28
	v_cvt_pk_bf16_f32 v45, v45, v29
	v_cvt_pk_bf16_f32 v46, v46, v30
	v_cvt_pk_bf16_f32 v47, v47, v31
; __device__ __forceinline__ unsigned cvt_pk_bf16(float lo, float hi) { unsigned r; asm("v_cvt_pk_bf16_f32 %0, %1, %2" : "=v"(r) : "v"(lo), "v"(hi)); return r; }
; __device__ __forceinline__ float bf2f(unsigned b) { return __uint_as_float(b << 16); }
; __device__ __forceinline__ void r1s_load(const bf16_t* __restrict__ kT, const bf16_t* __restrict__ vT, int bh, int cc, size_t koff, size_t voff, bf16x8 (&kk)[4], bf16x8 (&vv)[4]) {
;     const bf16_t* kt = kT + (size_t)(bh * 18 + cc) * 16384 + koff; const bf16_t* vt = vT + (size_t)(bh * 18 + cc) * 16384 + voff;
; #pragma unroll
;     for (int ks = 0; ks < 4; ++ks) { kk[ks] = *(const bf16x8*)(kt + 32 * ks); vv[ks] = *(const bf16x8*)(vt + 32 * ks); }
; }
; __device__ __forceinline__ void r1s_step(const bf16x8 (&kk)[4], const bf16x8 (&vv)[4], const float (&w)[4][8], f32x4& S, float gC, bool st, bf16_t* dst) {
;     f32x4 acc = {0.f, 0.f, 0.f, 0.f};
; #pragma unroll
;     for (int ks = 0; ks < 4; ++ks) {
;         float f[8];
; #pragma unroll
;         for (int e = 0; e < 8; ++e) f[e] = bf2f((unsigned)(unsigned short)kk[ks][e]) * w[ks][e];
;         u32x4 wf; wf.x = cvt_pk_bf16(f[0], f[1]); wf.y = cvt_pk_bf16(f[2], f[3]); wf.z = cvt_pk_bf16(f[4], f[5]); wf.w = cvt_pk_bf16(f[6], f[7]);
;         acc = __builtin_amdgcn_mfma_f32_16x16x32_bf16(__builtin_bit_cast(bf16x8, wf), vv[ks], acc, 0, 0, 0);
;     }
;     if (st) { u32x2 o; o.x = cvt_pk_bf16(S[0], S[1]); o.y = cvt_pk_bf16(S[2], S[3]); *(u32x2*)dst = o; }
;     S = S * gC + acc;
; }
	v_mfma_f32_16x16x32_bf16 v[40:43], v[86:89], v[98:101], v[40:43]
	v_lshlrev_b32_e32 v86, 16, v32
	v_lshlrev_b32_e32 v87, 16, v33
	v_lshlrev_b32_e32 v88, 16, v34
	v_lshlrev_b32_e32 v89, 16, v35
	v_and_b32_e32 v32, 0xffff0000, v32
	v_and_b32_e32 v33, 0xffff0000, v33
	v_and_b32_e32 v34, 0xffff0000, v34
	v_and_b32_e32 v35, 0xffff0000, v35
	v_mul_f32_e32 v86, v248, v86
	v_mul_f32_e32 v87, v250, v87
	v_mul_f32_e32 v88, v210, v88
	v_mul_f32_e32 v89, v212, v89
	v_mul_f32_e32 v32, v249, v32
	v_mul_f32_e32 v33, v251, v33
	v_mul_f32_e32 v34, v211, v34
	v_mul_f32_e32 v35, v213, v35
	v_cvt_pk_bf16_f32 v86, v86, v32
	v_cvt_pk_bf16_f32 v87, v87, v33
	v_cvt_pk_bf16_f32 v88, v88, v34
	v_cvt_pk_bf16_f32 v89, v89, v35
	v_mfma_f32_16x16x32_bf16 v[40:43], v[44:47], v[102:105], v[40:43]
	s_nop 1
	v_mfma_f32_16x16x32_bf16 v[40:43], v[86:89], v[106:109], v[40:43]
	s_add_u32 s8, s20, 0x58000
	s_addc_u32 s9, s21, 0
	v_cvt_pk_bf16_f32 v48, v36, v37
	v_cvt_pk_bf16_f32 v49, v38, v39
	global_store_dwordx2 v172, v[48:49], s[8:9]
	s_nop 7
	v_pk_fma_f32 v[36:37], v[90:91], v[36:37], v[40:41] op_sel_hi:[0,1,1]
	v_pk_fma_f32 v[38:39], v[90:91], v[38:39], v[42:43] op_sel_hi:[0,1,1]
	s_add_u32 s8, s16, 0x80000
	s_addc_u32 s9, s17, 0
	s_add_u32 s10, s18, 0x80000
	s_addc_u32 s11, s19, 0
	global_load_dwordx4 v[20:23], v170, s[8:9]
	global_load_dwordx4 v[24:27], v170, s[8:9] offset:64
	global_load_dwordx4 v[28:31], v170, s[8:9] offset:128
	global_load_dwordx4 v[32:35], v170, s[8:9] offset:192
	global_load_dwordx4 v[94:97], v171, s[10:11]
	global_load_dwordx4 v[98:101], v171, s[10:11] offset:64
	global_load_dwordx4 v[102:105], v171, s[10:11] offset:128
	global_load_dwordx4 v[106:109], v171, s[10:11] offset:192
	s_waitcnt vmcnt(18)
	v_lshlrev_b32_e32 v44, 16, v54
	v_lshlrev_b32_e32 v45, 16, v55
	v_lshlrev_b32_e32 v46, 16, v56
	v_lshlrev_b32_e32 v47, 16, v57
	v_and_b32_e32 v54, 0xffff0000, v54
	v_and_b32_e32 v55, 0xffff0000, v55
	v_and_b32_e32 v56, 0xffff0000, v56
	v_and_b32_e32 v57, 0xffff0000, v57
	v_mul_f32_e32 v44, v224, v44
	v_mul_f32_e32 v45, v226, v45
	v_mul_f32_e32 v46, v228, v46
	v_mul_f32_e32 v47, v230, v47
	v_mul_f32_e32 v54, v225, v54
	v_mul_f32_e32 v55, v227, v55
	v_mul_f32_e32 v56, v229, v56
	v_mul_f32_e32 v57, v231, v57
	v_cvt_pk_bf16_f32 v44, v44, v54
	v_cvt_pk_bf16_f32 v45, v45, v55
	v_cvt_pk_bf16_f32 v46, v46, v56
	v_cvt_pk_bf16_f32 v47, v47, v57
	v_lshlrev_b32_e32 v86, 16, v58
	v_lshlrev_b32_e32 v87, 16, v59
	v_lshlrev_b32_e32 v88, 16, v60
	v_lshlrev_b32_e32 v89, 16, v61
	v_and_b32_e32 v58, 0xffff0000, v58
	v_and_b32_e32 v59, 0xffff0000, v59
	v_and_b32_e32 v60, 0xffff0000, v60
	v_and_b32_e32 v61, 0xffff0000, v61
	v_mul_f32_e32 v86, v232, v86
	v_mul_f32_e32 v87, v234, v87
	v_mul_f32_e32 v88, v236, v88
	v_mul_f32_e32 v89, v238, v89
	v_mul_f32_e32 v58, v233, v58
	v_mul_f32_e32 v59, v235, v59
	v_mul_f32_e32 v60, v237, v60
	v_mul_f32_e32 v61, v239, v61
	v_cvt_pk_bf16_f32 v86, v86, v58
	v_cvt_pk_bf16_f32 v87, v87, v59
	v_cvt_pk_bf16_f32 v88, v88, v60
	v_cvt_pk_bf16_f32 v89, v89, v61
	s_nop 0
	v_mfma_f32_16x16x32_bf16 v[40:43], v[44:47], v[110:113], 0
	v_lshlrev_b32_e32 v44, 16, v62
	v_lshlrev_b32_e32 v45, 16, v63
	v_lshlrev_b32_e32 v46, 16, v64
	v_lshlrev_b32_e32 v47, 16, v65
	v_and_b32_e32 v62, 0xffff0000, v62
	v_and_b32_e32 v63, 0xffff0000, v63
	v_and_b32_e32 v64, 0xffff0000, v64
	v_and_b32_e32 v65, 0xffff0000, v65
	v_mul_f32_e32 v44, v240, v44
	v_mul_f32_e32 v45, v242, v45
	v_mul_f32_e32 v46, v244, v46
	v_mul_f32_e32 v47, v246, v47
	v_mul_f32_e32 v62, v241, v62
	v_mul_f32_e32 v63, v243, v63
	v_mul_f32_e32 v64, v245, v64
	v_mul_f32_e32 v65, v247, v65
	v_cvt_pk_bf16_f32 v44, v44, v62
	v_cvt_pk_bf16_f32 v45, v45, v63
	v_cvt_pk_bf16_f32 v46, v46, v64
	v_cvt_pk_bf16_f32 v47, v47, v65
	v_mfma_f32_16x16x32_bf16 v[40:43], v[86:89], v[114:117], v[40:43]
	v_lshlrev_b32_e32 v86, 16, v66
	v_lshlrev_b32_e32 v87, 16, v67
	v_lshlrev_b32_e32 v88, 16, v68
	v_lshlrev_b32_e32 v89, 16, v69
	v_and_b32_e32 v66, 0xffff0000, v66
	v_and_b32_e32 v67, 0xffff0000, v67
	v_and_b32_e32 v68, 0xffff0000, v68
	v_and_b32_e32 v69, 0xffff0000, v69
	v_mul_f32_e32 v86, v248, v86
	v_mul_f32_e32 v87, v250, v87
	v_mul_f32_e32 v88, v210, v88
	v_mul_f32_e32 v89, v212, v89
	v_mul_f32_e32 v66, v249, v66
	v_mul_f32_e32 v67, v251, v67
	v_mul_f32_e32 v68, v211, v68
	v_mul_f32_e32 v69, v213, v69
	v_cvt_pk_bf16_f32 v86, v86, v66
	v_cvt_pk_bf16_f32 v87, v87, v67
	v_cvt_pk_bf16_f32 v88, v88, v68
	v_cvt_pk_bf16_f32 v89, v89, v69
	v_mfma_f32_16x16x32_bf16 v[40:43], v[44:47], v[118:121], v[40:43]
	s_nop 1
	v_mfma_f32_16x16x32_bf16 v[40:43], v[86:89], v[122:125], v[40:43]
	s_add_u32 s8, s20, 0x60000
	s_addc_u32 s9, s21, 0
	v_cvt_pk_bf16_f32 v48, v36, v37
	v_cvt_pk_bf16_f32 v49, v38, v39
	global_store_dwordx2 v172, v[48:49], s[8:9]
	s_nop 7
	v_pk_fma_f32 v[36:37], v[90:91], v[36:37], v[40:41] op_sel_hi:[0,1,1]
	v_pk_fma_f32 v[38:39], v[90:91], v[38:39], v[42:43] op_sel_hi:[0,1,1]
	s_add_u32 s8, s16, 0x88000
	s_addc_u32 s9, s17, 0
	s_add_u32 s10, s18, 0x88000
	s_addc_u32 s11, s19, 0
	global_load_dwordx4 v[54:57], v170, s[8:9]
	global_load_dwordx4 v[58:61], v170, s[8:9] offset:64
	global_load_dwordx4 v[62:65], v170, s[8:9] offset:128
	global_load_dwordx4 v[66:69], v170, s[8:9] offset:192
	global_load_dwordx4 v[110:113], v171, s[10:11]
	global_load_dwordx4 v[114:117], v171, s[10:11] offset:64
	global_load_dwordx4 v[118:121], v171, s[10:11] offset:128
	global_load_dwordx4 v[122:125], v171, s[10:11] offset:192
	s_waitcnt vmcnt(18)
; __device__ __forceinline__ unsigned cvt_pk_bf16(float lo, float hi) { unsigned r; asm("v_cvt_pk_bf16_f32 %0, %1, %2" : "=v"(r) : "v"(lo), "v"(hi)); return r; }
; __device__ __forceinline__ float bf2f(unsigned b) { return __uint_as_float(b << 16); }
; __device__ __forceinline__ void r1s_load(const bf16_t* __restrict__ kT, const bf16_t* __restrict__ vT, int bh, int cc, size_t koff, size_t voff, bf16x8 (&kk)[4], bf16x8 (&vv)[4]) {
;     const bf16_t* kt = kT + (size_t)(bh * 18 + cc) * 16384 + koff; const bf16_t* vt = vT + (size_t)(bh * 18 + cc) * 16384 + voff;
; #pragma unroll
;     for (int ks = 0; ks < 4; ++ks) { kk[ks] = *(const bf16x8*)(kt + 32 * ks); vv[ks] = *(const bf16x8*)(vt + 32 * ks); }
; }
; __device__ __forceinline__ void r1s_step(const bf16x8 (&kk)[4], const bf16x8 (&vv)[4], const float (&w)[4][8], f32x4& S, float gC, bool st, bf16_t* dst) {
;     f32x4 acc = {0.f, 0.f, 0.f, 0.f};
; #pragma unroll
;     for (int ks = 0; ks < 4; ++ks) {
;         float f[8];
; #pragma unroll
;         for (int e = 0; e < 8; ++e) f[e] = bf2f((unsigned)(unsigned short)kk[ks][e]) * w[ks][e];
;         u32x4 wf; wf.x = cvt_pk_bf16(f[0], f[1]); wf.y = cvt_pk_bf16(f[2], f[3]); wf.z = cvt_pk_bf16(f[4], f[5]); wf.w = cvt_pk_bf16(f[6], f[7]);
;         acc = __builtin_amdgcn_mfma_f32_16x16x32_bf16(__builtin_bit_cast(bf16x8, wf), vv[ks], acc, 0, 0, 0);
;     }
;     if (st) { u32x2 o; o.x = cvt_pk_bf16(S[0], S[1]); o.y = cvt_pk_bf16(S[2], S[3]); *(u32x2*)dst = o; }
;     S = S * gC + acc;
; }
	v_lshlrev_b32_e32 v44, 16, v2
	v_lshlrev_b32_e32 v45, 16, v3
	v_lshlrev_b32_e32 v46, 16, v4
	v_lshlrev_b32_e32 v47, 16, v5
	v_and_b32_e32 v2, 0xffff0000, v2
	v_and_b32_e32 v3, 0xffff0000, v3
	v_and_b32_e32 v4, 0xffff0000, v4
	v_and_b32_e32 v5, 0xffff0000, v5
	v_mul_f32_e32 v44, v224, v44
	v_mul_f32_e32 v45, v226, v45
	v_mul_f32_e32 v46, v228, v46
	v_mul_f32_e32 v47, v230, v47
	v_mul_f32_e32 v2, v225, v2
	v_mul_f32_e32 v3, v227, v3
	v_mul_f32_e32 v4, v229, v4
	v_mul_f32_e32 v5, v231, v5
	v_cvt_pk_bf16_f32 v44, v44, v2
	v_cvt_pk_bf16_f32 v45, v45, v3
	v_cvt_pk_bf16_f32 v46, v46, v4
	v_cvt_pk_bf16_f32 v47, v47, v5
	v_lshlrev_b32_e32 v86, 16, v6
	v_lshlrev_b32_e32 v87, 16, v7
	v_lshlrev_b32_e32 v88, 16, v8
	v_lshlrev_b32_e32 v89, 16, v9
	v_and_b32_e32 v6, 0xffff0000, v6
	v_and_b32_e32 v7, 0xffff0000, v7
	v_and_b32_e32 v8, 0xffff0000, v8
	v_and_b32_e32 v9, 0xffff0000, v9
	v_mul_f32_e32 v86, v232, v86
	v_mul_f32_e32 v87, v234, v87
	v_mul_f32_e32 v88, v236, v88
	v_mul_f32_e32 v89, v238, v89
	v_mul_f32_e32 v6, v233, v6
	v_mul_f32_e32 v7, v235, v7
	v_mul_f32_e32 v8, v237, v8
	v_mul_f32_e32 v9, v239, v9
	v_cvt_pk_bf16_f32 v86, v86, v6
	v_cvt_pk_bf16_f32 v87, v87, v7
	v_cvt_pk_bf16_f32 v88, v88, v8
	v_cvt_pk_bf16_f32 v89, v89, v9
	s_nop 0
	v_mfma_f32_16x16x32_bf16 v[40:43], v[44:47], v[70:73], 0
	v_lshlrev_b32_e32 v44, 16, v10
	v_lshlrev_b32_e32 v45, 16, v11
	v_lshlrev_b32_e32 v46, 16, v12
	v_lshlrev_b32_e32 v47, 16, v13
	v_and_b32_e32 v10, 0xffff0000, v10
	v_and_b32_e32 v11, 0xffff0000, v11
	v_and_b32_e32 v12, 0xffff0000, v12
	v_and_b32_e32 v13, 0xffff0000, v13
	v_mul_f32_e32 v44, v240, v44
	v_mul_f32_e32 v45, v242, v45
	v_mul_f32_e32 v46, v244, v46
	v_mul_f32_e32 v47, v246, v47
	v_mul_f32_e32 v10, v241, v10
	v_mul_f32_e32 v11, v243, v11
	v_mul_f32_e32 v12, v245, v12
	v_mul_f32_e32 v13, v247, v13
	v_cvt_pk_bf16_f32 v44, v44, v10
	v_cvt_pk_bf16_f32 v45, v45, v11
	v_cvt_pk_bf16_f32 v46, v46, v12
	v_cvt_pk_bf16_f32 v47, v47, v13
	v_mfma_f32_16x16x32_bf16 v[40:43], v[86:89], v[74:77], v[40:43]
	v_lshlrev_b32_e32 v86, 16, v14
	v_lshlrev_b32_e32 v87, 16, v15
	v_lshlrev_b32_e32 v88, 16, v16
	v_lshlrev_b32_e32 v89, 16, v17
	v_and_b32_e32 v14, 0xffff0000, v14
	v_and_b32_e32 v15, 0xffff0000, v15
	v_and_b32_e32 v16, 0xffff0000, v16
	v_and_b32_e32 v17, 0xffff0000, v17
	v_mul_f32_e32 v86, v248, v86
	v_mul_f32_e32 v87, v250, v87
	v_mul_f32_e32 v88, v210, v88
	v_mul_f32_e32 v89, v212, v89
	v_mul_f32_e32 v14, v249, v14
	v_mul_f32_e32 v15, v251, v15
	v_mul_f32_e32 v16, v211, v16
	v_mul_f32_e32 v17, v213, v17
	v_cvt_pk_bf16_f32 v86, v86, v14
	v_cvt_pk_bf16_f32 v87, v87, v15
	v_cvt_pk_bf16_f32 v88, v88, v16
	v_cvt_pk_bf16_f32 v89, v89, v17
	v_mfma_f32_16x16x32_bf16 v[40:43], v[44:47], v[78:81], v[40:43]
	s_nop 1
	v_mfma_f32_16x16x32_bf16 v[40:43], v[86:89], v[82:85], v[40:43]
	s_add_u32 s8, s20, 0x68000
	s_addc_u32 s9, s21, 0
	v_cvt_pk_bf16_f32 v48, v36, v37
	v_cvt_pk_bf16_f32 v49, v38, v39
	global_store_dwordx2 v172, v[48:49], s[8:9]
	s_nop 7
	v_pk_fma_f32 v[36:37], v[90:91], v[36:37], v[40:41] op_sel_hi:[0,1,1]
	v_pk_fma_f32 v[38:39], v[90:91], v[38:39], v[42:43] op_sel_hi:[0,1,1]
	s_waitcnt vmcnt(10)
	v_lshlrev_b32_e32 v44, 16, v20
	v_lshlrev_b32_e32 v45, 16, v21
	v_lshlrev_b32_e32 v46, 16, v22
	v_lshlrev_b32_e32 v47, 16, v23
	v_and_b32_e32 v20, 0xffff0000, v20
	v_and_b32_e32 v21, 0xffff0000, v21
	v_and_b32_e32 v22, 0xffff0000, v22
	v_and_b32_e32 v23, 0xffff0000, v23
	v_mul_f32_e32 v44, v224, v44
	v_mul_f32_e32 v45, v226, v45
	v_mul_f32_e32 v46, v228, v46
	v_mul_f32_e32 v47, v230, v47
	v_mul_f32_e32 v20, v225, v20
	v_mul_f32_e32 v21, v227, v21
	v_mul_f32_e32 v22, v229, v22
	v_mul_f32_e32 v23, v231, v23
	v_cvt_pk_bf16_f32 v44, v44, v20
	v_cvt_pk_bf16_f32 v45, v45, v21
	v_cvt_pk_bf16_f32 v46, v46, v22
	v_cvt_pk_bf16_f32 v47, v47, v23
	v_lshlrev_b32_e32 v86, 16, v24
	v_lshlrev_b32_e32 v87, 16, v25
	v_lshlrev_b32_e32 v88, 16, v26
	v_lshlrev_b32_e32 v89, 16, v27
	v_and_b32_e32 v24, 0xffff0000, v24
	v_and_b32_e32 v25, 0xffff0000, v25
	v_and_b32_e32 v26, 0xffff0000, v26
	v_and_b32_e32 v27, 0xffff0000, v27
	v_mul_f32_e32 v86, v232, v86
	v_mul_f32_e32 v87, v234, v87
	v_mul_f32_e32 v88, v236, v88
	v_mul_f32_e32 v89, v238, v89
	v_mul_f32_e32 v24, v233, v24
	v_mul_f32_e32 v25, v235, v25
	v_mul_f32_e32 v26, v237, v26
	v_mul_f32_e32 v27, v239, v27
	v_cvt_pk_bf16_f32 v86, v86, v24
	v_cvt_pk_bf16_f32 v87, v87, v25
	v_cvt_pk_bf16_f32 v88, v88, v26
	v_cvt_pk_bf16_f32 v89, v89, v27
	s_nop 0
	v_mfma_f32_16x16x32_bf16 v[40:43], v[44:47], v[94:97], 0
	v_lshlrev_b32_e32 v44, 16, v28
	v_lshlrev_b32_e32 v45, 16, v29
	v_lshlrev_b32_e32 v46, 16, v30
	v_lshlrev_b32_e32 v47, 16, v31
	v_and_b32_e32 v28, 0xffff0000, v28
	v_and_b32_e32 v29, 0xffff0000, v29
	v_and_b32_e32 v30, 0xffff0000, v30
	v_and_b32_e32 v31, 0xffff0000, v31
	v_mul_f32_e32 v44, v240, v44
	v_mul_f32_e32 v45, v242, v45
	v_mul_f32_e32 v46, v244, v46
	v_mul_f32_e32 v47, v246, v47
	v_mul_f32_e32 v28, v241, v28
	v_mul_f32_e32 v29, v243, v29
	v_mul_f32_e32 v30, v245, v30
	v_mul_f32_e32 v31, v247, v31
	v_cvt_pk_bf16_f32 v44, v44, v28
	v_cvt_pk_bf16_f32 v45, v45, v29
	v_cvt_pk_bf16_f32 v46, v46, v30
	v_cvt_pk_bf16_f32 v47, v47, v31
	v_mfma_f32_16x16x32_bf16 v[40:43], v[86:89], v[98:101], v[40:43]
	v_lshlrev_b32_e32 v86, 16, v32
	v_lshlrev_b32_e32 v87, 16, v33
	v_lshlrev_b32_e32 v88, 16, v34
	v_lshlrev_b32_e32 v89, 16, v35
	v_and_b32_e32 v32, 0xffff0000, v32
	v_and_b32_e32 v33, 0xffff0000, v33
	v_and_b32_e32 v34, 0xffff0000, v34
	v_and_b32_e32 v35, 0xffff0000, v35
	v_mul_f32_e32 v86, v248, v86
	v_mul_f32_e32 v87, v250, v87
	v_mul_f32_e32 v88, v210, v88
	v_mul_f32_e32 v89, v212, v89
	v_mul_f32_e32 v32, v249, v32
	v_mul_f32_e32 v33, v251, v33
	v_mul_f32_e32 v34, v211, v34
	v_mul_f32_e32 v35, v213, v35
	v_cvt_pk_bf16_f32 v86, v86, v32
	v_cvt_pk_bf16_f32 v87, v87, v33
	v_cvt_pk_bf16_f32 v88, v88, v34
	v_cvt_pk_bf16_f32 v89, v89, v35
	v_mfma_f32_16x16x32_bf16 v[40:43], v[44:47], v[102:105], v[40:43]
	s_nop 1
	v_mfma_f32_16x16x32_bf16 v[40:43], v[86:89], v[106:109], v[40:43]
	s_add_u32 s8, s20, 0x70000
	s_addc_u32 s9, s21, 0
	v_cvt_pk_bf16_f32 v48, v36, v37
	v_cvt_pk_bf16_f32 v49, v38, v39
	global_store_dwordx2 v172, v[48:49], s[8:9]
	s_nop 7
	v_pk_fma_f32 v[36:37], v[90:91], v[36:37], v[40:41] op_sel_hi:[0,1,1]
	v_pk_fma_f32 v[38:39], v[90:91], v[38:39], v[42:43] op_sel_hi:[0,1,1]
	s_waitcnt vmcnt(2)
; __device__ __forceinline__ unsigned cvt_pk_bf16(float lo, float hi) { unsigned r; asm("v_cvt_pk_bf16_f32 %0, %1, %2" : "=v"(r) : "v"(lo), "v"(hi)); return r; }
; __device__ __forceinline__ float bf2f(unsigned b) { return __uint_as_float(b << 16); }
; __device__ __forceinline__ void r1s_step(const bf16x8 (&kk)[4], const bf16x8 (&vv)[4], const float (&w)[4][8], f32x4& S, float gC, bool st, bf16_t* dst) {
;     f32x4 acc = {0.f, 0.f, 0.f, 0.f};
; #pragma unroll
;     for (int ks = 0; ks < 4; ++ks) {
;         float f[8];
; #pragma unroll
;         for (int e = 0; e < 8; ++e) f[e] = bf2f((unsigned)(unsigned short)kk[ks][e]) * w[ks][e];
;         u32x4 wf; wf.x = cvt_pk_bf16(f[0], f[1]); wf.y = cvt_pk_bf16(f[2], f[3]); wf.z = cvt_pk_bf16(f[4], f[5]); wf.w = cvt_pk_bf16(f[6], f[7]);
;         acc = __builtin_amdgcn_mfma_f32_16x16x32_bf16(__builtin_bit_cast(bf16x8, wf), vv[ks], acc, 0, 0, 0);
;     }
;     if (st) { u32x2 o; o.x = cvt_pk_bf16(S[0], S[1]); o.y = cvt_pk_bf16(S[2], S[3]); *(u32x2*)dst = o; }
;     S = S * gC + acc;
; }
; __device__ __forceinline__ void r1s_sweep(const bf16_t* __restrict__ kT, const bf16_t* __restrict__ vT, bf16_t* __restrict__ STd, int bh, int s, int wid, int fr, int fq, float lg, float gC, bool fwd) {
;     ...
;         for (int e = 0; e < 8; ++e) { const int t = 32 * ks + 8 * fq + e; w[ks][e] = __builtin_amdgcn_exp2f(lg * (float)(fwd ? 127 - t : t)); }
;     f32x4 S = {0.f, 0.f, 0.f, 0.f};
;     const size_t koff = (size_t)(16 * s + fr) * 128 + 8 * fq, voff = (size_t)(16 * wid + fr) * 128 + 8 * fq;
;     bf16_t* dst0 = STd + (16 * wid + fr) * 128 + 16 * s + 4 * fq;
;     ...
;     bf16x8 kA[4], vA[4], kB[4], vB[4];
;     r1s_load(kT, vT, bh, R1S_CC(0), koff, voff, kA, vA);
; __device__ __forceinline__ void r1s_phase(KP p, int G, int bid, int wv) {
;     ...
;         r1s_sweep(kT, vT, ST + (size_t)(bh * 2 + 0) * 16 * 16384, bh, s, wid, fr, fq, lf, __builtin_amdgcn_exp2f(128.0f * lf), true);
;         r1s_sweep(kT, vT, ST + (size_t)(bh * 2 + 1) * 16 * 16384, bh, s, wid, fr, fq, lb, __builtin_amdgcn_exp2f(128.0f * lb), false);
	v_lshlrev_b32_e32 v44, 16, v54
	v_lshlrev_b32_e32 v45, 16, v55
	v_lshlrev_b32_e32 v46, 16, v56
	v_lshlrev_b32_e32 v47, 16, v57
	v_and_b32_e32 v54, 0xffff0000, v54
	v_and_b32_e32 v55, 0xffff0000, v55
	v_and_b32_e32 v56, 0xffff0000, v56
	v_and_b32_e32 v57, 0xffff0000, v57
	v_mul_f32_e32 v44, v224, v44
	v_mul_f32_e32 v45, v226, v45
	v_mul_f32_e32 v46, v228, v46
	v_mul_f32_e32 v47, v230, v47
	v_mul_f32_e32 v54, v225, v54
	v_mul_f32_e32 v55, v227, v55
	v_mul_f32_e32 v56, v229, v56
	v_mul_f32_e32 v57, v231, v57
	v_cvt_pk_bf16_f32 v44, v44, v54
	v_cvt_pk_bf16_f32 v45, v45, v55
	v_cvt_pk_bf16_f32 v46, v46, v56
	v_cvt_pk_bf16_f32 v47, v47, v57
	v_lshlrev_b32_e32 v86, 16, v58
	v_lshlrev_b32_e32 v87, 16, v59
	v_lshlrev_b32_e32 v88, 16, v60
	v_lshlrev_b32_e32 v89, 16, v61
	v_and_b32_e32 v58, 0xffff0000, v58
	v_and_b32_e32 v59, 0xffff0000, v59
	v_and_b32_e32 v60, 0xffff0000, v60
	v_and_b32_e32 v61, 0xffff0000, v61
	v_mul_f32_e32 v86, v232, v86
	v_mul_f32_e32 v87, v234, v87
	v_mul_f32_e32 v88, v236, v88
	v_mul_f32_e32 v89, v238, v89
	v_mul_f32_e32 v58, v233, v58
	v_mul_f32_e32 v59, v235, v59
	v_mul_f32_e32 v60, v237, v60
	v_mul_f32_e32 v61, v239, v61
	v_cvt_pk_bf16_f32 v86, v86, v58
	v_cvt_pk_bf16_f32 v87, v87, v59
	v_cvt_pk_bf16_f32 v88, v88, v60
	v_cvt_pk_bf16_f32 v89, v89, v61
	s_nop 0
	v_mfma_f32_16x16x32_bf16 v[40:43], v[44:47], v[110:113], 0
	v_lshlrev_b32_e32 v44, 16, v62
	v_lshlrev_b32_e32 v45, 16, v63
	v_lshlrev_b32_e32 v46, 16, v64
	v_lshlrev_b32_e32 v47, 16, v65
	v_and_b32_e32 v62, 0xffff0000, v62
	v_and_b32_e32 v63, 0xffff0000, v63
	v_and_b32_e32 v64, 0xffff0000, v64
	v_and_b32_e32 v65, 0xffff0000, v65
	v_mul_f32_e32 v44, v240, v44
	v_mul_f32_e32 v45, v242, v45
	v_mul_f32_e32 v46, v244, v46
	v_mul_f32_e32 v47, v246, v47
	v_mul_f32_e32 v62, v241, v62
	v_mul_f32_e32 v63, v243, v63
	v_mul_f32_e32 v64, v245, v64
	v_mul_f32_e32 v65, v247, v65
	v_cvt_pk_bf16_f32 v44, v44, v62
	v_cvt_pk_bf16_f32 v45, v45, v63
	v_cvt_pk_bf16_f32 v46, v46, v64
	v_cvt_pk_bf16_f32 v47, v47, v65
	v_mfma_f32_16x16x32_bf16 v[40:43], v[86:89], v[114:117], v[40:43]
	v_lshlrev_b32_e32 v86, 16, v66
	v_lshlrev_b32_e32 v87, 16, v67
	v_lshlrev_b32_e32 v88, 16, v68
	v_lshlrev_b32_e32 v89, 16, v69
	v_and_b32_e32 v66, 0xffff0000, v66
	v_and_b32_e32 v67, 0xffff0000, v67
	v_and_b32_e32 v68, 0xffff0000, v68
	v_and_b32_e32 v69, 0xffff0000, v69
	v_mul_f32_e32 v86, v248, v86
	v_mul_f32_e32 v87, v250, v87
	v_mul_f32_e32 v88, v210, v88
	v_mul_f32_e32 v89, v212, v89
	v_mul_f32_e32 v66, v249, v66
	v_mul_f32_e32 v67, v251, v67
	v_mul_f32_e32 v68, v211, v68
	v_mul_f32_e32 v69, v213, v69
	v_cvt_pk_bf16_f32 v86, v86, v66
	v_cvt_pk_bf16_f32 v87, v87, v67
	v_cvt_pk_bf16_f32 v88, v88, v68
	v_cvt_pk_bf16_f32 v89, v89, v69
	v_mfma_f32_16x16x32_bf16 v[40:43], v[44:47], v[118:121], v[40:43]
	s_nop 1
	v_mfma_f32_16x16x32_bf16 v[40:43], v[86:89], v[122:125], v[40:43]
	s_add_u32 s8, s20, 0x78000
	s_addc_u32 s9, s21, 0
	v_cvt_pk_bf16_f32 v48, v36, v37
	v_cvt_pk_bf16_f32 v49, v38, v39
	global_store_dwordx2 v172, v[48:49], s[8:9]
	s_nop 7
	v_pk_fma_f32 v[36:37], v[90:91], v[36:37], v[40:41] op_sel_hi:[0,1,1]
	v_pk_fma_f32 v[38:39], v[90:91], v[38:39], v[42:43] op_sel_hi:[0,1,1]
	s_add_u32 s8, s16, 0x8000
	s_addc_u32 s9, s17, 0
	s_add_u32 s10, s18, 0x8000
	s_addc_u32 s11, s19, 0
	global_load_dwordx4 v[2:5], v170, s[8:9]
	global_load_dwordx4 v[6:9], v170, s[8:9] offset:64
	global_load_dwordx4 v[10:13], v170, s[8:9] offset:128
	global_load_dwordx4 v[14:17], v170, s[8:9] offset:192
	global_load_dwordx4 v[70:73], v171, s[10:11]
	global_load_dwordx4 v[74:77], v171, s[10:11] offset:64
	global_load_dwordx4 v[78:81], v171, s[10:11] offset:128
	global_load_dwordx4 v[82:85], v171, s[10:11] offset:192
	s_add_u32 s8, s16, 0x0
	s_addc_u32 s9, s17, 0
	s_add_u32 s10, s18, 0x0
	s_addc_u32 s11, s19, 0
	global_load_dwordx4 v[20:23], v170, s[8:9]
	global_load_dwordx4 v[24:27], v170, s[8:9] offset:64
	global_load_dwordx4 v[28:31], v170, s[8:9] offset:128
	global_load_dwordx4 v[32:35], v170, s[8:9] offset:192
	global_load_dwordx4 v[94:97], v171, s[10:11]
	global_load_dwordx4 v[98:101], v171, s[10:11] offset:64
	global_load_dwordx4 v[102:105], v171, s[10:11] offset:128
	global_load_dwordx4 v[106:109], v171, s[10:11] offset:192
	v_add_u32_e32 v168, 0, v167
	v_cvt_f32_u32_e32 v168, v168
	v_mul_f32_e32 v168, v163, v168
	v_exp_f32_e32 v224, v168
	v_add_u32_e32 v168, 1, v167
	v_cvt_f32_u32_e32 v168, v168
	v_mul_f32_e32 v168, v163, v168
	v_exp_f32_e32 v225, v168
	v_add_u32_e32 v168, 2, v167
	v_cvt_f32_u32_e32 v168, v168
	v_mul_f32_e32 v168, v163, v168
	v_exp_f32_e32 v226, v168
	v_add_u32_e32 v168, 3, v167
	v_cvt_f32_u32_e32 v168, v168
	v_mul_f32_e32 v168, v163, v168
	v_exp_f32_e32 v227, v168
	v_add_u32_e32 v168, 4, v167
	v_cvt_f32_u32_e32 v168, v168
	v_mul_f32_e32 v168, v163, v168
	v_exp_f32_e32 v228, v168
	v_add_u32_e32 v168, 5, v167
	v_cvt_f32_u32_e32 v168, v168
	v_mul_f32_e32 v168, v163, v168
	v_exp_f32_e32 v229, v168
	v_add_u32_e32 v168, 6, v167
	v_cvt_f32_u32_e32 v168, v168
	v_mul_f32_e32 v168, v163, v168
	v_exp_f32_e32 v230, v168
	v_add_u32_e32 v168, 7, v167
	v_cvt_f32_u32_e32 v168, v168
	v_mul_f32_e32 v168, v163, v168
	v_exp_f32_e32 v231, v168
	v_add_u32_e32 v168, 32, v167
	v_cvt_f32_u32_e32 v168, v168
	v_mul_f32_e32 v168, v163, v168
	v_exp_f32_e32 v232, v168
	v_add_u32_e32 v168, 33, v167
	v_cvt_f32_u32_e32 v168, v168
	v_mul_f32_e32 v168, v163, v168
	v_exp_f32_e32 v233, v168
	v_add_u32_e32 v168, 34, v167
	v_cvt_f32_u32_e32 v168, v168
	v_mul_f32_e32 v168, v163, v168
	v_exp_f32_e32 v234, v168
	v_add_u32_e32 v168, 35, v167
	v_cvt_f32_u32_e32 v168, v168
	v_mul_f32_e32 v168, v163, v168
	v_exp_f32_e32 v235, v168
	v_add_u32_e32 v168, 36, v167
; __device__ __forceinline__ void r1s_sweep(const bf16_t* __restrict__ kT, const bf16_t* __restrict__ vT, bf16_t* __restrict__ STd, int bh, int s, int wid, int fr, int fq, float lg, float gC, bool fwd) {
;     float w[4][8];
; #pragma unroll
;     for (int ks = 0; ks < 4; ++ks)
; #pragma unroll
;         for (int e = 0; e < 8; ++e) { const int t = 32 * ks + 8 * fq + e; w[ks][e] = __builtin_amdgcn_exp2f(lg * (float)(fwd ? 127 - t : t)); }
;     f32x4 S = {0.f, 0.f, 0.f, 0.f};
;     const size_t koff = (size_t)(16 * s + fr) * 128 + 8 * fq, voff = (size_t)(16 * wid + fr) * 128 + 8 * fq;
;     bf16_t* dst0 = STd + (16 * wid + fr) * 128 + 16 * s + 4 * fq;
;     ...
;     bf16x8 kA[4], vA[4], kB[4], vB[4];
;     r1s_load(kT, vT, bh, R1S_CC(0), koff, voff, kA, vA);
; #pragma unroll
;     for (int i = 0; i < 18; i += 2) {
;         r1s_load(kT, vT, bh, R1S_CC(i + 1), koff, voff, kB, vB);
;         { const int cc = R1S_CC(i); r1s_step(kA, vA, w, S, gC, cc >= 2, dst0 + (size_t)(cc >= 2 ? cc - 2 : 0) * 16384); }
;         if (i + 2 < 18) r1s_load(kT, vT, bh, R1S_CC(i + 2), koff, voff, kA, vA);
;         { const int cc = R1S_CC(i + 1); r1s_step(kB, vB, w, S, gC, cc >= 2, dst0 + (size_t)(cc >= 2 ? cc - 2 : 0) * 16384); }
; __device__ __forceinline__ void r1s_phase(KP p, int G, int bid, int wv) {
;     ...
;         r1s_sweep(kT, vT, ST + (size_t)(bh * 2 + 0) * 16 * 16384, bh, s, wid, fr, fq, lf, __builtin_amdgcn_exp2f(128.0f * lf), true);
;         r1s_sweep(kT, vT, ST + (size_t)(bh * 2 + 1) * 16 * 16384, bh, s, wid, fr, fq, lb, __builtin_amdgcn_exp2f(128.0f * lb), false);
	v_cvt_f32_u32_e32 v168, v168
	v_mul_f32_e32 v168, v163, v168
	v_exp_f32_e32 v236, v168
	v_add_u32_e32 v168, 37, v167
	v_cvt_f32_u32_e32 v168, v168
	v_mul_f32_e32 v168, v163, v168
	v_exp_f32_e32 v237, v168
	v_add_u32_e32 v168, 38, v167
	v_cvt_f32_u32_e32 v168, v168
	v_mul_f32_e32 v168, v163, v168
	v_exp_f32_e32 v238, v168
	v_add_u32_e32 v168, 39, v167
	v_cvt_f32_u32_e32 v168, v168
	v_mul_f32_e32 v168, v163, v168
	v_exp_f32_e32 v239, v168
	v_add_u32_e32 v168, 64, v167
	v_cvt_f32_u32_e32 v168, v168
	v_mul_f32_e32 v168, v163, v168
	v_exp_f32_e32 v240, v168
	v_add_u32_e32 v168, 65, v167
	v_cvt_f32_u32_e32 v168, v168
	v_mul_f32_e32 v168, v163, v168
	v_exp_f32_e32 v241, v168
	v_add_u32_e32 v168, 66, v167
	v_cvt_f32_u32_e32 v168, v168
	v_mul_f32_e32 v168, v163, v168
	v_exp_f32_e32 v242, v168
	v_add_u32_e32 v168, 67, v167
	v_cvt_f32_u32_e32 v168, v168
	v_mul_f32_e32 v168, v163, v168
	v_exp_f32_e32 v243, v168
	v_add_u32_e32 v168, 68, v167
	v_cvt_f32_u32_e32 v168, v168
	v_mul_f32_e32 v168, v163, v168
	v_exp_f32_e32 v244, v168
	v_add_u32_e32 v168, 69, v167
	v_cvt_f32_u32_e32 v168, v168
	v_mul_f32_e32 v168, v163, v168
	v_exp_f32_e32 v245, v168
	v_add_u32_e32 v168, 70, v167
	v_cvt_f32_u32_e32 v168, v168
	v_mul_f32_e32 v168, v163, v168
	v_exp_f32_e32 v246, v168
	v_add_u32_e32 v168, 71, v167
	v_cvt_f32_u32_e32 v168, v168
	v_mul_f32_e32 v168, v163, v168
	v_exp_f32_e32 v247, v168
	v_add_u32_e32 v168, 96, v167
	v_cvt_f32_u32_e32 v168, v168
	v_mul_f32_e32 v168, v163, v168
	v_exp_f32_e32 v248, v168
	v_add_u32_e32 v168, 97, v167
	v_cvt_f32_u32_e32 v168, v168
	v_mul_f32_e32 v168, v163, v168
	v_exp_f32_e32 v249, v168
	v_add_u32_e32 v168, 98, v167
	v_cvt_f32_u32_e32 v168, v168
	v_mul_f32_e32 v168, v163, v168
	v_exp_f32_e32 v250, v168
	v_add_u32_e32 v168, 99, v167
	v_cvt_f32_u32_e32 v168, v168
	v_mul_f32_e32 v168, v163, v168
	v_exp_f32_e32 v251, v168
	v_add_u32_e32 v168, 100, v167
	v_cvt_f32_u32_e32 v168, v168
	v_mul_f32_e32 v168, v163, v168
	v_exp_f32_e32 v210, v168
	v_add_u32_e32 v168, 101, v167
	v_cvt_f32_u32_e32 v168, v168
	v_mul_f32_e32 v168, v163, v168
	v_exp_f32_e32 v211, v168
	v_add_u32_e32 v168, 102, v167
	v_cvt_f32_u32_e32 v168, v168
	v_mul_f32_e32 v168, v163, v168
	v_exp_f32_e32 v212, v168
	v_add_u32_e32 v168, 103, v167
	v_cvt_f32_u32_e32 v168, v168
	v_mul_f32_e32 v168, v163, v168
	v_exp_f32_e32 v213, v168
	v_mul_f32_e32 v168, 0x43000000, v163
	v_exp_f32_e32 v90, v168
	v_mov_b32_e32 v36, 0
	v_mov_b32_e32 v37, 0
	v_mov_b32_e32 v38, 0
	v_mov_b32_e32 v39, 0
	s_ashr_i32 s20, s1, 3
	s_lshl_b32 s20, s20, 20
	s_add_u32 s20, s20, 0x80000
	s_add_u32 s20, s20, 0xac00000
	s_add_u32 s20, s2, s20
	s_addc_u32 s21, s3, 0
	s_add_u32 s8, s16, 0x88000
	s_addc_u32 s9, s17, 0
	s_add_u32 s10, s18, 0x88000
	s_addc_u32 s11, s19, 0
	global_load_dwordx4 v[54:57], v170, s[8:9]
	global_load_dwordx4 v[58:61], v170, s[8:9] offset:64
	global_load_dwordx4 v[62:65], v170, s[8:9] offset:128
	global_load_dwordx4 v[66:69], v170, s[8:9] offset:192
	global_load_dwordx4 v[110:113], v171, s[10:11]
	global_load_dwordx4 v[114:117], v171, s[10:11] offset:64
	global_load_dwordx4 v[118:121], v171, s[10:11] offset:128
	global_load_dwordx4 v[122:125], v171, s[10:11] offset:192
	s_waitcnt vmcnt(16)
	v_lshlrev_b32_e32 v44, 16, v2
	v_lshlrev_b32_e32 v45, 16, v3
	v_lshlrev_b32_e32 v46, 16, v4
	v_lshlrev_b32_e32 v47, 16, v5
	v_and_b32_e32 v2, 0xffff0000, v2
	v_and_b32_e32 v3, 0xffff0000, v3
	v_and_b32_e32 v4, 0xffff0000, v4
	v_and_b32_e32 v5, 0xffff0000, v5
	v_mul_f32_e32 v44, v224, v44
	v_mul_f32_e32 v45, v226, v45
	v_mul_f32_e32 v46, v228, v46
	v_mul_f32_e32 v47, v230, v47
	v_mul_f32_e32 v2, v225, v2
	v_mul_f32_e32 v3, v227, v3
	v_mul_f32_e32 v4, v229, v4
	v_mul_f32_e32 v5, v231, v5
	v_cvt_pk_bf16_f32 v44, v44, v2
	v_cvt_pk_bf16_f32 v45, v45, v3
	v_cvt_pk_bf16_f32 v46, v46, v4
	v_cvt_pk_bf16_f32 v47, v47, v5
	v_lshlrev_b32_e32 v86, 16, v6
	v_lshlrev_b32_e32 v87, 16, v7
	v_lshlrev_b32_e32 v88, 16, v8
	v_lshlrev_b32_e32 v89, 16, v9
	v_and_b32_e32 v6, 0xffff0000, v6
	v_and_b32_e32 v7, 0xffff0000, v7
	v_and_b32_e32 v8, 0xffff0000, v8
	v_and_b32_e32 v9, 0xffff0000, v9
	v_mul_f32_e32 v86, v232, v86
	v_mul_f32_e32 v87, v234, v87
	v_mul_f32_e32 v88, v236, v88
	v_mul_f32_e32 v89, v238, v89
	v_mul_f32_e32 v6, v233, v6
	v_mul_f32_e32 v7, v235, v7
	v_mul_f32_e32 v8, v237, v8
	v_mul_f32_e32 v9, v239, v9
	v_cvt_pk_bf16_f32 v86, v86, v6
	v_cvt_pk_bf16_f32 v87, v87, v7
	v_cvt_pk_bf16_f32 v88, v88, v8
	v_cvt_pk_bf16_f32 v89, v89, v9
	s_nop 0
	v_mfma_f32_16x16x32_bf16 v[40:43], v[44:47], v[70:73], 0
	v_lshlrev_b32_e32 v44, 16, v10
	v_lshlrev_b32_e32 v45, 16, v11
	v_lshlrev_b32_e32 v46, 16, v12
	v_lshlrev_b32_e32 v47, 16, v13
	v_and_b32_e32 v10, 0xffff0000, v10
	v_and_b32_e32 v11, 0xffff0000, v11
	v_and_b32_e32 v12, 0xffff0000, v12
	v_and_b32_e32 v13, 0xffff0000, v13
	v_mul_f32_e32 v44, v240, v44
	v_mul_f32_e32 v45, v242, v45
	v_mul_f32_e32 v46, v244, v46
	v_mul_f32_e32 v47, v246, v47
	v_mul_f32_e32 v10, v241, v10
	v_mul_f32_e32 v11, v243, v11
	v_mul_f32_e32 v12, v245, v12
	v_mul_f32_e32 v13, v247, v13
	v_cvt_pk_bf16_f32 v44, v44, v10
	v_cvt_pk_bf16_f32 v45, v45, v11
	v_cvt_pk_bf16_f32 v46, v46, v12
	v_cvt_pk_bf16_f32 v47, v47, v13
	v_mfma_f32_16x16x32_bf16 v[40:43], v[86:89], v[74:77], v[40:43]
	v_lshlrev_b32_e32 v86, 16, v14
	v_lshlrev_b32_e32 v87, 16, v15
	v_lshlrev_b32_e32 v88, 16, v16
	v_lshlrev_b32_e32 v89, 16, v17
	v_and_b32_e32 v14, 0xffff0000, v14
	v_and_b32_e32 v15, 0xffff0000, v15
	v_and_b32_e32 v16, 0xffff0000, v16
	v_and_b32_e32 v17, 0xffff0000, v17
	v_mul_f32_e32 v86, v248, v86
	v_mul_f32_e32 v87, v250, v87
	v_mul_f32_e32 v88, v210, v88
	v_mul_f32_e32 v89, v212, v89
	v_mul_f32_e32 v14, v249, v14
	v_mul_f32_e32 v15, v251, v15
	v_mul_f32_e32 v16, v211, v16
	v_mul_f32_e32 v17, v213, v17
	v_cvt_pk_bf16_f32 v86, v86, v14
	v_cvt_pk_bf16_f32 v87, v87, v15
	v_cvt_pk_bf16_f32 v88, v88, v16
	v_cvt_pk_bf16_f32 v89, v89, v17
	v_mfma_f32_16x16x32_bf16 v[40:43], v[44:47], v[78:81], v[40:43]
	s_nop 1
	v_mfma_f32_16x16x32_bf16 v[40:43], v[86:89], v[82:85], v[40:43]
	s_nop 7
	v_pk_fma_f32 v[36:37], v[90:91], v[36:37], v[40:41] op_sel_hi:[0,1,1]
	v_pk_fma_f32 v[38:39], v[90:91], v[38:39], v[42:43] op_sel_hi:[0,1,1]
	s_add_u32 s8, s16, 0x80000
	s_addc_u32 s9, s17, 0
	s_add_u32 s10, s18, 0x80000
	s_addc_u32 s11, s19, 0
	global_load_dwordx4 v[2:5], v170, s[8:9]
	global_load_dwordx4 v[6:9], v170, s[8:9] offset:64
	global_load_dwordx4 v[10:13], v170, s[8:9] offset:128
	global_load_dwordx4 v[14:17], v170, s[8:9] offset:192
	global_load_dwordx4 v[70:73], v171, s[10:11]
	global_load_dwordx4 v[74:77], v171, s[10:11] offset:64
	global_load_dwordx4 v[78:81], v171, s[10:11] offset:128
	global_load_dwordx4 v[82:85], v171, s[10:11] offset:192
	s_waitcnt vmcnt(16)
; __device__ __forceinline__ unsigned cvt_pk_bf16(float lo, float hi) { unsigned r; asm("v_cvt_pk_bf16_f32 %0, %1, %2" : "=v"(r) : "v"(lo), "v"(hi)); return r; }
; __device__ __forceinline__ float bf2f(unsigned b) { return __uint_as_float(b << 16); }
; __device__ __forceinline__ void r1s_load(const bf16_t* __restrict__ kT, const bf16_t* __restrict__ vT, int bh, int cc, size_t koff, size_t voff, bf16x8 (&kk)[4], bf16x8 (&vv)[4]) {
;     const bf16_t* kt = kT + (size_t)(bh * 18 + cc) * 16384 + koff; const bf16_t* vt = vT + (size_t)(bh * 18 + cc) * 16384 + voff;
; #pragma unroll
;     for (int ks = 0; ks < 4; ++ks) { kk[ks] = *(const bf16x8*)(kt + 32 * ks); vv[ks] = *(const bf16x8*)(vt + 32 * ks); }
; }
; __device__ __forceinline__ void r1s_step(const bf16x8 (&kk)[4], const bf16x8 (&vv)[4], const float (&w)[4][8], f32x4& S, float gC, bool st, bf16_t* dst) {
;     f32x4 acc = {0.f, 0.f, 0.f, 0.f};
; #pragma unroll
;     for (int ks = 0; ks < 4; ++ks) {
;         float f[8];
; #pragma unroll
;         for (int e = 0; e < 8; ++e) f[e] = bf2f((unsigned)(unsigned short)kk[ks][e]) * w[ks][e];
;         u32x4 wf; wf.x = cvt_pk_bf16(f[0], f[1]); wf.y = cvt_pk_bf16(f[2], f[3]); wf.z = cvt_pk_bf16(f[4], f[5]); wf.w = cvt_pk_bf16(f[6], f[7]);
;         acc = __builtin_amdgcn_mfma_f32_16x16x32_bf16(__builtin_bit_cast(bf16x8, wf), vv[ks], acc, 0, 0, 0);
;     }
;     if (st) { u32x2 o; o.x = cvt_pk_bf16(S[0], S[1]); o.y = cvt_pk_bf16(S[2], S[3]); *(u32x2*)dst = o; }
;     S = S * gC + acc;
; }
	v_lshlrev_b32_e32 v44, 16, v20
	v_lshlrev_b32_e32 v45, 16, v21
	v_lshlrev_b32_e32 v46, 16, v22
	v_lshlrev_b32_e32 v47, 16, v23
	v_and_b32_e32 v20, 0xffff0000, v20
	v_and_b32_e32 v21, 0xffff0000, v21
	v_and_b32_e32 v22, 0xffff0000, v22
	v_and_b32_e32 v23, 0xffff0000, v23
	v_mul_f32_e32 v44, v224, v44
	v_mul_f32_e32 v45, v226, v45
	v_mul_f32_e32 v46, v228, v46
	v_mul_f32_e32 v47, v230, v47
	v_mul_f32_e32 v20, v225, v20
	v_mul_f32_e32 v21, v227, v21
	v_mul_f32_e32 v22, v229, v22
	v_mul_f32_e32 v23, v231, v23
	v_cvt_pk_bf16_f32 v44, v44, v20
	v_cvt_pk_bf16_f32 v45, v45, v21
	v_cvt_pk_bf16_f32 v46, v46, v22
	v_cvt_pk_bf16_f32 v47, v47, v23
	v_lshlrev_b32_e32 v86, 16, v24
	v_lshlrev_b32_e32 v87, 16, v25
	v_lshlrev_b32_e32 v88, 16, v26
	v_lshlrev_b32_e32 v89, 16, v27
	v_and_b32_e32 v24, 0xffff0000, v24
	v_and_b32_e32 v25, 0xffff0000, v25
	v_and_b32_e32 v26, 0xffff0000, v26
	v_and_b32_e32 v27, 0xffff0000, v27
	v_mul_f32_e32 v86, v232, v86
	v_mul_f32_e32 v87, v234, v87
	v_mul_f32_e32 v88, v236, v88
	v_mul_f32_e32 v89, v238, v89
	v_mul_f32_e32 v24, v233, v24
	v_mul_f32_e32 v25, v235, v25
	v_mul_f32_e32 v26, v237, v26
	v_mul_f32_e32 v27, v239, v27
	v_cvt_pk_bf16_f32 v86, v86, v24
	v_cvt_pk_bf16_f32 v87, v87, v25
	v_cvt_pk_bf16_f32 v88, v88, v26
	v_cvt_pk_bf16_f32 v89, v89, v27
	s_nop 0
	v_mfma_f32_16x16x32_bf16 v[40:43], v[44:47], v[94:97], 0
	v_lshlrev_b32_e32 v44, 16, v28
	v_lshlrev_b32_e32 v45, 16, v29
	v_lshlrev_b32_e32 v46, 16, v30
	v_lshlrev_b32_e32 v47, 16, v31
	v_and_b32_e32 v28, 0xffff0000, v28
	v_and_b32_e32 v29, 0xffff0000, v29
	v_and_b32_e32 v30, 0xffff0000, v30
	v_and_b32_e32 v31, 0xffff0000, v31
	v_mul_f32_e32 v44, v240, v44
	v_mul_f32_e32 v45, v242, v45
	v_mul_f32_e32 v46, v244, v46
	v_mul_f32_e32 v47, v246, v47
	v_mul_f32_e32 v28, v241, v28
	v_mul_f32_e32 v29, v243, v29
	v_mul_f32_e32 v30, v245, v30
	v_mul_f32_e32 v31, v247, v31
	v_cvt_pk_bf16_f32 v44, v44, v28
	v_cvt_pk_bf16_f32 v45, v45, v29
	v_cvt_pk_bf16_f32 v46, v46, v30
	v_cvt_pk_bf16_f32 v47, v47, v31
	v_mfma_f32_16x16x32_bf16 v[40:43], v[86:89], v[98:101], v[40:43]
	v_lshlrev_b32_e32 v86, 16, v32
	v_lshlrev_b32_e32 v87, 16, v33
	v_lshlrev_b32_e32 v88, 16, v34
	v_lshlrev_b32_e32 v89, 16, v35
	v_and_b32_e32 v32, 0xffff0000, v32
	v_and_b32_e32 v33, 0xffff0000, v33
	v_and_b32_e32 v34, 0xffff0000, v34
	v_and_b32_e32 v35, 0xffff0000, v35
	v_mul_f32_e32 v86, v248, v86
	v_mul_f32_e32 v87, v250, v87
	v_mul_f32_e32 v88, v210, v88
	v_mul_f32_e32 v89, v212, v89
	v_mul_f32_e32 v32, v249, v32
	v_mul_f32_e32 v33, v251, v33
	v_mul_f32_e32 v34, v211, v34
	v_mul_f32_e32 v35, v213, v35
	v_cvt_pk_bf16_f32 v86, v86, v32
	v_cvt_pk_bf16_f32 v87, v87, v33
	v_cvt_pk_bf16_f32 v88, v88, v34
	v_cvt_pk_bf16_f32 v89, v89, v35
	v_mfma_f32_16x16x32_bf16 v[40:43], v[44:47], v[102:105], v[40:43]
	s_nop 1
	v_mfma_f32_16x16x32_bf16 v[40:43], v[86:89], v[106:109], v[40:43]
	s_nop 7
	v_pk_fma_f32 v[36:37], v[90:91], v[36:37], v[40:41] op_sel_hi:[0,1,1]
	v_pk_fma_f32 v[38:39], v[90:91], v[38:39], v[42:43] op_sel_hi:[0,1,1]
	s_add_u32 s8, s16, 0x78000
	s_addc_u32 s9, s17, 0
	s_add_u32 s10, s18, 0x78000
	s_addc_u32 s11, s19, 0
	global_load_dwordx4 v[20:23], v170, s[8:9]
	global_load_dwordx4 v[24:27], v170, s[8:9] offset:64
	global_load_dwordx4 v[28:31], v170, s[8:9] offset:128
	global_load_dwordx4 v[32:35], v170, s[8:9] offset:192
	global_load_dwordx4 v[94:97], v171, s[10:11]
	global_load_dwordx4 v[98:101], v171, s[10:11] offset:64
	global_load_dwordx4 v[102:105], v171, s[10:11] offset:128
	global_load_dwordx4 v[106:109], v171, s[10:11] offset:192
	s_waitcnt vmcnt(16)
	v_lshlrev_b32_e32 v44, 16, v54
	v_lshlrev_b32_e32 v45, 16, v55
	v_lshlrev_b32_e32 v46, 16, v56
	v_lshlrev_b32_e32 v47, 16, v57
	v_and_b32_e32 v54, 0xffff0000, v54
	v_and_b32_e32 v55, 0xffff0000, v55
	v_and_b32_e32 v56, 0xffff0000, v56
	v_and_b32_e32 v57, 0xffff0000, v57
	v_mul_f32_e32 v44, v224, v44
	v_mul_f32_e32 v45, v226, v45
	v_mul_f32_e32 v46, v228, v46
	v_mul_f32_e32 v47, v230, v47
	v_mul_f32_e32 v54, v225, v54
	v_mul_f32_e32 v55, v227, v55
	v_mul_f32_e32 v56, v229, v56
	v_mul_f32_e32 v57, v231, v57
	v_cvt_pk_bf16_f32 v44, v44, v54
	v_cvt_pk_bf16_f32 v45, v45, v55
	v_cvt_pk_bf16_f32 v46, v46, v56
	v_cvt_pk_bf16_f32 v47, v47, v57
	v_lshlrev_b32_e32 v86, 16, v58
	v_lshlrev_b32_e32 v87, 16, v59
	v_lshlrev_b32_e32 v88, 16, v60
	v_lshlrev_b32_e32 v89, 16, v61
	v_and_b32_e32 v58, 0xffff0000, v58
	v_and_b32_e32 v59, 0xffff0000, v59
	v_and_b32_e32 v60, 0xffff0000, v60
	v_and_b32_e32 v61, 0xffff0000, v61
	v_mul_f32_e32 v86, v232, v86
	v_mul_f32_e32 v87, v234, v87
	v_mul_f32_e32 v88, v236, v88
	v_mul_f32_e32 v89, v238, v89
	v_mul_f32_e32 v58, v233, v58
	v_mul_f32_e32 v59, v235, v59
	v_mul_f32_e32 v60, v237, v60
	v_mul_f32_e32 v61, v239, v61
	v_cvt_pk_bf16_f32 v86, v86, v58
	v_cvt_pk_bf16_f32 v87, v87, v59
	v_cvt_pk_bf16_f32 v88, v88, v60
	v_cvt_pk_bf16_f32 v89, v89, v61
	s_nop 0
	v_mfma_f32_16x16x32_bf16 v[40:43], v[44:47], v[110:113], 0
	v_lshlrev_b32_e32 v44, 16, v62
	v_lshlrev_b32_e32 v45, 16, v63
	v_lshlrev_b32_e32 v46, 16, v64
	v_lshlrev_b32_e32 v47, 16, v65
	v_and_b32_e32 v62, 0xffff0000, v62
	v_and_b32_e32 v63, 0xffff0000, v63
	v_and_b32_e32 v64, 0xffff0000, v64
	v_and_b32_e32 v65, 0xffff0000, v65
	v_mul_f32_e32 v44, v240, v44
	v_mul_f32_e32 v45, v242, v45
	v_mul_f32_e32 v46, v244, v46
	v_mul_f32_e32 v47, v246, v47
	v_mul_f32_e32 v62, v241, v62
	v_mul_f32_e32 v63, v243, v63
	v_mul_f32_e32 v64, v245, v64
	v_mul_f32_e32 v65, v247, v65
	v_cvt_pk_bf16_f32 v44, v44, v62
	v_cvt_pk_bf16_f32 v45, v45, v63
	v_cvt_pk_bf16_f32 v46, v46, v64
	v_cvt_pk_bf16_f32 v47, v47, v65
	v_mfma_f32_16x16x32_bf16 v[40:43], v[86:89], v[114:117], v[40:43]
; __device__ __forceinline__ unsigned cvt_pk_bf16(float lo, float hi) { unsigned r; asm("v_cvt_pk_bf16_f32 %0, %1, %2" : "=v"(r) : "v"(lo), "v"(hi)); return r; }
; __device__ __forceinline__ float bf2f(unsigned b) { return __uint_as_float(b << 16); }
; __device__ __forceinline__ void r1s_load(const bf16_t* __restrict__ kT, const bf16_t* __restrict__ vT, int bh, int cc, size_t koff, size_t voff, bf16x8 (&kk)[4], bf16x8 (&vv)[4]) {
;     const bf16_t* kt = kT + (size_t)(bh * 18 + cc) * 16384 + koff; const bf16_t* vt = vT + (size_t)(bh * 18 + cc) * 16384 + voff;
; #pragma unroll
;     for (int ks = 0; ks < 4; ++ks) { kk[ks] = *(const bf16x8*)(kt + 32 * ks); vv[ks] = *(const bf16x8*)(vt + 32 * ks); }
; }
; __device__ __forceinline__ void r1s_step(const bf16x8 (&kk)[4], const bf16x8 (&vv)[4], const float (&w)[4][8], f32x4& S, float gC, bool st, bf16_t* dst) {
;     f32x4 acc = {0.f, 0.f, 0.f, 0.f};
; #pragma unroll
;     for (int ks = 0; ks < 4; ++ks) {
;         float f[8];
; #pragma unroll
;         for (int e = 0; e < 8; ++e) f[e] = bf2f((unsigned)(unsigned short)kk[ks][e]) * w[ks][e];
;         u32x4 wf; wf.x = cvt_pk_bf16(f[0], f[1]); wf.y = cvt_pk_bf16(f[2], f[3]); wf.z = cvt_pk_bf16(f[4], f[5]); wf.w = cvt_pk_bf16(f[6], f[7]);
;         acc = __builtin_amdgcn_mfma_f32_16x16x32_bf16(__builtin_bit_cast(bf16x8, wf), vv[ks], acc, 0, 0, 0);
;     }
;     if (st) { u32x2 o; o.x = cvt_pk_bf16(S[0], S[1]); o.y = cvt_pk_bf16(S[2], S[3]); *(u32x2*)dst = o; }
;     S = S * gC + acc;
; }
	v_lshlrev_b32_e32 v86, 16, v66
	v_lshlrev_b32_e32 v87, 16, v67
	v_lshlrev_b32_e32 v88, 16, v68
	v_lshlrev_b32_e32 v89, 16, v69
	v_and_b32_e32 v66, 0xffff0000, v66
	v_and_b32_e32 v67, 0xffff0000, v67
	v_and_b32_e32 v68, 0xffff0000, v68
	v_and_b32_e32 v69, 0xffff0000, v69
	v_mul_f32_e32 v86, v248, v86
	v_mul_f32_e32 v87, v250, v87
	v_mul_f32_e32 v88, v210, v88
	v_mul_f32_e32 v89, v212, v89
	v_mul_f32_e32 v66, v249, v66
	v_mul_f32_e32 v67, v251, v67
	v_mul_f32_e32 v68, v211, v68
	v_mul_f32_e32 v69, v213, v69
	v_cvt_pk_bf16_f32 v86, v86, v66
	v_cvt_pk_bf16_f32 v87, v87, v67
	v_cvt_pk_bf16_f32 v88, v88, v68
	v_cvt_pk_bf16_f32 v89, v89, v69
	v_mfma_f32_16x16x32_bf16 v[40:43], v[44:47], v[118:121], v[40:43]
	s_nop 1
	v_mfma_f32_16x16x32_bf16 v[40:43], v[86:89], v[122:125], v[40:43]
	s_add_u32 s8, s20, 0x78000
	s_addc_u32 s9, s21, 0
	v_cvt_pk_bf16_f32 v48, v36, v37
	v_cvt_pk_bf16_f32 v49, v38, v39
	global_store_dwordx2 v172, v[48:49], s[8:9]
	s_nop 7
	v_pk_fma_f32 v[36:37], v[90:91], v[36:37], v[40:41] op_sel_hi:[0,1,1]
	v_pk_fma_f32 v[38:39], v[90:91], v[38:39], v[42:43] op_sel_hi:[0,1,1]
	s_add_u32 s8, s16, 0x70000
	s_addc_u32 s9, s17, 0
	s_add_u32 s10, s18, 0x70000
	s_addc_u32 s11, s19, 0
	global_load_dwordx4 v[54:57], v170, s[8:9]
	global_load_dwordx4 v[58:61], v170, s[8:9] offset:64
	global_load_dwordx4 v[62:65], v170, s[8:9] offset:128
	global_load_dwordx4 v[66:69], v170, s[8:9] offset:192
	global_load_dwordx4 v[110:113], v171, s[10:11]
	global_load_dwordx4 v[114:117], v171, s[10:11] offset:64
	global_load_dwordx4 v[118:121], v171, s[10:11] offset:128
	global_load_dwordx4 v[122:125], v171, s[10:11] offset:192
	s_waitcnt vmcnt(17)
	v_lshlrev_b32_e32 v44, 16, v2
	v_lshlrev_b32_e32 v45, 16, v3
	v_lshlrev_b32_e32 v46, 16, v4
	v_lshlrev_b32_e32 v47, 16, v5
	v_and_b32_e32 v2, 0xffff0000, v2
	v_and_b32_e32 v3, 0xffff0000, v3
	v_and_b32_e32 v4, 0xffff0000, v4
	v_and_b32_e32 v5, 0xffff0000, v5
	v_mul_f32_e32 v44, v224, v44
	v_mul_f32_e32 v45, v226, v45
	v_mul_f32_e32 v46, v228, v46
	v_mul_f32_e32 v47, v230, v47
	v_mul_f32_e32 v2, v225, v2
	v_mul_f32_e32 v3, v227, v3
	v_mul_f32_e32 v4, v229, v4
	v_mul_f32_e32 v5, v231, v5
	v_cvt_pk_bf16_f32 v44, v44, v2
	v_cvt_pk_bf16_f32 v45, v45, v3
	v_cvt_pk_bf16_f32 v46, v46, v4
	v_cvt_pk_bf16_f32 v47, v47, v5
	v_lshlrev_b32_e32 v86, 16, v6
	v_lshlrev_b32_e32 v87, 16, v7
	v_lshlrev_b32_e32 v88, 16, v8
	v_lshlrev_b32_e32 v89, 16, v9
	v_and_b32_e32 v6, 0xffff0000, v6
	v_and_b32_e32 v7, 0xffff0000, v7
	v_and_b32_e32 v8, 0xffff0000, v8
	v_and_b32_e32 v9, 0xffff0000, v9
	v_mul_f32_e32 v86, v232, v86
	v_mul_f32_e32 v87, v234, v87
	v_mul_f32_e32 v88, v236, v88
	v_mul_f32_e32 v89, v238, v89
	v_mul_f32_e32 v6, v233, v6
	v_mul_f32_e32 v7, v235, v7
	v_mul_f32_e32 v8, v237, v8
	v_mul_f32_e32 v9, v239, v9
	v_cvt_pk_bf16_f32 v86, v86, v6
	v_cvt_pk_bf16_f32 v87, v87, v7
	v_cvt_pk_bf16_f32 v88, v88, v8
	v_cvt_pk_bf16_f32 v89, v89, v9
	s_nop 0
	v_mfma_f32_16x16x32_bf16 v[40:43], v[44:47], v[70:73], 0
	v_lshlrev_b32_e32 v44, 16, v10
	v_lshlrev_b32_e32 v45, 16, v11
	v_lshlrev_b32_e32 v46, 16, v12
	v_lshlrev_b32_e32 v47, 16, v13
	v_and_b32_e32 v10, 0xffff0000, v10
	v_and_b32_e32 v11, 0xffff0000, v11
	v_and_b32_e32 v12, 0xffff0000, v12
	v_and_b32_e32 v13, 0xffff0000, v13
	v_mul_f32_e32 v44, v240, v44
	v_mul_f32_e32 v45, v242, v45
	v_mul_f32_e32 v46, v244, v46
	v_mul_f32_e32 v47, v246, v47
	v_mul_f32_e32 v10, v241, v10
	v_mul_f32_e32 v11, v243, v11
	v_mul_f32_e32 v12, v245, v12
	v_mul_f32_e32 v13, v247, v13
	v_cvt_pk_bf16_f32 v44, v44, v10
	v_cvt_pk_bf16_f32 v45, v45, v11
	v_cvt_pk_bf16_f32 v46, v46, v12
	v_cvt_pk_bf16_f32 v47, v47, v13
	v_mfma_f32_16x16x32_bf16 v[40:43], v[86:89], v[74:77], v[40:43]
	v_lshlrev_b32_e32 v86, 16, v14
	v_lshlrev_b32_e32 v87, 16, v15
	v_lshlrev_b32_e32 v88, 16, v16
	v_lshlrev_b32_e32 v89, 16, v17
	v_and_b32_e32 v14, 0xffff0000, v14
	v_and_b32_e32 v15, 0xffff0000, v15
	v_and_b32_e32 v16, 0xffff0000, v16
	v_and_b32_e32 v17, 0xffff0000, v17
	v_mul_f32_e32 v86, v248, v86
	v_mul_f32_e32 v87, v250, v87
	v_mul_f32_e32 v88, v210, v88
	v_mul_f32_e32 v89, v212, v89
	v_mul_f32_e32 v14, v249, v14
	v_mul_f32_e32 v15, v251, v15
	v_mul_f32_e32 v16, v211, v16
	v_mul_f32_e32 v17, v213, v17
	v_cvt_pk_bf16_f32 v86, v86, v14
	v_cvt_pk_bf16_f32 v87, v87, v15
	v_cvt_pk_bf16_f32 v88, v88, v16
	v_cvt_pk_bf16_f32 v89, v89, v17
	v_mfma_f32_16x16x32_bf16 v[40:43], v[44:47], v[78:81], v[40:43]
	s_nop 1
	v_mfma_f32_16x16x32_bf16 v[40:43], v[86:89], v[82:85], v[40:43]
	s_add_u32 s8, s20, 0x70000
	s_addc_u32 s9, s21, 0
	v_cvt_pk_bf16_f32 v48, v36, v37
	v_cvt_pk_bf16_f32 v49, v38, v39
	global_store_dwordx2 v172, v[48:49], s[8:9]
	s_nop 7
	v_pk_fma_f32 v[36:37], v[90:91], v[36:37], v[40:41] op_sel_hi:[0,1,1]
	v_pk_fma_f32 v[38:39], v[90:91], v[38:39], v[42:43] op_sel_hi:[0,1,1]
	s_add_u32 s8, s16, 0x68000
	s_addc_u32 s9, s17, 0
	s_add_u32 s10, s18, 0x68000
	s_addc_u32 s11, s19, 0
	global_load_dwordx4 v[2:5], v170, s[8:9]
	global_load_dwordx4 v[6:9], v170, s[8:9] offset:64
	global_load_dwordx4 v[10:13], v170, s[8:9] offset:128
	global_load_dwordx4 v[14:17], v170, s[8:9] offset:192
	global_load_dwordx4 v[70:73], v171, s[10:11]
	global_load_dwordx4 v[74:77], v171, s[10:11] offset:64
	global_load_dwordx4 v[78:81], v171, s[10:11] offset:128
	global_load_dwordx4 v[82:85], v171, s[10:11] offset:192
	s_waitcnt vmcnt(18)
; __device__ __forceinline__ unsigned cvt_pk_bf16(float lo, float hi) { unsigned r; asm("v_cvt_pk_bf16_f32 %0, %1, %2" : "=v"(r) : "v"(lo), "v"(hi)); return r; }
; __device__ __forceinline__ float bf2f(unsigned b) { return __uint_as_float(b << 16); }
; __device__ __forceinline__ void r1s_load(const bf16_t* __restrict__ kT, const bf16_t* __restrict__ vT, int bh, int cc, size_t koff, size_t voff, bf16x8 (&kk)[4], bf16x8 (&vv)[4]) {
;     const bf16_t* kt = kT + (size_t)(bh * 18 + cc) * 16384 + koff; const bf16_t* vt = vT + (size_t)(bh * 18 + cc) * 16384 + voff;
; #pragma unroll
;     for (int ks = 0; ks < 4; ++ks) { kk[ks] = *(const bf16x8*)(kt + 32 * ks); vv[ks] = *(const bf16x8*)(vt + 32 * ks); }
; }
; __device__ __forceinline__ void r1s_step(const bf16x8 (&kk)[4], const bf16x8 (&vv)[4], const float (&w)[4][8], f32x4& S, float gC, bool st, bf16_t* dst) {
;     f32x4 acc = {0.f, 0.f, 0.f, 0.f};
; #pragma unroll
;     for (int ks = 0; ks < 4; ++ks) {
;         float f[8];
; #pragma unroll
;         for (int e = 0; e < 8; ++e) f[e] = bf2f((unsigned)(unsigned short)kk[ks][e]) * w[ks][e];
;         u32x4 wf; wf.x = cvt_pk_bf16(f[0], f[1]); wf.y = cvt_pk_bf16(f[2], f[3]); wf.z = cvt_pk_bf16(f[4], f[5]); wf.w = cvt_pk_bf16(f[6], f[7]);
;         acc = __builtin_amdgcn_mfma_f32_16x16x32_bf16(__builtin_bit_cast(bf16x8, wf), vv[ks], acc, 0, 0, 0);
;     }
;     if (st) { u32x2 o; o.x = cvt_pk_bf16(S[0], S[1]); o.y = cvt_pk_bf16(S[2], S[3]); *(u32x2*)dst = o; }
;     S = S * gC + acc;
; }
	v_lshlrev_b32_e32 v44, 16, v20
	v_lshlrev_b32_e32 v45, 16, v21
	v_lshlrev_b32_e32 v46, 16, v22
	v_lshlrev_b32_e32 v47, 16, v23
	v_and_b32_e32 v20, 0xffff0000, v20
	v_and_b32_e32 v21, 0xffff0000, v21
	v_and_b32_e32 v22, 0xffff0000, v22
	v_and_b32_e32 v23, 0xffff0000, v23
	v_mul_f32_e32 v44, v224, v44
	v_mul_f32_e32 v45, v226, v45
	v_mul_f32_e32 v46, v228, v46
	v_mul_f32_e32 v47, v230, v47
	v_mul_f32_e32 v20, v225, v20
	v_mul_f32_e32 v21, v227, v21
	v_mul_f32_e32 v22, v229, v22
	v_mul_f32_e32 v23, v231, v23
	v_cvt_pk_bf16_f32 v44, v44, v20
	v_cvt_pk_bf16_f32 v45, v45, v21
	v_cvt_pk_bf16_f32 v46, v46, v22
	v_cvt_pk_bf16_f32 v47, v47, v23
	v_lshlrev_b32_e32 v86, 16, v24
	v_lshlrev_b32_e32 v87, 16, v25
	v_lshlrev_b32_e32 v88, 16, v26
	v_lshlrev_b32_e32 v89, 16, v27
	v_and_b32_e32 v24, 0xffff0000, v24
	v_and_b32_e32 v25, 0xffff0000, v25
	v_and_b32_e32 v26, 0xffff0000, v26
	v_and_b32_e32 v27, 0xffff0000, v27
	v_mul_f32_e32 v86, v232, v86
	v_mul_f32_e32 v87, v234, v87
	v_mul_f32_e32 v88, v236, v88
	v_mul_f32_e32 v89, v238, v89
	v_mul_f32_e32 v24, v233, v24
	v_mul_f32_e32 v25, v235, v25
	v_mul_f32_e32 v26, v237, v26
	v_mul_f32_e32 v27, v239, v27
	v_cvt_pk_bf16_f32 v86, v86, v24
	v_cvt_pk_bf16_f32 v87, v87, v25
	v_cvt_pk_bf16_f32 v88, v88, v26
	v_cvt_pk_bf16_f32 v89, v89, v27
	s_nop 0
	v_mfma_f32_16x16x32_bf16 v[40:43], v[44:47], v[94:97], 0
	v_lshlrev_b32_e32 v44, 16, v28
	v_lshlrev_b32_e32 v45, 16, v29
	v_lshlrev_b32_e32 v46, 16, v30
	v_lshlrev_b32_e32 v47, 16, v31
	v_and_b32_e32 v28, 0xffff0000, v28
	v_and_b32_e32 v29, 0xffff0000, v29
	v_and_b32_e32 v30, 0xffff0000, v30
	v_and_b32_e32 v31, 0xffff0000, v31
	v_mul_f32_e32 v44, v240, v44
	v_mul_f32_e32 v45, v242, v45
	v_mul_f32_e32 v46, v244, v46
	v_mul_f32_e32 v47, v246, v47
	v_mul_f32_e32 v28, v241, v28
	v_mul_f32_e32 v29, v243, v29
	v_mul_f32_e32 v30, v245, v30
	v_mul_f32_e32 v31, v247, v31
	v_cvt_pk_bf16_f32 v44, v44, v28
	v_cvt_pk_bf16_f32 v45, v45, v29
	v_cvt_pk_bf16_f32 v46, v46, v30
	v_cvt_pk_bf16_f32 v47, v47, v31
	v_mfma_f32_16x16x32_bf16 v[40:43], v[86:89], v[98:101], v[40:43]
	v_lshlrev_b32_e32 v86, 16, v32
	v_lshlrev_b32_e32 v87, 16, v33
	v_lshlrev_b32_e32 v88, 16, v34
	v_lshlrev_b32_e32 v89, 16, v35
	v_and_b32_e32 v32, 0xffff0000, v32
	v_and_b32_e32 v33, 0xffff0000, v33
	v_and_b32_e32 v34, 0xffff0000, v34
	v_and_b32_e32 v35, 0xffff0000, v35
	v_mul_f32_e32 v86, v248, v86
	v_mul_f32_e32 v87, v250, v87
	v_mul_f32_e32 v88, v210, v88
	v_mul_f32_e32 v89, v212, v89
	v_mul_f32_e32 v32, v249, v32
	v_mul_f32_e32 v33, v251, v33
	v_mul_f32_e32 v34, v211, v34
	v_mul_f32_e32 v35, v213, v35
	v_cvt_pk_bf16_f32 v86, v86, v32
	v_cvt_pk_bf16_f32 v87, v87, v33
	v_cvt_pk_bf16_f32 v88, v88, v34
	v_cvt_pk_bf16_f32 v89, v89, v35
	v_mfma_f32_16x16x32_bf16 v[40:43], v[44:47], v[102:105], v[40:43]
	s_nop 1
	v_mfma_f32_16x16x32_bf16 v[40:43], v[86:89], v[106:109], v[40:43]
	s_add_u32 s8, s20, 0x68000
	s_addc_u32 s9, s21, 0
	v_cvt_pk_bf16_f32 v48, v36, v37
	v_cvt_pk_bf16_f32 v49, v38, v39
	global_store_dwordx2 v172, v[48:49], s[8:9]
	s_nop 7
	v_pk_fma_f32 v[36:37], v[90:91], v[36:37], v[40:41] op_sel_hi:[0,1,1]
	v_pk_fma_f32 v[38:39], v[90:91], v[38:39], v[42:43] op_sel_hi:[0,1,1]
	s_add_u32 s8, s16, 0x60000
	s_addc_u32 s9, s17, 0
	s_add_u32 s10, s18, 0x60000
	s_addc_u32 s11, s19, 0
	global_load_dwordx4 v[20:23], v170, s[8:9]
	global_load_dwordx4 v[24:27], v170, s[8:9] offset:64
	global_load_dwordx4 v[28:31], v170, s[8:9] offset:128
	global_load_dwordx4 v[32:35], v170, s[8:9] offset:192
	global_load_dwordx4 v[94:97], v171, s[10:11]
	global_load_dwordx4 v[98:101], v171, s[10:11] offset:64
	global_load_dwordx4 v[102:105], v171, s[10:11] offset:128
	global_load_dwordx4 v[106:109], v171, s[10:11] offset:192
	s_waitcnt vmcnt(18)
	v_lshlrev_b32_e32 v44, 16, v54
	v_lshlrev_b32_e32 v45, 16, v55
	v_lshlrev_b32_e32 v46, 16, v56
	v_lshlrev_b32_e32 v47, 16, v57
	v_and_b32_e32 v54, 0xffff0000, v54
	v_and_b32_e32 v55, 0xffff0000, v55
	v_and_b32_e32 v56, 0xffff0000, v56
	v_and_b32_e32 v57, 0xffff0000, v57
	v_mul_f32_e32 v44, v224, v44
	v_mul_f32_e32 v45, v226, v45
	v_mul_f32_e32 v46, v228, v46
	v_mul_f32_e32 v47, v230, v47
	v_mul_f32_e32 v54, v225, v54
	v_mul_f32_e32 v55, v227, v55
	v_mul_f32_e32 v56, v229, v56
	v_mul_f32_e32 v57, v231, v57
	v_cvt_pk_bf16_f32 v44, v44, v54
	v_cvt_pk_bf16_f32 v45, v45, v55
	v_cvt_pk_bf16_f32 v46, v46, v56
	v_cvt_pk_bf16_f32 v47, v47, v57
	v_lshlrev_b32_e32 v86, 16, v58
	v_lshlrev_b32_e32 v87, 16, v59
	v_lshlrev_b32_e32 v88, 16, v60
	v_lshlrev_b32_e32 v89, 16, v61
	v_and_b32_e32 v58, 0xffff0000, v58
	v_and_b32_e32 v59, 0xffff0000, v59
	v_and_b32_e32 v60, 0xffff0000, v60
	v_and_b32_e32 v61, 0xffff0000, v61
	v_mul_f32_e32 v86, v232, v86
	v_mul_f32_e32 v87, v234, v87
	v_mul_f32_e32 v88, v236, v88
	v_mul_f32_e32 v89, v238, v89
	v_mul_f32_e32 v58, v233, v58
	v_mul_f32_e32 v59, v235, v59
	v_mul_f32_e32 v60, v237, v60
	v_mul_f32_e32 v61, v239, v61
	v_cvt_pk_bf16_f32 v86, v86, v58
	v_cvt_pk_bf16_f32 v87, v87, v59
	v_cvt_pk_bf16_f32 v88, v88, v60
	v_cvt_pk_bf16_f32 v89, v89, v61
	s_nop 0
	v_mfma_f32_16x16x32_bf16 v[40:43], v[44:47], v[110:113], 0
	v_lshlrev_b32_e32 v44, 16, v62
	v_lshlrev_b32_e32 v45, 16, v63
	v_lshlrev_b32_e32 v46, 16, v64
	v_lshlrev_b32_e32 v47, 16, v65
	v_and_b32_e32 v62, 0xffff0000, v62
	v_and_b32_e32 v63, 0xffff0000, v63
	v_and_b32_e32 v64, 0xffff0000, v64
	v_and_b32_e32 v65, 0xffff0000, v65
	v_mul_f32_e32 v44, v240, v44
	v_mul_f32_e32 v45, v242, v45
	v_mul_f32_e32 v46, v244, v46
	v_mul_f32_e32 v47, v246, v47
	v_mul_f32_e32 v62, v241, v62
	v_mul_f32_e32 v63, v243, v63
	v_mul_f32_e32 v64, v245, v64
	v_mul_f32_e32 v65, v247, v65
	v_cvt_pk_bf16_f32 v44, v44, v62
	v_cvt_pk_bf16_f32 v45, v45, v63
; __device__ __forceinline__ unsigned cvt_pk_bf16(float lo, float hi) { unsigned r; asm("v_cvt_pk_bf16_f32 %0, %1, %2" : "=v"(r) : "v"(lo), "v"(hi)); return r; }
; __device__ __forceinline__ float bf2f(unsigned b) { return __uint_as_float(b << 16); }
; __device__ __forceinline__ void r1s_load(const bf16_t* __restrict__ kT, const bf16_t* __restrict__ vT, int bh, int cc, size_t koff, size_t voff, bf16x8 (&kk)[4], bf16x8 (&vv)[4]) {
;     const bf16_t* kt = kT + (size_t)(bh * 18 + cc) * 16384 + koff; const bf16_t* vt = vT + (size_t)(bh * 18 + cc) * 16384 + voff;
; #pragma unroll
;     for (int ks = 0; ks < 4; ++ks) { kk[ks] = *(const bf16x8*)(kt + 32 * ks); vv[ks] = *(const bf16x8*)(vt + 32 * ks); }
; }
; __device__ __forceinline__ void r1s_step(const bf16x8 (&kk)[4], const bf16x8 (&vv)[4], const float (&w)[4][8], f32x4& S, float gC, bool st, bf16_t* dst) {
;     f32x4 acc = {0.f, 0.f, 0.f, 0.f};
; #pragma unroll
;     for (int ks = 0; ks < 4; ++ks) {
;         float f[8];
; #pragma unroll
;         for (int e = 0; e < 8; ++e) f[e] = bf2f((unsigned)(unsigned short)kk[ks][e]) * w[ks][e];
;         u32x4 wf; wf.x = cvt_pk_bf16(f[0], f[1]); wf.y = cvt_pk_bf16(f[2], f[3]); wf.z = cvt_pk_bf16(f[4], f[5]); wf.w = cvt_pk_bf16(f[6], f[7]);
;         acc = __builtin_amdgcn_mfma_f32_16x16x32_bf16(__builtin_bit_cast(bf16x8, wf), vv[ks], acc, 0, 0, 0);
;     }
;     if (st) { u32x2 o; o.x = cvt_pk_bf16(S[0], S[1]); o.y = cvt_pk_bf16(S[2], S[3]); *(u32x2*)dst = o; }
;     S = S * gC + acc;
; }
	v_cvt_pk_bf16_f32 v46, v46, v64
	v_cvt_pk_bf16_f32 v47, v47, v65
	v_mfma_f32_16x16x32_bf16 v[40:43], v[86:89], v[114:117], v[40:43]
	v_lshlrev_b32_e32 v86, 16, v66
	v_lshlrev_b32_e32 v87, 16, v67
	v_lshlrev_b32_e32 v88, 16, v68
	v_lshlrev_b32_e32 v89, 16, v69
	v_and_b32_e32 v66, 0xffff0000, v66
	v_and_b32_e32 v67, 0xffff0000, v67
	v_and_b32_e32 v68, 0xffff0000, v68
	v_and_b32_e32 v69, 0xffff0000, v69
	v_mul_f32_e32 v86, v248, v86
	v_mul_f32_e32 v87, v250, v87
	v_mul_f32_e32 v88, v210, v88
	v_mul_f32_e32 v89, v212, v89
	v_mul_f32_e32 v66, v249, v66
	v_mul_f32_e32 v67, v251, v67
	v_mul_f32_e32 v68, v211, v68
	v_mul_f32_e32 v69, v213, v69
	v_cvt_pk_bf16_f32 v86, v86, v66
	v_cvt_pk_bf16_f32 v87, v87, v67
	v_cvt_pk_bf16_f32 v88, v88, v68
	v_cvt_pk_bf16_f32 v89, v89, v69
	v_mfma_f32_16x16x32_bf16 v[40:43], v[44:47], v[118:121], v[40:43]
	s_nop 1
	v_mfma_f32_16x16x32_bf16 v[40:43], v[86:89], v[122:125], v[40:43]
	s_add_u32 s8, s20, 0x60000
	s_addc_u32 s9, s21, 0
	v_cvt_pk_bf16_f32 v48, v36, v37
	v_cvt_pk_bf16_f32 v49, v38, v39
	global_store_dwordx2 v172, v[48:49], s[8:9]
	s_nop 7
	v_pk_fma_f32 v[36:37], v[90:91], v[36:37], v[40:41] op_sel_hi:[0,1,1]
	v_pk_fma_f32 v[38:39], v[90:91], v[38:39], v[42:43] op_sel_hi:[0,1,1]
	s_add_u32 s8, s16, 0x58000
	s_addc_u32 s9, s17, 0
	s_add_u32 s10, s18, 0x58000
	s_addc_u32 s11, s19, 0
	global_load_dwordx4 v[54:57], v170, s[8:9]
	global_load_dwordx4 v[58:61], v170, s[8:9] offset:64
	global_load_dwordx4 v[62:65], v170, s[8:9] offset:128
	global_load_dwordx4 v[66:69], v170, s[8:9] offset:192
	global_load_dwordx4 v[110:113], v171, s[10:11]
	global_load_dwordx4 v[114:117], v171, s[10:11] offset:64
	global_load_dwordx4 v[118:121], v171, s[10:11] offset:128
	global_load_dwordx4 v[122:125], v171, s[10:11] offset:192
	s_waitcnt vmcnt(18)
	v_lshlrev_b32_e32 v44, 16, v2
	v_lshlrev_b32_e32 v45, 16, v3
	v_lshlrev_b32_e32 v46, 16, v4
	v_lshlrev_b32_e32 v47, 16, v5
	v_and_b32_e32 v2, 0xffff0000, v2
	v_and_b32_e32 v3, 0xffff0000, v3
	v_and_b32_e32 v4, 0xffff0000, v4
	v_and_b32_e32 v5, 0xffff0000, v5
	v_mul_f32_e32 v44, v224, v44
	v_mul_f32_e32 v45, v226, v45
	v_mul_f32_e32 v46, v228, v46
	v_mul_f32_e32 v47, v230, v47
	v_mul_f32_e32 v2, v225, v2
	v_mul_f32_e32 v3, v227, v3
	v_mul_f32_e32 v4, v229, v4
	v_mul_f32_e32 v5, v231, v5
	v_cvt_pk_bf16_f32 v44, v44, v2
	v_cvt_pk_bf16_f32 v45, v45, v3
	v_cvt_pk_bf16_f32 v46, v46, v4
	v_cvt_pk_bf16_f32 v47, v47, v5
	v_lshlrev_b32_e32 v86, 16, v6
	v_lshlrev_b32_e32 v87, 16, v7
	v_lshlrev_b32_e32 v88, 16, v8
	v_lshlrev_b32_e32 v89, 16, v9
	v_and_b32_e32 v6, 0xffff0000, v6
	v_and_b32_e32 v7, 0xffff0000, v7
	v_and_b32_e32 v8, 0xffff0000, v8
	v_and_b32_e32 v9, 0xffff0000, v9
	v_mul_f32_e32 v86, v232, v86
	v_mul_f32_e32 v87, v234, v87
	v_mul_f32_e32 v88, v236, v88
	v_mul_f32_e32 v89, v238, v89
	v_mul_f32_e32 v6, v233, v6
	v_mul_f32_e32 v7, v235, v7
	v_mul_f32_e32 v8, v237, v8
	v_mul_f32_e32 v9, v239, v9
	v_cvt_pk_bf16_f32 v86, v86, v6
	v_cvt_pk_bf16_f32 v87, v87, v7
	v_cvt_pk_bf16_f32 v88, v88, v8
	v_cvt_pk_bf16_f32 v89, v89, v9
	s_nop 0
	v_mfma_f32_16x16x32_bf16 v[40:43], v[44:47], v[70:73], 0
	v_lshlrev_b32_e32 v44, 16, v10
	v_lshlrev_b32_e32 v45, 16, v11
	v_lshlrev_b32_e32 v46, 16, v12
	v_lshlrev_b32_e32 v47, 16, v13
	v_and_b32_e32 v10, 0xffff0000, v10
	v_and_b32_e32 v11, 0xffff0000, v11
	v_and_b32_e32 v12, 0xffff0000, v12
	v_and_b32_e32 v13, 0xffff0000, v13
	v_mul_f32_e32 v44, v240, v44
	v_mul_f32_e32 v45, v242, v45
	v_mul_f32_e32 v46, v244, v46
	v_mul_f32_e32 v47, v246, v47
	v_mul_f32_e32 v10, v241, v10
	v_mul_f32_e32 v11, v243, v11
	v_mul_f32_e32 v12, v245, v12
	v_mul_f32_e32 v13, v247, v13
	v_cvt_pk_bf16_f32 v44, v44, v10
	v_cvt_pk_bf16_f32 v45, v45, v11
	v_cvt_pk_bf16_f32 v46, v46, v12
	v_cvt_pk_bf16_f32 v47, v47, v13
	v_mfma_f32_16x16x32_bf16 v[40:43], v[86:89], v[74:77], v[40:43]
	v_lshlrev_b32_e32 v86, 16, v14
	v_lshlrev_b32_e32 v87, 16, v15
	v_lshlrev_b32_e32 v88, 16, v16
	v_lshlrev_b32_e32 v89, 16, v17
	v_and_b32_e32 v14, 0xffff0000, v14
	v_and_b32_e32 v15, 0xffff0000, v15
	v_and_b32_e32 v16, 0xffff0000, v16
	v_and_b32_e32 v17, 0xffff0000, v17
	v_mul_f32_e32 v86, v248, v86
	v_mul_f32_e32 v87, v250, v87
	v_mul_f32_e32 v88, v210, v88
	v_mul_f32_e32 v89, v212, v89
	v_mul_f32_e32 v14, v249, v14
	v_mul_f32_e32 v15, v251, v15
	v_mul_f32_e32 v16, v211, v16
	v_mul_f32_e32 v17, v213, v17
	v_cvt_pk_bf16_f32 v86, v86, v14
	v_cvt_pk_bf16_f32 v87, v87, v15
	v_cvt_pk_bf16_f32 v88, v88, v16
	v_cvt_pk_bf16_f32 v89, v89, v17
	v_mfma_f32_16x16x32_bf16 v[40:43], v[44:47], v[78:81], v[40:43]
	s_nop 1
	v_mfma_f32_16x16x32_bf16 v[40:43], v[86:89], v[82:85], v[40:43]
	s_add_u32 s8, s20, 0x58000
	s_addc_u32 s9, s21, 0
	v_cvt_pk_bf16_f32 v48, v36, v37
	v_cvt_pk_bf16_f32 v49, v38, v39
	global_store_dwordx2 v172, v[48:49], s[8:9]
	s_nop 7
	v_pk_fma_f32 v[36:37], v[90:91], v[36:37], v[40:41] op_sel_hi:[0,1,1]
	v_pk_fma_f32 v[38:39], v[90:91], v[38:39], v[42:43] op_sel_hi:[0,1,1]
	s_add_u32 s8, s16, 0x50000
	s_addc_u32 s9, s17, 0
	s_add_u32 s10, s18, 0x50000
	s_addc_u32 s11, s19, 0
	global_load_dwordx4 v[2:5], v170, s[8:9]
	global_load_dwordx4 v[6:9], v170, s[8:9] offset:64
	global_load_dwordx4 v[10:13], v170, s[8:9] offset:128
	global_load_dwordx4 v[14:17], v170, s[8:9] offset:192
	global_load_dwordx4 v[70:73], v171, s[10:11]
	global_load_dwordx4 v[74:77], v171, s[10:11] offset:64
	global_load_dwordx4 v[78:81], v171, s[10:11] offset:128
	global_load_dwordx4 v[82:85], v171, s[10:11] offset:192
	s_waitcnt vmcnt(18)
; __device__ __forceinline__ unsigned cvt_pk_bf16(float lo, float hi) { unsigned r; asm("v_cvt_pk_bf16_f32 %0, %1, %2" : "=v"(r) : "v"(lo), "v"(hi)); return r; }
; __device__ __forceinline__ float bf2f(unsigned b) { return __uint_as_float(b << 16); }
; __device__ __forceinline__ void r1s_load(const bf16_t* __restrict__ kT, const bf16_t* __restrict__ vT, int bh, int cc, size_t koff, size_t voff, bf16x8 (&kk)[4], bf16x8 (&vv)[4]) {
;     const bf16_t* kt = kT + (size_t)(bh * 18 + cc) * 16384 + koff; const bf16_t* vt = vT + (size_t)(bh * 18 + cc) * 16384 + voff;
; #pragma unroll
;     for (int ks = 0; ks < 4; ++ks) { kk[ks] = *(const bf16x8*)(kt + 32 * ks); vv[ks] = *(const bf16x8*)(vt + 32 * ks); }
; }
; __device__ __forceinline__ void r1s_step(const bf16x8 (&kk)[4], const bf16x8 (&vv)[4], const float (&w)[4][8], f32x4& S, float gC, bool st, bf16_t* dst) {
;     f32x4 acc = {0.f, 0.f, 0.f, 0.f};
; #pragma unroll
;     for (int ks = 0; ks < 4; ++ks) {
;         float f[8];
; #pragma unroll
;         for (int e = 0; e < 8; ++e) f[e] = bf2f((unsigned)(unsigned short)kk[ks][e]) * w[ks][e];
;         u32x4 wf; wf.x = cvt_pk_bf16(f[0], f[1]); wf.y = cvt_pk_bf16(f[2], f[3]); wf.z = cvt_pk_bf16(f[4], f[5]); wf.w = cvt_pk_bf16(f[6], f[7]);
;         acc = __builtin_amdgcn_mfma_f32_16x16x32_bf16(__builtin_bit_cast(bf16x8, wf), vv[ks], acc, 0, 0, 0);
;     }
;     if (st) { u32x2 o; o.x = cvt_pk_bf16(S[0], S[1]); o.y = cvt_pk_bf16(S[2], S[3]); *(u32x2*)dst = o; }
;     S = S * gC + acc;
; }
	v_lshlrev_b32_e32 v44, 16, v20
	v_lshlrev_b32_e32 v45, 16, v21
	v_lshlrev_b32_e32 v46, 16, v22
	v_lshlrev_b32_e32 v47, 16, v23
	v_and_b32_e32 v20, 0xffff0000, v20
	v_and_b32_e32 v21, 0xffff0000, v21
	v_and_b32_e32 v22, 0xffff0000, v22
	v_and_b32_e32 v23, 0xffff0000, v23
	v_mul_f32_e32 v44, v224, v44
	v_mul_f32_e32 v45, v226, v45
	v_mul_f32_e32 v46, v228, v46
	v_mul_f32_e32 v47, v230, v47
	v_mul_f32_e32 v20, v225, v20
	v_mul_f32_e32 v21, v227, v21
	v_mul_f32_e32 v22, v229, v22
	v_mul_f32_e32 v23, v231, v23
	v_cvt_pk_bf16_f32 v44, v44, v20
	v_cvt_pk_bf16_f32 v45, v45, v21
	v_cvt_pk_bf16_f32 v46, v46, v22
	v_cvt_pk_bf16_f32 v47, v47, v23
	v_lshlrev_b32_e32 v86, 16, v24
	v_lshlrev_b32_e32 v87, 16, v25
	v_lshlrev_b32_e32 v88, 16, v26
	v_lshlrev_b32_e32 v89, 16, v27
	v_and_b32_e32 v24, 0xffff0000, v24
	v_and_b32_e32 v25, 0xffff0000, v25
	v_and_b32_e32 v26, 0xffff0000, v26
	v_and_b32_e32 v27, 0xffff0000, v27
	v_mul_f32_e32 v86, v232, v86
	v_mul_f32_e32 v87, v234, v87
	v_mul_f32_e32 v88, v236, v88
	v_mul_f32_e32 v89, v238, v89
	v_mul_f32_e32 v24, v233, v24
	v_mul_f32_e32 v25, v235, v25
	v_mul_f32_e32 v26, v237, v26
	v_mul_f32_e32 v27, v239, v27
	v_cvt_pk_bf16_f32 v86, v86, v24
	v_cvt_pk_bf16_f32 v87, v87, v25
	v_cvt_pk_bf16_f32 v88, v88, v26
	v_cvt_pk_bf16_f32 v89, v89, v27
	s_nop 0
	v_mfma_f32_16x16x32_bf16 v[40:43], v[44:47], v[94:97], 0
	v_lshlrev_b32_e32 v44, 16, v28
	v_lshlrev_b32_e32 v45, 16, v29
	v_lshlrev_b32_e32 v46, 16, v30
	v_lshlrev_b32_e32 v47, 16, v31
	v_and_b32_e32 v28, 0xffff0000, v28
	v_and_b32_e32 v29, 0xffff0000, v29
	v_and_b32_e32 v30, 0xffff0000, v30
	v_and_b32_e32 v31, 0xffff0000, v31
	v_mul_f32_e32 v44, v240, v44
	v_mul_f32_e32 v45, v242, v45
	v_mul_f32_e32 v46, v244, v46
	v_mul_f32_e32 v47, v246, v47
	v_mul_f32_e32 v28, v241, v28
	v_mul_f32_e32 v29, v243, v29
	v_mul_f32_e32 v30, v245, v30
	v_mul_f32_e32 v31, v247, v31
	v_cvt_pk_bf16_f32 v44, v44, v28
	v_cvt_pk_bf16_f32 v45, v45, v29
	v_cvt_pk_bf16_f32 v46, v46, v30
	v_cvt_pk_bf16_f32 v47, v47, v31
	v_mfma_f32_16x16x32_bf16 v[40:43], v[86:89], v[98:101], v[40:43]
	v_lshlrev_b32_e32 v86, 16, v32
	v_lshlrev_b32_e32 v87, 16, v33
	v_lshlrev_b32_e32 v88, 16, v34
	v_lshlrev_b32_e32 v89, 16, v35
	v_and_b32_e32 v32, 0xffff0000, v32
	v_and_b32_e32 v33, 0xffff0000, v33
	v_and_b32_e32 v34, 0xffff0000, v34
	v_and_b32_e32 v35, 0xffff0000, v35
	v_mul_f32_e32 v86, v248, v86
	v_mul_f32_e32 v87, v250, v87
	v_mul_f32_e32 v88, v210, v88
	v_mul_f32_e32 v89, v212, v89
	v_mul_f32_e32 v32, v249, v32
	v_mul_f32_e32 v33, v251, v33
	v_mul_f32_e32 v34, v211, v34
	v_mul_f32_e32 v35, v213, v35
	v_cvt_pk_bf16_f32 v86, v86, v32
	v_cvt_pk_bf16_f32 v87, v87, v33
	v_cvt_pk_bf16_f32 v88, v88, v34
	v_cvt_pk_bf16_f32 v89, v89, v35
	v_mfma_f32_16x16x32_bf16 v[40:43], v[44:47], v[102:105], v[40:43]
	s_nop 1
	v_mfma_f32_16x16x32_bf16 v[40:43], v[86:89], v[106:109], v[40:43]
	s_add_u32 s8, s20, 0x50000
	s_addc_u32 s9, s21, 0
	v_cvt_pk_bf16_f32 v48, v36, v37
	v_cvt_pk_bf16_f32 v49, v38, v39
	global_store_dwordx2 v172, v[48:49], s[8:9]
	s_nop 7
	v_pk_fma_f32 v[36:37], v[90:91], v[36:37], v[40:41] op_sel_hi:[0,1,1]
	v_pk_fma_f32 v[38:39], v[90:91], v[38:39], v[42:43] op_sel_hi:[0,1,1]
	s_add_u32 s8, s16, 0x48000
	s_addc_u32 s9, s17, 0
	s_add_u32 s10, s18, 0x48000
	s_addc_u32 s11, s19, 0
	global_load_dwordx4 v[20:23], v170, s[8:9]
	global_load_dwordx4 v[24:27], v170, s[8:9] offset:64
	global_load_dwordx4 v[28:31], v170, s[8:9] offset:128
	global_load_dwordx4 v[32:35], v170, s[8:9] offset:192
	global_load_dwordx4 v[94:97], v171, s[10:11]
	global_load_dwordx4 v[98:101], v171, s[10:11] offset:64
	global_load_dwordx4 v[102:105], v171, s[10:11] offset:128
	global_load_dwordx4 v[106:109], v171, s[10:11] offset:192
	s_waitcnt vmcnt(18)
	v_lshlrev_b32_e32 v44, 16, v54
	v_lshlrev_b32_e32 v45, 16, v55
	v_lshlrev_b32_e32 v46, 16, v56
	v_lshlrev_b32_e32 v47, 16, v57
	v_and_b32_e32 v54, 0xffff0000, v54
	v_and_b32_e32 v55, 0xffff0000, v55
	v_and_b32_e32 v56, 0xffff0000, v56
	v_and_b32_e32 v57, 0xffff0000, v57
	v_mul_f32_e32 v44, v224, v44
	v_mul_f32_e32 v45, v226, v45
	v_mul_f32_e32 v46, v228, v46
	v_mul_f32_e32 v47, v230, v47
	v_mul_f32_e32 v54, v225, v54
	v_mul_f32_e32 v55, v227, v55
	v_mul_f32_e32 v56, v229, v56
	v_mul_f32_e32 v57, v231, v57
	v_cvt_pk_bf16_f32 v44, v44, v54
	v_cvt_pk_bf16_f32 v45, v45, v55
	v_cvt_pk_bf16_f32 v46, v46, v56
	v_cvt_pk_bf16_f32 v47, v47, v57
	v_lshlrev_b32_e32 v86, 16, v58
	v_lshlrev_b32_e32 v87, 16, v59
	v_lshlrev_b32_e32 v88, 16, v60
	v_lshlrev_b32_e32 v89, 16, v61
	v_and_b32_e32 v58, 0xffff0000, v58
	v_and_b32_e32 v59, 0xffff0000, v59
	v_and_b32_e32 v60, 0xffff0000, v60
	v_and_b32_e32 v61, 0xffff0000, v61
	v_mul_f32_e32 v86, v232, v86
	v_mul_f32_e32 v87, v234, v87
	v_mul_f32_e32 v88, v236, v88
	v_mul_f32_e32 v89, v238, v89
	v_mul_f32_e32 v58, v233, v58
	v_mul_f32_e32 v59, v235, v59
	v_mul_f32_e32 v60, v237, v60
	v_mul_f32_e32 v61, v239, v61
	v_cvt_pk_bf16_f32 v86, v86, v58
	v_cvt_pk_bf16_f32 v87, v87, v59
	v_cvt_pk_bf16_f32 v88, v88, v60
	v_cvt_pk_bf16_f32 v89, v89, v61
	s_nop 0
	v_mfma_f32_16x16x32_bf16 v[40:43], v[44:47], v[110:113], 0
	v_lshlrev_b32_e32 v44, 16, v62
	v_lshlrev_b32_e32 v45, 16, v63
	v_lshlrev_b32_e32 v46, 16, v64
	v_lshlrev_b32_e32 v47, 16, v65
	v_and_b32_e32 v62, 0xffff0000, v62
	v_and_b32_e32 v63, 0xffff0000, v63
	v_and_b32_e32 v64, 0xffff0000, v64
	v_and_b32_e32 v65, 0xffff0000, v65
	v_mul_f32_e32 v44, v240, v44
	v_mul_f32_e32 v45, v242, v45
	v_mul_f32_e32 v46, v244, v46
	v_mul_f32_e32 v47, v246, v47
	v_mul_f32_e32 v62, v241, v62
	v_mul_f32_e32 v63, v243, v63
	v_mul_f32_e32 v64, v245, v64
	v_mul_f32_e32 v65, v247, v65
	v_cvt_pk_bf16_f32 v44, v44, v62
	v_cvt_pk_bf16_f32 v45, v45, v63
; __device__ __forceinline__ unsigned cvt_pk_bf16(float lo, float hi) { unsigned r; asm("v_cvt_pk_bf16_f32 %0, %1, %2" : "=v"(r) : "v"(lo), "v"(hi)); return r; }
; __device__ __forceinline__ float bf2f(unsigned b) { return __uint_as_float(b << 16); }
; __device__ __forceinline__ void r1s_load(const bf16_t* __restrict__ kT, const bf16_t* __restrict__ vT, int bh, int cc, size_t koff, size_t voff, bf16x8 (&kk)[4], bf16x8 (&vv)[4]) {
;     const bf16_t* kt = kT + (size_t)(bh * 18 + cc) * 16384 + koff; const bf16_t* vt = vT + (size_t)(bh * 18 + cc) * 16384 + voff;
; #pragma unroll
;     for (int ks = 0; ks < 4; ++ks) { kk[ks] = *(const bf16x8*)(kt + 32 * ks); vv[ks] = *(const bf16x8*)(vt + 32 * ks); }
; }
; __device__ __forceinline__ void r1s_step(const bf16x8 (&kk)[4], const bf16x8 (&vv)[4], const float (&w)[4][8], f32x4& S, float gC, bool st, bf16_t* dst) {
;     f32x4 acc = {0.f, 0.f, 0.f, 0.f};
; #pragma unroll
;     for (int ks = 0; ks < 4; ++ks) {
;         float f[8];
; #pragma unroll
;         for (int e = 0; e < 8; ++e) f[e] = bf2f((unsigned)(unsigned short)kk[ks][e]) * w[ks][e];
;         u32x4 wf; wf.x = cvt_pk_bf16(f[0], f[1]); wf.y = cvt_pk_bf16(f[2], f[3]); wf.z = cvt_pk_bf16(f[4], f[5]); wf.w = cvt_pk_bf16(f[6], f[7]);
;         acc = __builtin_amdgcn_mfma_f32_16x16x32_bf16(__builtin_bit_cast(bf16x8, wf), vv[ks], acc, 0, 0, 0);
;     }
;     if (st) { u32x2 o; o.x = cvt_pk_bf16(S[0], S[1]); o.y = cvt_pk_bf16(S[2], S[3]); *(u32x2*)dst = o; }
;     S = S * gC + acc;
; }
	v_cvt_pk_bf16_f32 v46, v46, v64
	v_cvt_pk_bf16_f32 v47, v47, v65
	v_mfma_f32_16x16x32_bf16 v[40:43], v[86:89], v[114:117], v[40:43]
	v_lshlrev_b32_e32 v86, 16, v66
	v_lshlrev_b32_e32 v87, 16, v67
	v_lshlrev_b32_e32 v88, 16, v68
	v_lshlrev_b32_e32 v89, 16, v69
	v_and_b32_e32 v66, 0xffff0000, v66
	v_and_b32_e32 v67, 0xffff0000, v67
	v_and_b32_e32 v68, 0xffff0000, v68
	v_and_b32_e32 v69, 0xffff0000, v69
	v_mul_f32_e32 v86, v248, v86
	v_mul_f32_e32 v87, v250, v87
	v_mul_f32_e32 v88, v210, v88
	v_mul_f32_e32 v89, v212, v89
	v_mul_f32_e32 v66, v249, v66
	v_mul_f32_e32 v67, v251, v67
	v_mul_f32_e32 v68, v211, v68
	v_mul_f32_e32 v69, v213, v69
	v_cvt_pk_bf16_f32 v86, v86, v66
	v_cvt_pk_bf16_f32 v87, v87, v67
	v_cvt_pk_bf16_f32 v88, v88, v68
	v_cvt_pk_bf16_f32 v89, v89, v69
	v_mfma_f32_16x16x32_bf16 v[40:43], v[44:47], v[118:121], v[40:43]
	s_nop 1
	v_mfma_f32_16x16x32_bf16 v[40:43], v[86:89], v[122:125], v[40:43]
	s_add_u32 s8, s20, 0x48000
	s_addc_u32 s9, s21, 0
	v_cvt_pk_bf16_f32 v48, v36, v37
	v_cvt_pk_bf16_f32 v49, v38, v39
	global_store_dwordx2 v172, v[48:49], s[8:9]
	s_nop 7
	v_pk_fma_f32 v[36:37], v[90:91], v[36:37], v[40:41] op_sel_hi:[0,1,1]
	v_pk_fma_f32 v[38:39], v[90:91], v[38:39], v[42:43] op_sel_hi:[0,1,1]
	s_add_u32 s8, s16, 0x40000
	s_addc_u32 s9, s17, 0
	s_add_u32 s10, s18, 0x40000
	s_addc_u32 s11, s19, 0
	global_load_dwordx4 v[54:57], v170, s[8:9]
	global_load_dwordx4 v[58:61], v170, s[8:9] offset:64
	global_load_dwordx4 v[62:65], v170, s[8:9] offset:128
	global_load_dwordx4 v[66:69], v170, s[8:9] offset:192
	global_load_dwordx4 v[110:113], v171, s[10:11]
	global_load_dwordx4 v[114:117], v171, s[10:11] offset:64
	global_load_dwordx4 v[118:121], v171, s[10:11] offset:128
	global_load_dwordx4 v[122:125], v171, s[10:11] offset:192
	s_waitcnt vmcnt(18)
	v_lshlrev_b32_e32 v44, 16, v2
	v_lshlrev_b32_e32 v45, 16, v3
	v_lshlrev_b32_e32 v46, 16, v4
	v_lshlrev_b32_e32 v47, 16, v5
	v_and_b32_e32 v2, 0xffff0000, v2
	v_and_b32_e32 v3, 0xffff0000, v3
	v_and_b32_e32 v4, 0xffff0000, v4
	v_and_b32_e32 v5, 0xffff0000, v5
	v_mul_f32_e32 v44, v224, v44
	v_mul_f32_e32 v45, v226, v45
	v_mul_f32_e32 v46, v228, v46
	v_mul_f32_e32 v47, v230, v47
	v_mul_f32_e32 v2, v225, v2
	v_mul_f32_e32 v3, v227, v3
	v_mul_f32_e32 v4, v229, v4
	v_mul_f32_e32 v5, v231, v5
	v_cvt_pk_bf16_f32 v44, v44, v2
	v_cvt_pk_bf16_f32 v45, v45, v3
	v_cvt_pk_bf16_f32 v46, v46, v4
	v_cvt_pk_bf16_f32 v47, v47, v5
	v_lshlrev_b32_e32 v86, 16, v6
	v_lshlrev_b32_e32 v87, 16, v7
	v_lshlrev_b32_e32 v88, 16, v8
	v_lshlrev_b32_e32 v89, 16, v9
	v_and_b32_e32 v6, 0xffff0000, v6
	v_and_b32_e32 v7, 0xffff0000, v7
	v_and_b32_e32 v8, 0xffff0000, v8
	v_and_b32_e32 v9, 0xffff0000, v9
	v_mul_f32_e32 v86, v232, v86
	v_mul_f32_e32 v87, v234, v87
	v_mul_f32_e32 v88, v236, v88
	v_mul_f32_e32 v89, v238, v89
	v_mul_f32_e32 v6, v233, v6
	v_mul_f32_e32 v7, v235, v7
	v_mul_f32_e32 v8, v237, v8
	v_mul_f32_e32 v9, v239, v9
	v_cvt_pk_bf16_f32 v86, v86, v6
	v_cvt_pk_bf16_f32 v87, v87, v7
	v_cvt_pk_bf16_f32 v88, v88, v8
	v_cvt_pk_bf16_f32 v89, v89, v9
	s_nop 0
	v_mfma_f32_16x16x32_bf16 v[40:43], v[44:47], v[70:73], 0
	v_lshlrev_b32_e32 v44, 16, v10
	v_lshlrev_b32_e32 v45, 16, v11
	v_lshlrev_b32_e32 v46, 16, v12
	v_lshlrev_b32_e32 v47, 16, v13
	v_and_b32_e32 v10, 0xffff0000, v10
	v_and_b32_e32 v11, 0xffff0000, v11
	v_and_b32_e32 v12, 0xffff0000, v12
	v_and_b32_e32 v13, 0xffff0000, v13
	v_mul_f32_e32 v44, v240, v44
	v_mul_f32_e32 v45, v242, v45
	v_mul_f32_e32 v46, v244, v46
	v_mul_f32_e32 v47, v246, v47
	v_mul_f32_e32 v10, v241, v10
	v_mul_f32_e32 v11, v243, v11
	v_mul_f32_e32 v12, v245, v12
	v_mul_f32_e32 v13, v247, v13
	v_cvt_pk_bf16_f32 v44, v44, v10
	v_cvt_pk_bf16_f32 v45, v45, v11
	v_cvt_pk_bf16_f32 v46, v46, v12
	v_cvt_pk_bf16_f32 v47, v47, v13
	v_mfma_f32_16x16x32_bf16 v[40:43], v[86:89], v[74:77], v[40:43]
	v_lshlrev_b32_e32 v86, 16, v14
	v_lshlrev_b32_e32 v87, 16, v15
	v_lshlrev_b32_e32 v88, 16, v16
	v_lshlrev_b32_e32 v89, 16, v17
	v_and_b32_e32 v14, 0xffff0000, v14
	v_and_b32_e32 v15, 0xffff0000, v15
	v_and_b32_e32 v16, 0xffff0000, v16
	v_and_b32_e32 v17, 0xffff0000, v17
	v_mul_f32_e32 v86, v248, v86
	v_mul_f32_e32 v87, v250, v87
	v_mul_f32_e32 v88, v210, v88
	v_mul_f32_e32 v89, v212, v89
	v_mul_f32_e32 v14, v249, v14
	v_mul_f32_e32 v15, v251, v15
	v_mul_f32_e32 v16, v211, v16
	v_mul_f32_e32 v17, v213, v17
	v_cvt_pk_bf16_f32 v86, v86, v14
	v_cvt_pk_bf16_f32 v87, v87, v15
	v_cvt_pk_bf16_f32 v88, v88, v16
	v_cvt_pk_bf16_f32 v89, v89, v17
	v_mfma_f32_16x16x32_bf16 v[40:43], v[44:47], v[78:81], v[40:43]
	s_nop 1
	v_mfma_f32_16x16x32_bf16 v[40:43], v[86:89], v[82:85], v[40:43]
	s_add_u32 s8, s20, 0x40000
	s_addc_u32 s9, s21, 0
	v_cvt_pk_bf16_f32 v48, v36, v37
	v_cvt_pk_bf16_f32 v49, v38, v39
	global_store_dwordx2 v172, v[48:49], s[8:9]
	s_nop 7
	v_pk_fma_f32 v[36:37], v[90:91], v[36:37], v[40:41] op_sel_hi:[0,1,1]
	v_pk_fma_f32 v[38:39], v[90:91], v[38:39], v[42:43] op_sel_hi:[0,1,1]
	s_add_u32 s8, s16, 0x38000
	s_addc_u32 s9, s17, 0
	s_add_u32 s10, s18, 0x38000
	s_addc_u32 s11, s19, 0
	global_load_dwordx4 v[2:5], v170, s[8:9]
	global_load_dwordx4 v[6:9], v170, s[8:9] offset:64
	global_load_dwordx4 v[10:13], v170, s[8:9] offset:128
	global_load_dwordx4 v[14:17], v170, s[8:9] offset:192
	global_load_dwordx4 v[70:73], v171, s[10:11]
	global_load_dwordx4 v[74:77], v171, s[10:11] offset:64
	global_load_dwordx4 v[78:81], v171, s[10:11] offset:128
	global_load_dwordx4 v[82:85], v171, s[10:11] offset:192
	s_waitcnt vmcnt(18)
; __device__ __forceinline__ unsigned cvt_pk_bf16(float lo, float hi) { unsigned r; asm("v_cvt_pk_bf16_f32 %0, %1, %2" : "=v"(r) : "v"(lo), "v"(hi)); return r; }
; __device__ __forceinline__ float bf2f(unsigned b) { return __uint_as_float(b << 16); }
; __device__ __forceinline__ void r1s_load(const bf16_t* __restrict__ kT, const bf16_t* __restrict__ vT, int bh, int cc, size_t koff, size_t voff, bf16x8 (&kk)[4], bf16x8 (&vv)[4]) {
;     const bf16_t* kt = kT + (size_t)(bh * 18 + cc) * 16384 + koff; const bf16_t* vt = vT + (size_t)(bh * 18 + cc) * 16384 + voff;
; #pragma unroll
;     for (int ks = 0; ks < 4; ++ks) { kk[ks] = *(const bf16x8*)(kt + 32 * ks); vv[ks] = *(const bf16x8*)(vt + 32 * ks); }
; }
; __device__ __forceinline__ void r1s_step(const bf16x8 (&kk)[4], const bf16x8 (&vv)[4], const float (&w)[4][8], f32x4& S, float gC, bool st, bf16_t* dst) {
;     f32x4 acc = {0.f, 0.f, 0.f, 0.f};
; #pragma unroll
;     for (int ks = 0; ks < 4; ++ks) {
;         float f[8];
; #pragma unroll
;         for (int e = 0; e < 8; ++e) f[e] = bf2f((unsigned)(unsigned short)kk[ks][e]) * w[ks][e];
;         u32x4 wf; wf.x = cvt_pk_bf16(f[0], f[1]); wf.y = cvt_pk_bf16(f[2], f[3]); wf.z = cvt_pk_bf16(f[4], f[5]); wf.w = cvt_pk_bf16(f[6], f[7]);
;         acc = __builtin_amdgcn_mfma_f32_16x16x32_bf16(__builtin_bit_cast(bf16x8, wf), vv[ks], acc, 0, 0, 0);
;     }
;     if (st) { u32x2 o; o.x = cvt_pk_bf16(S[0], S[1]); o.y = cvt_pk_bf16(S[2], S[3]); *(u32x2*)dst = o; }
;     S = S * gC + acc;
; }
	v_lshlrev_b32_e32 v44, 16, v20
	v_lshlrev_b32_e32 v45, 16, v21
	v_lshlrev_b32_e32 v46, 16, v22
	v_lshlrev_b32_e32 v47, 16, v23
	v_and_b32_e32 v20, 0xffff0000, v20
	v_and_b32_e32 v21, 0xffff0000, v21
	v_and_b32_e32 v22, 0xffff0000, v22
	v_and_b32_e32 v23, 0xffff0000, v23
	v_mul_f32_e32 v44, v224, v44
	v_mul_f32_e32 v45, v226, v45
	v_mul_f32_e32 v46, v228, v46
	v_mul_f32_e32 v47, v230, v47
	v_mul_f32_e32 v20, v225, v20
	v_mul_f32_e32 v21, v227, v21
	v_mul_f32_e32 v22, v229, v22
	v_mul_f32_e32 v23, v231, v23
	v_cvt_pk_bf16_f32 v44, v44, v20
	v_cvt_pk_bf16_f32 v45, v45, v21
	v_cvt_pk_bf16_f32 v46, v46, v22
	v_cvt_pk_bf16_f32 v47, v47, v23
	v_lshlrev_b32_e32 v86, 16, v24
	v_lshlrev_b32_e32 v87, 16, v25
	v_lshlrev_b32_e32 v88, 16, v26
	v_lshlrev_b32_e32 v89, 16, v27
	v_and_b32_e32 v24, 0xffff0000, v24
	v_and_b32_e32 v25, 0xffff0000, v25
	v_and_b32_e32 v26, 0xffff0000, v26
	v_and_b32_e32 v27, 0xffff0000, v27
	v_mul_f32_e32 v86, v232, v86
	v_mul_f32_e32 v87, v234, v87
	v_mul_f32_e32 v88, v236, v88
	v_mul_f32_e32 v89, v238, v89
	v_mul_f32_e32 v24, v233, v24
	v_mul_f32_e32 v25, v235, v25
	v_mul_f32_e32 v26, v237, v26
	v_mul_f32_e32 v27, v239, v27
	v_cvt_pk_bf16_f32 v86, v86, v24
	v_cvt_pk_bf16_f32 v87, v87, v25
	v_cvt_pk_bf16_f32 v88, v88, v26
	v_cvt_pk_bf16_f32 v89, v89, v27
	s_nop 0
	v_mfma_f32_16x16x32_bf16 v[40:43], v[44:47], v[94:97], 0
	v_lshlrev_b32_e32 v44, 16, v28
	v_lshlrev_b32_e32 v45, 16, v29
	v_lshlrev_b32_e32 v46, 16, v30
	v_lshlrev_b32_e32 v47, 16, v31
	v_and_b32_e32 v28, 0xffff0000, v28
	v_and_b32_e32 v29, 0xffff0000, v29
	v_and_b32_e32 v30, 0xffff0000, v30
	v_and_b32_e32 v31, 0xffff0000, v31
	v_mul_f32_e32 v44, v240, v44
	v_mul_f32_e32 v45, v242, v45
	v_mul_f32_e32 v46, v244, v46
	v_mul_f32_e32 v47, v246, v47
	v_mul_f32_e32 v28, v241, v28
	v_mul_f32_e32 v29, v243, v29
	v_mul_f32_e32 v30, v245, v30
	v_mul_f32_e32 v31, v247, v31
	v_cvt_pk_bf16_f32 v44, v44, v28
	v_cvt_pk_bf16_f32 v45, v45, v29
	v_cvt_pk_bf16_f32 v46, v46, v30
	v_cvt_pk_bf16_f32 v47, v47, v31
	v_mfma_f32_16x16x32_bf16 v[40:43], v[86:89], v[98:101], v[40:43]
	v_lshlrev_b32_e32 v86, 16, v32
	v_lshlrev_b32_e32 v87, 16, v33
	v_lshlrev_b32_e32 v88, 16, v34
	v_lshlrev_b32_e32 v89, 16, v35
	v_and_b32_e32 v32, 0xffff0000, v32
	v_and_b32_e32 v33, 0xffff0000, v33
	v_and_b32_e32 v34, 0xffff0000, v34
	v_and_b32_e32 v35, 0xffff0000, v35
	v_mul_f32_e32 v86, v248, v86
	v_mul_f32_e32 v87, v250, v87
	v_mul_f32_e32 v88, v210, v88
	v_mul_f32_e32 v89, v212, v89
	v_mul_f32_e32 v32, v249, v32
	v_mul_f32_e32 v33, v251, v33
	v_mul_f32_e32 v34, v211, v34
	v_mul_f32_e32 v35, v213, v35
	v_cvt_pk_bf16_f32 v86, v86, v32
	v_cvt_pk_bf16_f32 v87, v87, v33
	v_cvt_pk_bf16_f32 v88, v88, v34
	v_cvt_pk_bf16_f32 v89, v89, v35
	v_mfma_f32_16x16x32_bf16 v[40:43], v[44:47], v[102:105], v[40:43]
	s_nop 1
	v_mfma_f32_16x16x32_bf16 v[40:43], v[86:89], v[106:109], v[40:43]
	s_add_u32 s8, s20, 0x38000
	s_addc_u32 s9, s21, 0
	v_cvt_pk_bf16_f32 v48, v36, v37
	v_cvt_pk_bf16_f32 v49, v38, v39
	global_store_dwordx2 v172, v[48:49], s[8:9]
	s_nop 7
	v_pk_fma_f32 v[36:37], v[90:91], v[36:37], v[40:41] op_sel_hi:[0,1,1]
	v_pk_fma_f32 v[38:39], v[90:91], v[38:39], v[42:43] op_sel_hi:[0,1,1]
	s_add_u32 s8, s16, 0x30000
	s_addc_u32 s9, s17, 0
	s_add_u32 s10, s18, 0x30000
	s_addc_u32 s11, s19, 0
	global_load_dwordx4 v[20:23], v170, s[8:9]
	global_load_dwordx4 v[24:27], v170, s[8:9] offset:64
	global_load_dwordx4 v[28:31], v170, s[8:9] offset:128
	global_load_dwordx4 v[32:35], v170, s[8:9] offset:192
	global_load_dwordx4 v[94:97], v171, s[10:11]
	global_load_dwordx4 v[98:101], v171, s[10:11] offset:64
	global_load_dwordx4 v[102:105], v171, s[10:11] offset:128
	global_load_dwordx4 v[106:109], v171, s[10:11] offset:192
	s_waitcnt vmcnt(18)
	v_lshlrev_b32_e32 v44, 16, v54
	v_lshlrev_b32_e32 v45, 16, v55
	v_lshlrev_b32_e32 v46, 16, v56
	v_lshlrev_b32_e32 v47, 16, v57
	v_and_b32_e32 v54, 0xffff0000, v54
	v_and_b32_e32 v55, 0xffff0000, v55
	v_and_b32_e32 v56, 0xffff0000, v56
	v_and_b32_e32 v57, 0xffff0000, v57
	v_mul_f32_e32 v44, v224, v44
	v_mul_f32_e32 v45, v226, v45
	v_mul_f32_e32 v46, v228, v46
	v_mul_f32_e32 v47, v230, v47
	v_mul_f32_e32 v54, v225, v54
	v_mul_f32_e32 v55, v227, v55
	v_mul_f32_e32 v56, v229, v56
	v_mul_f32_e32 v57, v231, v57
	v_cvt_pk_bf16_f32 v44, v44, v54
	v_cvt_pk_bf16_f32 v45, v45, v55
	v_cvt_pk_bf16_f32 v46, v46, v56
	v_cvt_pk_bf16_f32 v47, v47, v57
	v_lshlrev_b32_e32 v86, 16, v58
	v_lshlrev_b32_e32 v87, 16, v59
	v_lshlrev_b32_e32 v88, 16, v60
	v_lshlrev_b32_e32 v89, 16, v61
	v_and_b32_e32 v58, 0xffff0000, v58
	v_and_b32_e32 v59, 0xffff0000, v59
	v_and_b32_e32 v60, 0xffff0000, v60
	v_and_b32_e32 v61, 0xffff0000, v61
	v_mul_f32_e32 v86, v232, v86
	v_mul_f32_e32 v87, v234, v87
	v_mul_f32_e32 v88, v236, v88
	v_mul_f32_e32 v89, v238, v89
	v_mul_f32_e32 v58, v233, v58
	v_mul_f32_e32 v59, v235, v59
	v_mul_f32_e32 v60, v237, v60
	v_mul_f32_e32 v61, v239, v61
	v_cvt_pk_bf16_f32 v86, v86, v58
	v_cvt_pk_bf16_f32 v87, v87, v59
	v_cvt_pk_bf16_f32 v88, v88, v60
	v_cvt_pk_bf16_f32 v89, v89, v61
	s_nop 0
	v_mfma_f32_16x16x32_bf16 v[40:43], v[44:47], v[110:113], 0
	v_lshlrev_b32_e32 v44, 16, v62
	v_lshlrev_b32_e32 v45, 16, v63
	v_lshlrev_b32_e32 v46, 16, v64
	v_lshlrev_b32_e32 v47, 16, v65
	v_and_b32_e32 v62, 0xffff0000, v62
	v_and_b32_e32 v63, 0xffff0000, v63
	v_and_b32_e32 v64, 0xffff0000, v64
	v_and_b32_e32 v65, 0xffff0000, v65
	v_mul_f32_e32 v44, v240, v44
	v_mul_f32_e32 v45, v242, v45
	v_mul_f32_e32 v46, v244, v46
	v_mul_f32_e32 v47, v246, v47
	v_mul_f32_e32 v62, v241, v62
	v_mul_f32_e32 v63, v243, v63
	v_mul_f32_e32 v64, v245, v64
	v_mul_f32_e32 v65, v247, v65
	v_cvt_pk_bf16_f32 v44, v44, v62
	v_cvt_pk_bf16_f32 v45, v45, v63
; __device__ __forceinline__ unsigned cvt_pk_bf16(float lo, float hi) { unsigned r; asm("v_cvt_pk_bf16_f32 %0, %1, %2" : "=v"(r) : "v"(lo), "v"(hi)); return r; }
; __device__ __forceinline__ float bf2f(unsigned b) { return __uint_as_float(b << 16); }
; __device__ __forceinline__ void r1s_load(const bf16_t* __restrict__ kT, const bf16_t* __restrict__ vT, int bh, int cc, size_t koff, size_t voff, bf16x8 (&kk)[4], bf16x8 (&vv)[4]) {
;     const bf16_t* kt = kT + (size_t)(bh * 18 + cc) * 16384 + koff; const bf16_t* vt = vT + (size_t)(bh * 18 + cc) * 16384 + voff;
; #pragma unroll
;     for (int ks = 0; ks < 4; ++ks) { kk[ks] = *(const bf16x8*)(kt + 32 * ks); vv[ks] = *(const bf16x8*)(vt + 32 * ks); }
; }
; __device__ __forceinline__ void r1s_step(const bf16x8 (&kk)[4], const bf16x8 (&vv)[4], const float (&w)[4][8], f32x4& S, float gC, bool st, bf16_t* dst) {
;     f32x4 acc = {0.f, 0.f, 0.f, 0.f};
; #pragma unroll
;     for (int ks = 0; ks < 4; ++ks) {
;         float f[8];
; #pragma unroll
;         for (int e = 0; e < 8; ++e) f[e] = bf2f((unsigned)(unsigned short)kk[ks][e]) * w[ks][e];
;         u32x4 wf; wf.x = cvt_pk_bf16(f[0], f[1]); wf.y = cvt_pk_bf16(f[2], f[3]); wf.z = cvt_pk_bf16(f[4], f[5]); wf.w = cvt_pk_bf16(f[6], f[7]);
;         acc = __builtin_amdgcn_mfma_f32_16x16x32_bf16(__builtin_bit_cast(bf16x8, wf), vv[ks], acc, 0, 0, 0);
;     }
;     if (st) { u32x2 o; o.x = cvt_pk_bf16(S[0], S[1]); o.y = cvt_pk_bf16(S[2], S[3]); *(u32x2*)dst = o; }
;     S = S * gC + acc;
; }
	v_cvt_pk_bf16_f32 v46, v46, v64
	v_cvt_pk_bf16_f32 v47, v47, v65
	v_mfma_f32_16x16x32_bf16 v[40:43], v[86:89], v[114:117], v[40:43]
	v_lshlrev_b32_e32 v86, 16, v66
	v_lshlrev_b32_e32 v87, 16, v67
	v_lshlrev_b32_e32 v88, 16, v68
	v_lshlrev_b32_e32 v89, 16, v69
	v_and_b32_e32 v66, 0xffff0000, v66
	v_and_b32_e32 v67, 0xffff0000, v67
	v_and_b32_e32 v68, 0xffff0000, v68
	v_and_b32_e32 v69, 0xffff0000, v69
	v_mul_f32_e32 v86, v248, v86
	v_mul_f32_e32 v87, v250, v87
	v_mul_f32_e32 v88, v210, v88
	v_mul_f32_e32 v89, v212, v89
	v_mul_f32_e32 v66, v249, v66
	v_mul_f32_e32 v67, v251, v67
	v_mul_f32_e32 v68, v211, v68
	v_mul_f32_e32 v69, v213, v69
	v_cvt_pk_bf16_f32 v86, v86, v66
	v_cvt_pk_bf16_f32 v87, v87, v67
	v_cvt_pk_bf16_f32 v88, v88, v68
	v_cvt_pk_bf16_f32 v89, v89, v69
	v_mfma_f32_16x16x32_bf16 v[40:43], v[44:47], v[118:121], v[40:43]
	s_nop 1
	v_mfma_f32_16x16x32_bf16 v[40:43], v[86:89], v[122:125], v[40:43]
	s_add_u32 s8, s20, 0x30000
	s_addc_u32 s9, s21, 0
	v_cvt_pk_bf16_f32 v48, v36, v37
	v_cvt_pk_bf16_f32 v49, v38, v39
	global_store_dwordx2 v172, v[48:49], s[8:9]
	s_nop 7
	v_pk_fma_f32 v[36:37], v[90:91], v[36:37], v[40:41] op_sel_hi:[0,1,1]
	v_pk_fma_f32 v[38:39], v[90:91], v[38:39], v[42:43] op_sel_hi:[0,1,1]
	s_add_u32 s8, s16, 0x28000
	s_addc_u32 s9, s17, 0
	s_add_u32 s10, s18, 0x28000
	s_addc_u32 s11, s19, 0
	global_load_dwordx4 v[54:57], v170, s[8:9]
	global_load_dwordx4 v[58:61], v170, s[8:9] offset:64
	global_load_dwordx4 v[62:65], v170, s[8:9] offset:128
	global_load_dwordx4 v[66:69], v170, s[8:9] offset:192
	global_load_dwordx4 v[110:113], v171, s[10:11]
	global_load_dwordx4 v[114:117], v171, s[10:11] offset:64
	global_load_dwordx4 v[118:121], v171, s[10:11] offset:128
	global_load_dwordx4 v[122:125], v171, s[10:11] offset:192
	s_waitcnt vmcnt(18)
	v_lshlrev_b32_e32 v44, 16, v2
	v_lshlrev_b32_e32 v45, 16, v3
	v_lshlrev_b32_e32 v46, 16, v4
	v_lshlrev_b32_e32 v47, 16, v5
	v_and_b32_e32 v2, 0xffff0000, v2
	v_and_b32_e32 v3, 0xffff0000, v3
	v_and_b32_e32 v4, 0xffff0000, v4
	v_and_b32_e32 v5, 0xffff0000, v5
	v_mul_f32_e32 v44, v224, v44
	v_mul_f32_e32 v45, v226, v45
	v_mul_f32_e32 v46, v228, v46
	v_mul_f32_e32 v47, v230, v47
	v_mul_f32_e32 v2, v225, v2
	v_mul_f32_e32 v3, v227, v3
	v_mul_f32_e32 v4, v229, v4
	v_mul_f32_e32 v5, v231, v5
	v_cvt_pk_bf16_f32 v44, v44, v2
	v_cvt_pk_bf16_f32 v45, v45, v3
	v_cvt_pk_bf16_f32 v46, v46, v4
	v_cvt_pk_bf16_f32 v47, v47, v5
	v_lshlrev_b32_e32 v86, 16, v6
	v_lshlrev_b32_e32 v87, 16, v7
	v_lshlrev_b32_e32 v88, 16, v8
	v_lshlrev_b32_e32 v89, 16, v9
	v_and_b32_e32 v6, 0xffff0000, v6
	v_and_b32_e32 v7, 0xffff0000, v7
	v_and_b32_e32 v8, 0xffff0000, v8
	v_and_b32_e32 v9, 0xffff0000, v9
	v_mul_f32_e32 v86, v232, v86
	v_mul_f32_e32 v87, v234, v87
	v_mul_f32_e32 v88, v236, v88
	v_mul_f32_e32 v89, v238, v89
	v_mul_f32_e32 v6, v233, v6
	v_mul_f32_e32 v7, v235, v7
	v_mul_f32_e32 v8, v237, v8
	v_mul_f32_e32 v9, v239, v9
	v_cvt_pk_bf16_f32 v86, v86, v6
	v_cvt_pk_bf16_f32 v87, v87, v7
	v_cvt_pk_bf16_f32 v88, v88, v8
	v_cvt_pk_bf16_f32 v89, v89, v9
	s_nop 0
	v_mfma_f32_16x16x32_bf16 v[40:43], v[44:47], v[70:73], 0
	v_lshlrev_b32_e32 v44, 16, v10
	v_lshlrev_b32_e32 v45, 16, v11
	v_lshlrev_b32_e32 v46, 16, v12
	v_lshlrev_b32_e32 v47, 16, v13
	v_and_b32_e32 v10, 0xffff0000, v10
	v_and_b32_e32 v11, 0xffff0000, v11
	v_and_b32_e32 v12, 0xffff0000, v12
	v_and_b32_e32 v13, 0xffff0000, v13
	v_mul_f32_e32 v44, v240, v44
	v_mul_f32_e32 v45, v242, v45
	v_mul_f32_e32 v46, v244, v46
	v_mul_f32_e32 v47, v246, v47
	v_mul_f32_e32 v10, v241, v10
	v_mul_f32_e32 v11, v243, v11
	v_mul_f32_e32 v12, v245, v12
	v_mul_f32_e32 v13, v247, v13
	v_cvt_pk_bf16_f32 v44, v44, v10
	v_cvt_pk_bf16_f32 v45, v45, v11
	v_cvt_pk_bf16_f32 v46, v46, v12
	v_cvt_pk_bf16_f32 v47, v47, v13
	v_mfma_f32_16x16x32_bf16 v[40:43], v[86:89], v[74:77], v[40:43]
	v_lshlrev_b32_e32 v86, 16, v14
	v_lshlrev_b32_e32 v87, 16, v15
	v_lshlrev_b32_e32 v88, 16, v16
	v_lshlrev_b32_e32 v89, 16, v17
	v_and_b32_e32 v14, 0xffff0000, v14
	v_and_b32_e32 v15, 0xffff0000, v15
	v_and_b32_e32 v16, 0xffff0000, v16
	v_and_b32_e32 v17, 0xffff0000, v17
	v_mul_f32_e32 v86, v248, v86
	v_mul_f32_e32 v87, v250, v87
	v_mul_f32_e32 v88, v210, v88
	v_mul_f32_e32 v89, v212, v89
	v_mul_f32_e32 v14, v249, v14
	v_mul_f32_e32 v15, v251, v15
	v_mul_f32_e32 v16, v211, v16
	v_mul_f32_e32 v17, v213, v17
	v_cvt_pk_bf16_f32 v86, v86, v14
	v_cvt_pk_bf16_f32 v87, v87, v15
	v_cvt_pk_bf16_f32 v88, v88, v16
	v_cvt_pk_bf16_f32 v89, v89, v17
	v_mfma_f32_16x16x32_bf16 v[40:43], v[44:47], v[78:81], v[40:43]
	s_nop 1
	v_mfma_f32_16x16x32_bf16 v[40:43], v[86:89], v[82:85], v[40:43]
	s_add_u32 s8, s20, 0x28000
	s_addc_u32 s9, s21, 0
	v_cvt_pk_bf16_f32 v48, v36, v37
	v_cvt_pk_bf16_f32 v49, v38, v39
	global_store_dwordx2 v172, v[48:49], s[8:9]
	s_nop 7
	v_pk_fma_f32 v[36:37], v[90:91], v[36:37], v[40:41] op_sel_hi:[0,1,1]
	v_pk_fma_f32 v[38:39], v[90:91], v[38:39], v[42:43] op_sel_hi:[0,1,1]
	s_add_u32 s8, s16, 0x20000
	s_addc_u32 s9, s17, 0
	s_add_u32 s10, s18, 0x20000
	s_addc_u32 s11, s19, 0
	global_load_dwordx4 v[2:5], v170, s[8:9]
	global_load_dwordx4 v[6:9], v170, s[8:9] offset:64
	global_load_dwordx4 v[10:13], v170, s[8:9] offset:128
	global_load_dwordx4 v[14:17], v170, s[8:9] offset:192
	global_load_dwordx4 v[70:73], v171, s[10:11]
	global_load_dwordx4 v[74:77], v171, s[10:11] offset:64
	global_load_dwordx4 v[78:81], v171, s[10:11] offset:128
	global_load_dwordx4 v[82:85], v171, s[10:11] offset:192
	s_waitcnt vmcnt(18)
; __device__ __forceinline__ unsigned cvt_pk_bf16(float lo, float hi) { unsigned r; asm("v_cvt_pk_bf16_f32 %0, %1, %2" : "=v"(r) : "v"(lo), "v"(hi)); return r; }
; __device__ __forceinline__ float bf2f(unsigned b) { return __uint_as_float(b << 16); }
; __device__ __forceinline__ void r1s_load(const bf16_t* __restrict__ kT, const bf16_t* __restrict__ vT, int bh, int cc, size_t koff, size_t voff, bf16x8 (&kk)[4], bf16x8 (&vv)[4]) {
;     const bf16_t* kt = kT + (size_t)(bh * 18 + cc) * 16384 + koff; const bf16_t* vt = vT + (size_t)(bh * 18 + cc) * 16384 + voff;
; #pragma unroll
;     for (int ks = 0; ks < 4; ++ks) { kk[ks] = *(const bf16x8*)(kt + 32 * ks); vv[ks] = *(const bf16x8*)(vt + 32 * ks); }
; }
; __device__ __forceinline__ void r1s_step(const bf16x8 (&kk)[4], const bf16x8 (&vv)[4], const float (&w)[4][8], f32x4& S, float gC, bool st, bf16_t* dst) {
;     f32x4 acc = {0.f, 0.f, 0.f, 0.f};
; #pragma unroll
;     for (int ks = 0; ks < 4; ++ks) {
;         float f[8];
; #pragma unroll
;         for (int e = 0; e < 8; ++e) f[e] = bf2f((unsigned)(unsigned short)kk[ks][e]) * w[ks][e];
;         u32x4 wf; wf.x = cvt_pk_bf16(f[0], f[1]); wf.y = cvt_pk_bf16(f[2], f[3]); wf.z = cvt_pk_bf16(f[4], f[5]); wf.w = cvt_pk_bf16(f[6], f[7]);
;         acc = __builtin_amdgcn_mfma_f32_16x16x32_bf16(__builtin_bit_cast(bf16x8, wf), vv[ks], acc, 0, 0, 0);
;     }
;     if (st) { u32x2 o; o.x = cvt_pk_bf16(S[0], S[1]); o.y = cvt_pk_bf16(S[2], S[3]); *(u32x2*)dst = o; }
;     S = S * gC + acc;
; }
	v_lshlrev_b32_e32 v44, 16, v20
	v_lshlrev_b32_e32 v45, 16, v21
	v_lshlrev_b32_e32 v46, 16, v22
	v_lshlrev_b32_e32 v47, 16, v23
	v_and_b32_e32 v20, 0xffff0000, v20
	v_and_b32_e32 v21, 0xffff0000, v21
	v_and_b32_e32 v22, 0xffff0000, v22
	v_and_b32_e32 v23, 0xffff0000, v23
	v_mul_f32_e32 v44, v224, v44
	v_mul_f32_e32 v45, v226, v45
	v_mul_f32_e32 v46, v228, v46
	v_mul_f32_e32 v47, v230, v47
	v_mul_f32_e32 v20, v225, v20
	v_mul_f32_e32 v21, v227, v21
	v_mul_f32_e32 v22, v229, v22
	v_mul_f32_e32 v23, v231, v23
	v_cvt_pk_bf16_f32 v44, v44, v20
	v_cvt_pk_bf16_f32 v45, v45, v21
	v_cvt_pk_bf16_f32 v46, v46, v22
	v_cvt_pk_bf16_f32 v47, v47, v23
	v_lshlrev_b32_e32 v86, 16, v24
	v_lshlrev_b32_e32 v87, 16, v25
	v_lshlrev_b32_e32 v88, 16, v26
	v_lshlrev_b32_e32 v89, 16, v27
	v_and_b32_e32 v24, 0xffff0000, v24
	v_and_b32_e32 v25, 0xffff0000, v25
	v_and_b32_e32 v26, 0xffff0000, v26
	v_and_b32_e32 v27, 0xffff0000, v27
	v_mul_f32_e32 v86, v232, v86
	v_mul_f32_e32 v87, v234, v87
	v_mul_f32_e32 v88, v236, v88
	v_mul_f32_e32 v89, v238, v89
	v_mul_f32_e32 v24, v233, v24
	v_mul_f32_e32 v25, v235, v25
	v_mul_f32_e32 v26, v237, v26
	v_mul_f32_e32 v27, v239, v27
	v_cvt_pk_bf16_f32 v86, v86, v24
	v_cvt_pk_bf16_f32 v87, v87, v25
	v_cvt_pk_bf16_f32 v88, v88, v26
	v_cvt_pk_bf16_f32 v89, v89, v27
	s_nop 0
	v_mfma_f32_16x16x32_bf16 v[40:43], v[44:47], v[94:97], 0
	v_lshlrev_b32_e32 v44, 16, v28
	v_lshlrev_b32_e32 v45, 16, v29
	v_lshlrev_b32_e32 v46, 16, v30
	v_lshlrev_b32_e32 v47, 16, v31
	v_and_b32_e32 v28, 0xffff0000, v28
	v_and_b32_e32 v29, 0xffff0000, v29
	v_and_b32_e32 v30, 0xffff0000, v30
	v_and_b32_e32 v31, 0xffff0000, v31
	v_mul_f32_e32 v44, v240, v44
	v_mul_f32_e32 v45, v242, v45
	v_mul_f32_e32 v46, v244, v46
	v_mul_f32_e32 v47, v246, v47
	v_mul_f32_e32 v28, v241, v28
	v_mul_f32_e32 v29, v243, v29
	v_mul_f32_e32 v30, v245, v30
	v_mul_f32_e32 v31, v247, v31
	v_cvt_pk_bf16_f32 v44, v44, v28
	v_cvt_pk_bf16_f32 v45, v45, v29
	v_cvt_pk_bf16_f32 v46, v46, v30
	v_cvt_pk_bf16_f32 v47, v47, v31
	v_mfma_f32_16x16x32_bf16 v[40:43], v[86:89], v[98:101], v[40:43]
	v_lshlrev_b32_e32 v86, 16, v32
	v_lshlrev_b32_e32 v87, 16, v33
	v_lshlrev_b32_e32 v88, 16, v34
	v_lshlrev_b32_e32 v89, 16, v35
	v_and_b32_e32 v32, 0xffff0000, v32
	v_and_b32_e32 v33, 0xffff0000, v33
	v_and_b32_e32 v34, 0xffff0000, v34
	v_and_b32_e32 v35, 0xffff0000, v35
	v_mul_f32_e32 v86, v248, v86
	v_mul_f32_e32 v87, v250, v87
	v_mul_f32_e32 v88, v210, v88
	v_mul_f32_e32 v89, v212, v89
	v_mul_f32_e32 v32, v249, v32
	v_mul_f32_e32 v33, v251, v33
	v_mul_f32_e32 v34, v211, v34
	v_mul_f32_e32 v35, v213, v35
	v_cvt_pk_bf16_f32 v86, v86, v32
	v_cvt_pk_bf16_f32 v87, v87, v33
	v_cvt_pk_bf16_f32 v88, v88, v34
	v_cvt_pk_bf16_f32 v89, v89, v35
	v_mfma_f32_16x16x32_bf16 v[40:43], v[44:47], v[102:105], v[40:43]
	s_nop 1
	v_mfma_f32_16x16x32_bf16 v[40:43], v[86:89], v[106:109], v[40:43]
	s_add_u32 s8, s20, 0x20000
	s_addc_u32 s9, s21, 0
	v_cvt_pk_bf16_f32 v48, v36, v37
	v_cvt_pk_bf16_f32 v49, v38, v39
	global_store_dwordx2 v172, v[48:49], s[8:9]
	s_nop 7
	v_pk_fma_f32 v[36:37], v[90:91], v[36:37], v[40:41] op_sel_hi:[0,1,1]
	v_pk_fma_f32 v[38:39], v[90:91], v[38:39], v[42:43] op_sel_hi:[0,1,1]
	s_add_u32 s8, s16, 0x18000
	s_addc_u32 s9, s17, 0
	s_add_u32 s10, s18, 0x18000
	s_addc_u32 s11, s19, 0
	global_load_dwordx4 v[20:23], v170, s[8:9]
	global_load_dwordx4 v[24:27], v170, s[8:9] offset:64
	global_load_dwordx4 v[28:31], v170, s[8:9] offset:128
	global_load_dwordx4 v[32:35], v170, s[8:9] offset:192
	global_load_dwordx4 v[94:97], v171, s[10:11]
	global_load_dwordx4 v[98:101], v171, s[10:11] offset:64
	global_load_dwordx4 v[102:105], v171, s[10:11] offset:128
	global_load_dwordx4 v[106:109], v171, s[10:11] offset:192
	s_waitcnt vmcnt(18)
	v_lshlrev_b32_e32 v44, 16, v54
	v_lshlrev_b32_e32 v45, 16, v55
	v_lshlrev_b32_e32 v46, 16, v56
	v_lshlrev_b32_e32 v47, 16, v57
	v_and_b32_e32 v54, 0xffff0000, v54
	v_and_b32_e32 v55, 0xffff0000, v55
	v_and_b32_e32 v56, 0xffff0000, v56
	v_and_b32_e32 v57, 0xffff0000, v57
	v_mul_f32_e32 v44, v224, v44
	v_mul_f32_e32 v45, v226, v45
	v_mul_f32_e32 v46, v228, v46
	v_mul_f32_e32 v47, v230, v47
	v_mul_f32_e32 v54, v225, v54
	v_mul_f32_e32 v55, v227, v55
	v_mul_f32_e32 v56, v229, v56
	v_mul_f32_e32 v57, v231, v57
	v_cvt_pk_bf16_f32 v44, v44, v54
	v_cvt_pk_bf16_f32 v45, v45, v55
	v_cvt_pk_bf16_f32 v46, v46, v56
	v_cvt_pk_bf16_f32 v47, v47, v57
	v_lshlrev_b32_e32 v86, 16, v58
	v_lshlrev_b32_e32 v87, 16, v59
	v_lshlrev_b32_e32 v88, 16, v60
	v_lshlrev_b32_e32 v89, 16, v61
	v_and_b32_e32 v58, 0xffff0000, v58
	v_and_b32_e32 v59, 0xffff0000, v59
	v_and_b32_e32 v60, 0xffff0000, v60
	v_and_b32_e32 v61, 0xffff0000, v61
	v_mul_f32_e32 v86, v232, v86
	v_mul_f32_e32 v87, v234, v87
	v_mul_f32_e32 v88, v236, v88
	v_mul_f32_e32 v89, v238, v89
	v_mul_f32_e32 v58, v233, v58
	v_mul_f32_e32 v59, v235, v59
	v_mul_f32_e32 v60, v237, v60
	v_mul_f32_e32 v61, v239, v61
	v_cvt_pk_bf16_f32 v86, v86, v58
	v_cvt_pk_bf16_f32 v87, v87, v59
	v_cvt_pk_bf16_f32 v88, v88, v60
	v_cvt_pk_bf16_f32 v89, v89, v61
	s_nop 0
	v_mfma_f32_16x16x32_bf16 v[40:43], v[44:47], v[110:113], 0
	v_lshlrev_b32_e32 v44, 16, v62
	v_lshlrev_b32_e32 v45, 16, v63
	v_lshlrev_b32_e32 v46, 16, v64
	v_lshlrev_b32_e32 v47, 16, v65
	v_and_b32_e32 v62, 0xffff0000, v62
	v_and_b32_e32 v63, 0xffff0000, v63
	v_and_b32_e32 v64, 0xffff0000, v64
	v_and_b32_e32 v65, 0xffff0000, v65
	v_mul_f32_e32 v44, v240, v44
	v_mul_f32_e32 v45, v242, v45
	v_mul_f32_e32 v46, v244, v46
	v_mul_f32_e32 v47, v246, v47
	v_mul_f32_e32 v62, v241, v62
	v_mul_f32_e32 v63, v243, v63
	v_mul_f32_e32 v64, v245, v64
	v_mul_f32_e32 v65, v247, v65
	v_cvt_pk_bf16_f32 v44, v44, v62
	v_cvt_pk_bf16_f32 v45, v45, v63
; __device__ __forceinline__ unsigned cvt_pk_bf16(float lo, float hi) { unsigned r; asm("v_cvt_pk_bf16_f32 %0, %1, %2" : "=v"(r) : "v"(lo), "v"(hi)); return r; }
; __device__ __forceinline__ float bf2f(unsigned b) { return __uint_as_float(b << 16); }
; __device__ __forceinline__ void r1s_load(const bf16_t* __restrict__ kT, const bf16_t* __restrict__ vT, int bh, int cc, size_t koff, size_t voff, bf16x8 (&kk)[4], bf16x8 (&vv)[4]) {
;     const bf16_t* kt = kT + (size_t)(bh * 18 + cc) * 16384 + koff; const bf16_t* vt = vT + (size_t)(bh * 18 + cc) * 16384 + voff;
; #pragma unroll
;     for (int ks = 0; ks < 4; ++ks) { kk[ks] = *(const bf16x8*)(kt + 32 * ks); vv[ks] = *(const bf16x8*)(vt + 32 * ks); }
; }
; __device__ __forceinline__ void r1s_step(const bf16x8 (&kk)[4], const bf16x8 (&vv)[4], const float (&w)[4][8], f32x4& S, float gC, bool st, bf16_t* dst) {
;     f32x4 acc = {0.f, 0.f, 0.f, 0.f};
; #pragma unroll
;     for (int ks = 0; ks < 4; ++ks) {
;         float f[8];
; #pragma unroll
;         for (int e = 0; e < 8; ++e) f[e] = bf2f((unsigned)(unsigned short)kk[ks][e]) * w[ks][e];
;         u32x4 wf; wf.x = cvt_pk_bf16(f[0], f[1]); wf.y = cvt_pk_bf16(f[2], f[3]); wf.z = cvt_pk_bf16(f[4], f[5]); wf.w = cvt_pk_bf16(f[6], f[7]);
;         acc = __builtin_amdgcn_mfma_f32_16x16x32_bf16(__builtin_bit_cast(bf16x8, wf), vv[ks], acc, 0, 0, 0);
;     }
;     if (st) { u32x2 o; o.x = cvt_pk_bf16(S[0], S[1]); o.y = cvt_pk_bf16(S[2], S[3]); *(u32x2*)dst = o; }
;     S = S * gC + acc;
; }
	v_cvt_pk_bf16_f32 v46, v46, v64
	v_cvt_pk_bf16_f32 v47, v47, v65
	v_mfma_f32_16x16x32_bf16 v[40:43], v[86:89], v[114:117], v[40:43]
	v_lshlrev_b32_e32 v86, 16, v66
	v_lshlrev_b32_e32 v87, 16, v67
	v_lshlrev_b32_e32 v88, 16, v68
	v_lshlrev_b32_e32 v89, 16, v69
	v_and_b32_e32 v66, 0xffff0000, v66
	v_and_b32_e32 v67, 0xffff0000, v67
	v_and_b32_e32 v68, 0xffff0000, v68
	v_and_b32_e32 v69, 0xffff0000, v69
	v_mul_f32_e32 v86, v248, v86
	v_mul_f32_e32 v87, v250, v87
	v_mul_f32_e32 v88, v210, v88
	v_mul_f32_e32 v89, v212, v89
	v_mul_f32_e32 v66, v249, v66
	v_mul_f32_e32 v67, v251, v67
	v_mul_f32_e32 v68, v211, v68
	v_mul_f32_e32 v69, v213, v69
	v_cvt_pk_bf16_f32 v86, v86, v66
	v_cvt_pk_bf16_f32 v87, v87, v67
	v_cvt_pk_bf16_f32 v88, v88, v68
	v_cvt_pk_bf16_f32 v89, v89, v69
	v_mfma_f32_16x16x32_bf16 v[40:43], v[44:47], v[118:121], v[40:43]
	s_nop 1
	v_mfma_f32_16x16x32_bf16 v[40:43], v[86:89], v[122:125], v[40:43]
	s_add_u32 s8, s20, 0x18000
	s_addc_u32 s9, s21, 0
	v_cvt_pk_bf16_f32 v48, v36, v37
	v_cvt_pk_bf16_f32 v49, v38, v39
	global_store_dwordx2 v172, v[48:49], s[8:9]
	s_nop 7
	v_pk_fma_f32 v[36:37], v[90:91], v[36:37], v[40:41] op_sel_hi:[0,1,1]
	v_pk_fma_f32 v[38:39], v[90:91], v[38:39], v[42:43] op_sel_hi:[0,1,1]
	s_add_u32 s8, s16, 0x10000
	s_addc_u32 s9, s17, 0
	s_add_u32 s10, s18, 0x10000
	s_addc_u32 s11, s19, 0
	global_load_dwordx4 v[54:57], v170, s[8:9]
	global_load_dwordx4 v[58:61], v170, s[8:9] offset:64
	global_load_dwordx4 v[62:65], v170, s[8:9] offset:128
	global_load_dwordx4 v[66:69], v170, s[8:9] offset:192
	global_load_dwordx4 v[110:113], v171, s[10:11]
	global_load_dwordx4 v[114:117], v171, s[10:11] offset:64
	global_load_dwordx4 v[118:121], v171, s[10:11] offset:128
	global_load_dwordx4 v[122:125], v171, s[10:11] offset:192
	s_waitcnt vmcnt(18)
	v_lshlrev_b32_e32 v44, 16, v2
	v_lshlrev_b32_e32 v45, 16, v3
	v_lshlrev_b32_e32 v46, 16, v4
	v_lshlrev_b32_e32 v47, 16, v5
	v_and_b32_e32 v2, 0xffff0000, v2
	v_and_b32_e32 v3, 0xffff0000, v3
	v_and_b32_e32 v4, 0xffff0000, v4
	v_and_b32_e32 v5, 0xffff0000, v5
	v_mul_f32_e32 v44, v224, v44
	v_mul_f32_e32 v45, v226, v45
	v_mul_f32_e32 v46, v228, v46
	v_mul_f32_e32 v47, v230, v47
	v_mul_f32_e32 v2, v225, v2
	v_mul_f32_e32 v3, v227, v3
	v_mul_f32_e32 v4, v229, v4
	v_mul_f32_e32 v5, v231, v5
	v_cvt_pk_bf16_f32 v44, v44, v2
	v_cvt_pk_bf16_f32 v45, v45, v3
	v_cvt_pk_bf16_f32 v46, v46, v4
	v_cvt_pk_bf16_f32 v47, v47, v5
	v_lshlrev_b32_e32 v86, 16, v6
	v_lshlrev_b32_e32 v87, 16, v7
	v_lshlrev_b32_e32 v88, 16, v8
	v_lshlrev_b32_e32 v89, 16, v9
	v_and_b32_e32 v6, 0xffff0000, v6
	v_and_b32_e32 v7, 0xffff0000, v7
	v_and_b32_e32 v8, 0xffff0000, v8
	v_and_b32_e32 v9, 0xffff0000, v9
	v_mul_f32_e32 v86, v232, v86
	v_mul_f32_e32 v87, v234, v87
	v_mul_f32_e32 v88, v236, v88
	v_mul_f32_e32 v89, v238, v89
	v_mul_f32_e32 v6, v233, v6
	v_mul_f32_e32 v7, v235, v7
	v_mul_f32_e32 v8, v237, v8
	v_mul_f32_e32 v9, v239, v9
	v_cvt_pk_bf16_f32 v86, v86, v6
	v_cvt_pk_bf16_f32 v87, v87, v7
	v_cvt_pk_bf16_f32 v88, v88, v8
	v_cvt_pk_bf16_f32 v89, v89, v9
	s_nop 0
	v_mfma_f32_16x16x32_bf16 v[40:43], v[44:47], v[70:73], 0
	v_lshlrev_b32_e32 v44, 16, v10
	v_lshlrev_b32_e32 v45, 16, v11
	v_lshlrev_b32_e32 v46, 16, v12
	v_lshlrev_b32_e32 v47, 16, v13
	v_and_b32_e32 v10, 0xffff0000, v10
	v_and_b32_e32 v11, 0xffff0000, v11
	v_and_b32_e32 v12, 0xffff0000, v12
	v_and_b32_e32 v13, 0xffff0000, v13
	v_mul_f32_e32 v44, v240, v44
	v_mul_f32_e32 v45, v242, v45
	v_mul_f32_e32 v46, v244, v46
	v_mul_f32_e32 v47, v246, v47
	v_mul_f32_e32 v10, v241, v10
	v_mul_f32_e32 v11, v243, v11
	v_mul_f32_e32 v12, v245, v12
	v_mul_f32_e32 v13, v247, v13
	v_cvt_pk_bf16_f32 v44, v44, v10
	v_cvt_pk_bf16_f32 v45, v45, v11
	v_cvt_pk_bf16_f32 v46, v46, v12
	v_cvt_pk_bf16_f32 v47, v47, v13
	v_mfma_f32_16x16x32_bf16 v[40:43], v[86:89], v[74:77], v[40:43]
	v_lshlrev_b32_e32 v86, 16, v14
	v_lshlrev_b32_e32 v87, 16, v15
	v_lshlrev_b32_e32 v88, 16, v16
	v_lshlrev_b32_e32 v89, 16, v17
	v_and_b32_e32 v14, 0xffff0000, v14
	v_and_b32_e32 v15, 0xffff0000, v15
	v_and_b32_e32 v16, 0xffff0000, v16
	v_and_b32_e32 v17, 0xffff0000, v17
	v_mul_f32_e32 v86, v248, v86
	v_mul_f32_e32 v87, v250, v87
	v_mul_f32_e32 v88, v210, v88
	v_mul_f32_e32 v89, v212, v89
	v_mul_f32_e32 v14, v249, v14
	v_mul_f32_e32 v15, v251, v15
	v_mul_f32_e32 v16, v211, v16
	v_mul_f32_e32 v17, v213, v17
	v_cvt_pk_bf16_f32 v86, v86, v14
	v_cvt_pk_bf16_f32 v87, v87, v15
	v_cvt_pk_bf16_f32 v88, v88, v16
	v_cvt_pk_bf16_f32 v89, v89, v17
	v_mfma_f32_16x16x32_bf16 v[40:43], v[44:47], v[78:81], v[40:43]
	s_nop 1
	v_mfma_f32_16x16x32_bf16 v[40:43], v[86:89], v[82:85], v[40:43]
	s_add_u32 s8, s20, 0x10000
	s_addc_u32 s9, s21, 0
	v_cvt_pk_bf16_f32 v48, v36, v37
	v_cvt_pk_bf16_f32 v49, v38, v39
	global_store_dwordx2 v172, v[48:49], s[8:9]
	s_nop 7
	v_pk_fma_f32 v[36:37], v[90:91], v[36:37], v[40:41] op_sel_hi:[0,1,1]
	v_pk_fma_f32 v[38:39], v[90:91], v[38:39], v[42:43] op_sel_hi:[0,1,1]
	s_waitcnt vmcnt(10)
; __device__ __forceinline__ unsigned cvt_pk_bf16(float lo, float hi) { unsigned r; asm("v_cvt_pk_bf16_f32 %0, %1, %2" : "=v"(r) : "v"(lo), "v"(hi)); return r; }
; __device__ __forceinline__ float bf2f(unsigned b) { return __uint_as_float(b << 16); }
; __device__ __forceinline__ void r1s_step(const bf16x8 (&kk)[4], const bf16x8 (&vv)[4], const float (&w)[4][8], f32x4& S, float gC, bool st, bf16_t* dst) {
;     f32x4 acc = {0.f, 0.f, 0.f, 0.f};
; #pragma unroll
;     for (int ks = 0; ks < 4; ++ks) {
;         float f[8];
; #pragma unroll
;         for (int e = 0; e < 8; ++e) f[e] = bf2f((unsigned)(unsigned short)kk[ks][e]) * w[ks][e];
;         u32x4 wf; wf.x = cvt_pk_bf16(f[0], f[1]); wf.y = cvt_pk_bf16(f[2], f[3]); wf.z = cvt_pk_bf16(f[4], f[5]); wf.w = cvt_pk_bf16(f[6], f[7]);
;         acc = __builtin_amdgcn_mfma_f32_16x16x32_bf16(__builtin_bit_cast(bf16x8, wf), vv[ks], acc, 0, 0, 0);
;     }
;     if (st) { u32x2 o; o.x = cvt_pk_bf16(S[0], S[1]); o.y = cvt_pk_bf16(S[2], S[3]); *(u32x2*)dst = o; }
;     S = S * gC + acc;
; }
; __device__ __forceinline__ void r1s_sweep(const bf16_t* __restrict__ kT, const bf16_t* __restrict__ vT, bf16_t* __restrict__ STd, int bh, int s, int wid, int fr, int fq, float lg, float gC, bool fwd) {
;     ...
;     for (int i = 0; i < 18; i += 2) {
;         r1s_load(kT, vT, bh, R1S_CC(i + 1), koff, voff, kB, vB);
;         { const int cc = R1S_CC(i); r1s_step(kA, vA, w, S, gC, cc >= 2, dst0 + (size_t)(cc >= 2 ? cc - 2 : 0) * 16384); }
;         if (i + 2 < 18) r1s_load(kT, vT, bh, R1S_CC(i + 2), koff, voff, kA, vA);
;         { const int cc = R1S_CC(i + 1); r1s_step(kB, vB, w, S, gC, cc >= 2, dst0 + (size_t)(cc >= 2 ? cc - 2 : 0) * 16384); }
;     }
	v_lshlrev_b32_e32 v44, 16, v20
	v_lshlrev_b32_e32 v45, 16, v21
	v_lshlrev_b32_e32 v46, 16, v22
	v_lshlrev_b32_e32 v47, 16, v23
	v_and_b32_e32 v20, 0xffff0000, v20
	v_and_b32_e32 v21, 0xffff0000, v21
	v_and_b32_e32 v22, 0xffff0000, v22
	v_and_b32_e32 v23, 0xffff0000, v23
	v_mul_f32_e32 v44, v224, v44
	v_mul_f32_e32 v45, v226, v45
	v_mul_f32_e32 v46, v228, v46
	v_mul_f32_e32 v47, v230, v47
	v_mul_f32_e32 v20, v225, v20
	v_mul_f32_e32 v21, v227, v21
	v_mul_f32_e32 v22, v229, v22
	v_mul_f32_e32 v23, v231, v23
	v_cvt_pk_bf16_f32 v44, v44, v20
	v_cvt_pk_bf16_f32 v45, v45, v21
	v_cvt_pk_bf16_f32 v46, v46, v22
	v_cvt_pk_bf16_f32 v47, v47, v23
	v_lshlrev_b32_e32 v86, 16, v24
	v_lshlrev_b32_e32 v87, 16, v25
	v_lshlrev_b32_e32 v88, 16, v26
	v_lshlrev_b32_e32 v89, 16, v27
	v_and_b32_e32 v24, 0xffff0000, v24
	v_and_b32_e32 v25, 0xffff0000, v25
	v_and_b32_e32 v26, 0xffff0000, v26
	v_and_b32_e32 v27, 0xffff0000, v27
	v_mul_f32_e32 v86, v232, v86
	v_mul_f32_e32 v87, v234, v87
	v_mul_f32_e32 v88, v236, v88
	v_mul_f32_e32 v89, v238, v89
	v_mul_f32_e32 v24, v233, v24
	v_mul_f32_e32 v25, v235, v25
	v_mul_f32_e32 v26, v237, v26
	v_mul_f32_e32 v27, v239, v27
	v_cvt_pk_bf16_f32 v86, v86, v24
	v_cvt_pk_bf16_f32 v87, v87, v25
	v_cvt_pk_bf16_f32 v88, v88, v26
	v_cvt_pk_bf16_f32 v89, v89, v27
	s_nop 0
	v_mfma_f32_16x16x32_bf16 v[40:43], v[44:47], v[94:97], 0
	v_lshlrev_b32_e32 v44, 16, v28
	v_lshlrev_b32_e32 v45, 16, v29
	v_lshlrev_b32_e32 v46, 16, v30
	v_lshlrev_b32_e32 v47, 16, v31
	v_and_b32_e32 v28, 0xffff0000, v28
	v_and_b32_e32 v29, 0xffff0000, v29
	v_and_b32_e32 v30, 0xffff0000, v30
	v_and_b32_e32 v31, 0xffff0000, v31
	v_mul_f32_e32 v44, v240, v44
	v_mul_f32_e32 v45, v242, v45
	v_mul_f32_e32 v46, v244, v46
	v_mul_f32_e32 v47, v246, v47
	v_mul_f32_e32 v28, v241, v28
	v_mul_f32_e32 v29, v243, v29
	v_mul_f32_e32 v30, v245, v30
	v_mul_f32_e32 v31, v247, v31
	v_cvt_pk_bf16_f32 v44, v44, v28
	v_cvt_pk_bf16_f32 v45, v45, v29
	v_cvt_pk_bf16_f32 v46, v46, v30
	v_cvt_pk_bf16_f32 v47, v47, v31
	v_mfma_f32_16x16x32_bf16 v[40:43], v[86:89], v[98:101], v[40:43]
	v_lshlrev_b32_e32 v86, 16, v32
	v_lshlrev_b32_e32 v87, 16, v33
	v_lshlrev_b32_e32 v88, 16, v34
	v_lshlrev_b32_e32 v89, 16, v35
	v_and_b32_e32 v32, 0xffff0000, v32
	v_and_b32_e32 v33, 0xffff0000, v33
	v_and_b32_e32 v34, 0xffff0000, v34
	v_and_b32_e32 v35, 0xffff0000, v35
	v_mul_f32_e32 v86, v248, v86
	v_mul_f32_e32 v87, v250, v87
	v_mul_f32_e32 v88, v210, v88
	v_mul_f32_e32 v89, v212, v89
	v_mul_f32_e32 v32, v249, v32
	v_mul_f32_e32 v33, v251, v33
	v_mul_f32_e32 v34, v211, v34
	v_mul_f32_e32 v35, v213, v35
	v_cvt_pk_bf16_f32 v86, v86, v32
	v_cvt_pk_bf16_f32 v87, v87, v33
	v_cvt_pk_bf16_f32 v88, v88, v34
	v_cvt_pk_bf16_f32 v89, v89, v35
	v_mfma_f32_16x16x32_bf16 v[40:43], v[44:47], v[102:105], v[40:43]
	s_nop 1
	v_mfma_f32_16x16x32_bf16 v[40:43], v[86:89], v[106:109], v[40:43]
	s_add_u32 s8, s20, 0x8000
	s_addc_u32 s9, s21, 0
	v_cvt_pk_bf16_f32 v48, v36, v37
	v_cvt_pk_bf16_f32 v49, v38, v39
	global_store_dwordx2 v172, v[48:49], s[8:9]
	s_nop 7
	v_pk_fma_f32 v[36:37], v[90:91], v[36:37], v[40:41] op_sel_hi:[0,1,1]
	v_pk_fma_f32 v[38:39], v[90:91], v[38:39], v[42:43] op_sel_hi:[0,1,1]
	s_waitcnt vmcnt(2)
	v_lshlrev_b32_e32 v44, 16, v54
	v_lshlrev_b32_e32 v45, 16, v55
	v_lshlrev_b32_e32 v46, 16, v56
	v_lshlrev_b32_e32 v47, 16, v57
	v_and_b32_e32 v54, 0xffff0000, v54
	v_and_b32_e32 v55, 0xffff0000, v55
	v_and_b32_e32 v56, 0xffff0000, v56
	v_and_b32_e32 v57, 0xffff0000, v57
	v_mul_f32_e32 v44, v224, v44
	v_mul_f32_e32 v45, v226, v45
	v_mul_f32_e32 v46, v228, v46
	v_mul_f32_e32 v47, v230, v47
	v_mul_f32_e32 v54, v225, v54
	v_mul_f32_e32 v55, v227, v55
	v_mul_f32_e32 v56, v229, v56
	v_mul_f32_e32 v57, v231, v57
	v_cvt_pk_bf16_f32 v44, v44, v54
	v_cvt_pk_bf16_f32 v45, v45, v55
	v_cvt_pk_bf16_f32 v46, v46, v56
	v_cvt_pk_bf16_f32 v47, v47, v57
	v_lshlrev_b32_e32 v86, 16, v58
	v_lshlrev_b32_e32 v87, 16, v59
	v_lshlrev_b32_e32 v88, 16, v60
	v_lshlrev_b32_e32 v89, 16, v61
	v_and_b32_e32 v58, 0xffff0000, v58
	v_and_b32_e32 v59, 0xffff0000, v59
	v_and_b32_e32 v60, 0xffff0000, v60
	v_and_b32_e32 v61, 0xffff0000, v61
	v_mul_f32_e32 v86, v232, v86
	v_mul_f32_e32 v87, v234, v87
	v_mul_f32_e32 v88, v236, v88
	v_mul_f32_e32 v89, v238, v89
	v_mul_f32_e32 v58, v233, v58
	v_mul_f32_e32 v59, v235, v59
	v_mul_f32_e32 v60, v237, v60
	v_mul_f32_e32 v61, v239, v61
	v_cvt_pk_bf16_f32 v86, v86, v58
	v_cvt_pk_bf16_f32 v87, v87, v59
	v_cvt_pk_bf16_f32 v88, v88, v60
	v_cvt_pk_bf16_f32 v89, v89, v61
	s_nop 0
	v_mfma_f32_16x16x32_bf16 v[40:43], v[44:47], v[110:113], 0
	v_lshlrev_b32_e32 v44, 16, v62
	v_lshlrev_b32_e32 v45, 16, v63
	v_lshlrev_b32_e32 v46, 16, v64
	v_lshlrev_b32_e32 v47, 16, v65
	v_and_b32_e32 v62, 0xffff0000, v62
	v_and_b32_e32 v63, 0xffff0000, v63
	v_and_b32_e32 v64, 0xffff0000, v64
	v_and_b32_e32 v65, 0xffff0000, v65
	v_mul_f32_e32 v44, v240, v44
	v_mul_f32_e32 v45, v242, v45
	v_mul_f32_e32 v46, v244, v46
	v_mul_f32_e32 v47, v246, v47
	v_mul_f32_e32 v62, v241, v62
	v_mul_f32_e32 v63, v243, v63
	v_mul_f32_e32 v64, v245, v64
	v_mul_f32_e32 v65, v247, v65
	v_cvt_pk_bf16_f32 v44, v44, v62
	v_cvt_pk_bf16_f32 v45, v45, v63
	v_cvt_pk_bf16_f32 v46, v46, v64
	v_cvt_pk_bf16_f32 v47, v47, v65
	v_mfma_f32_16x16x32_bf16 v[40:43], v[86:89], v[114:117], v[40:43]
	v_lshlrev_b32_e32 v86, 16, v66
	v_lshlrev_b32_e32 v87, 16, v67
	v_lshlrev_b32_e32 v88, 16, v68
	v_lshlrev_b32_e32 v89, 16, v69
	v_and_b32_e32 v66, 0xffff0000, v66
	v_and_b32_e32 v67, 0xffff0000, v67
	v_and_b32_e32 v68, 0xffff0000, v68
	v_and_b32_e32 v69, 0xffff0000, v69
	v_mul_f32_e32 v86, v248, v86
	v_mul_f32_e32 v87, v250, v87
	v_mul_f32_e32 v88, v210, v88
	v_mul_f32_e32 v89, v212, v89
	v_mul_f32_e32 v66, v249, v66
	v_mul_f32_e32 v67, v251, v67
	v_mul_f32_e32 v68, v211, v68
	v_mul_f32_e32 v69, v213, v69
	v_cvt_pk_bf16_f32 v86, v86, v66
	v_cvt_pk_bf16_f32 v87, v87, v67
	v_cvt_pk_bf16_f32 v88, v88, v68
	v_cvt_pk_bf16_f32 v89, v89, v69
	v_mfma_f32_16x16x32_bf16 v[40:43], v[44:47], v[118:121], v[40:43]
	s_nop 1
	v_mfma_f32_16x16x32_bf16 v[40:43], v[86:89], v[122:125], v[40:43]
	s_add_u32 s8, s20, 0x0
	s_addc_u32 s9, s21, 0
	v_cvt_pk_bf16_f32 v48, v36, v37
	v_cvt_pk_bf16_f32 v49, v38, v39
	global_store_dwordx2 v172, v[48:49], s[8:9]
	s_nop 7
	v_pk_fma_f32 v[36:37], v[90:91], v[36:37], v[40:41] op_sel_hi:[0,1,1]
	v_pk_fma_f32 v[38:39], v[90:91], v[38:39], v[42:43] op_sel_hi:[0,1,1]
	v_mov_b32_e32 v246, v219
	s_add_i32 s1, s1, s42
	s_add_i32 s0, s0, s97
	s_cmpk_gt_i32 s1, 0xff
	s_cbranch_scc0 .LBB0_113
; __device__ __forceinline__ unsigned cvt_pk_bf16(float lo, float hi) { unsigned r; asm("v_cvt_pk_bf16_f32 %0, %1, %2" : "=v"(r) : "v"(lo), "v"(hi)); return r; }
; __device__ __forceinline__ float bf2f(unsigned b) { return __uint_as_float(b << 16); }
; __device__ __forceinline__ void r1s_phase(KP p, int G, int bid, int wv) {
;     ...
;     const bf16_t* pr = (const bf16_t*)(ws + WS_PR); bf16_t* Y = (bf16_t*)(ws + WS_Y); const float* wc = p->in[16];
;     for (int e = bid * 512 + tid; e < MLAT * 128; e += G * 512) {
;         const int row = e >> 7, c8 = (e & 127) * 8, t = row & (SEQ - 1);
;         const bf16_t* rp = pr + (size_t)row * 4096;
;         const u32x4 bg = *(const u32x4*)(rp + 1024 + c8);
;         const u32x4 c1 = *(const u32x4*)(rp + 2048 + c8), u1 = *(const u32x4*)(rp + 3072 + c8);
;         u32x4 c0 = {0, 0, 0, 0}, u0 = {0, 0, 0, 0}, c2 = {0, 0, 0, 0}, u2 = {0, 0, 0, 0};
;         if (t > 0) { c0 = *(const u32x4*)(rp - 4096 + 2048 + c8); u0 = *(const u32x4*)(rp - 4096 + 3072 + c8); }
;         if (t < SEQ - 1) { c2 = *(const u32x4*)(rp + 4096 + 2048 + c8); u2 = *(const u32x4*)(rp + 4096 + 3072 + c8); }
;         float o[8];
; #pragma unroll
;         for (int i = 0; i < 4; ++i) {
; #pragma unroll
;             for (int hh = 0; hh < 2; ++hh) {
;                 const int sh = hh * 16, ch = c8 + 2 * i + hh;
;                 const float m0 = bf2f((c0[i] >> sh) & 0xffffu) * bf2f((u0[i] >> sh) & 0xffffu);
;                 const float m1 = bf2f((c1[i] >> sh) & 0xffffu) * bf2f((u1[i] >> sh) & 0xffffu);
;                 const float m2 = bf2f((c2[i] >> sh) & 0xffffu) * bf2f((u2[i] >> sh) & 0xffffu);
;                 o[2 * i + hh] = bf2f((bg[i] >> sh) & 0xffffu) * (m0 * wc[ch] + m1 * wc[1024 + ch] + m2 * wc[2048 + ch]);
;             }
;         }
;         u32x4 w; w.x = cvt_pk_bf16(o[0], o[1]); w.y = cvt_pk_bf16(o[2], o[3]); w.z = cvt_pk_bf16(o[4], o[5]); w.w = cvt_pk_bf16(o[6], o[7]);
;         *(u32x4*)(Y + (size_t)row * DM + 1024 + c8) = w;
;     }
.LBB0_114:
	v_add_u32_e32 v44, s60, v93
	s_mov_b32 s0, 0x100000
	v_cmp_gt_i32_e32 vcc, s0, v44
	s_mov_b64 s[2:3], exec
	v_readlane_b32 s36, v253, 39
	v_readlane_b32 s12, v254, 35
	s_and_b64 s[0:1], s[2:3], vcc
	v_readlane_b32 s37, v253, 40
	s_mov_b64 s[10:11], 0x2000
	v_readlane_b32 s13, v254, 36
	v_mov_b32_e32 v247, v252
	s_mov_b64 exec, s[0:1]
	s_cbranch_execz .LBB0_121
	s_load_dwordx2 s[4:5], s[78:79], 0x80
	v_lshrrev_b32_e32 v118, 7, v93
	v_and_b32_e32 v119, 0x7f, v93
	v_lshlrev_b32_e32 v86, 4, v119
	v_lshlrev_b32_e32 v87, 5, v119
	v_readfirstlane_b32 s8, v118
	s_lshl_b32 s9, s33, 5
	s_lshl_b32 s8, s8, 3
	s_add_i32 s8, s8, s9
	s_and_b32 s9, s8, 0x7ff
	s_lshl_b32 s10, s8, 13
	s_add_u32 s16, s80, s10
	s_addc_u32 s17, s81, 0
	s_add_u32 s16, s16, 0x242b5000
	s_addc_u32 s17, s17, 0
	s_lshl_b32 s10, s8, 12
	s_add_u32 s18, s80, s10
	s_addc_u32 s19, s81, 0
	s_add_u32 s18, s18, 0x2eab4800
	s_addc_u32 s19, s19, 0
	s_waitcnt lgkmcnt(0)
	global_load_dwordx4 v[2:5], v87, s[4:5]
	global_load_dwordx4 v[6:9], v87, s[4:5] offset:16
	s_add_u32 s10, s4, 0x1000
	s_addc_u32 s11, s5, 0
	global_load_dwordx4 v[10:13], v87, s[10:11]
	global_load_dwordx4 v[14:17], v87, s[10:11] offset:16
	s_add_u32 s10, s4, 0x2000
	s_addc_u32 s11, s5, 0
	global_load_dwordx4 v[18:21], v87, s[10:11]
	global_load_dwordx4 v[22:25], v87, s[10:11] offset:16
	s_sub_u32 s10, s16, 0x2000
	s_subb_u32 s11, s17, 0
	global_load_dwordx4 v[26:29], v86, s[10:11]
	global_load_dwordx4 v[30:33], v86, s[10:11] offset:2048
	s_add_u32 s10, s16, 0x0
	s_addc_u32 s11, s17, 0
	global_load_dwordx4 v[34:37], v86, s[10:11]
	global_load_dwordx4 v[38:41], v86, s[10:11] offset:2048
	global_load_dwordx4 v[62:65], v86, s[10:11] offset:-2048
	s_add_u32 s10, s16, 0x2000
	s_addc_u32 s11, s17, 0
	global_load_dwordx4 v[42:45], v86, s[10:11]
	global_load_dwordx4 v[46:49], v86, s[10:11] offset:2048
	global_load_dwordx4 v[66:69], v86, s[10:11] offset:-2048
	s_add_u32 s10, s16, 0x4000
	s_addc_u32 s11, s17, 0
	global_load_dwordx4 v[54:57], v86, s[10:11]
	global_load_dwordx4 v[58:61], v86, s[10:11] offset:2048
	global_load_dwordx4 v[70:73], v86, s[10:11] offset:-2048
	s_waitcnt vmcnt(11)
	s_cmp_eq_u32 s9, 0
	s_waitcnt vmcnt(9)
	s_cbranch_scc1 .Lgc_zero_1
	v_lshlrev_b32_e32 v118, 16, v26
	v_lshlrev_b32_e32 v119, 16, v30
	v_mul_f32_e32 v94, v118, v119
	v_and_b32_e32 v26, 0xffff0000, v26
	v_and_b32_e32 v30, 0xffff0000, v30
	v_mul_f32_e32 v95, v26, v30
	v_lshlrev_b32_e32 v118, 16, v27
	v_lshlrev_b32_e32 v119, 16, v31
	v_mul_f32_e32 v96, v118, v119
	v_and_b32_e32 v27, 0xffff0000, v27
	v_and_b32_e32 v31, 0xffff0000, v31
	v_mul_f32_e32 v97, v27, v31
	v_lshlrev_b32_e32 v118, 16, v28
	v_lshlrev_b32_e32 v119, 16, v32
	v_mul_f32_e32 v98, v118, v119
	v_and_b32_e32 v28, 0xffff0000, v28
	v_and_b32_e32 v32, 0xffff0000, v32
	v_mul_f32_e32 v99, v28, v32
	v_lshlrev_b32_e32 v118, 16, v29
	v_lshlrev_b32_e32 v119, 16, v33
	v_mul_f32_e32 v100, v118, v119
	v_and_b32_e32 v29, 0xffff0000, v29
	v_and_b32_e32 v33, 0xffff0000, v33
	v_mul_f32_e32 v101, v29, v33
	s_branch .Lgc_done_1
.Lgc_zero_1:
	v_mov_b32_e32 v94, 0
	v_mov_b32_e32 v95, 0
	v_mov_b32_e32 v96, 0
	v_mov_b32_e32 v97, 0
	v_mov_b32_e32 v98, 0
	v_mov_b32_e32 v99, 0
	v_mov_b32_e32 v100, 0
	v_mov_b32_e32 v101, 0
.Lgc_done_1:
	s_waitcnt vmcnt(7)
	v_lshlrev_b32_e32 v118, 16, v34
	v_lshlrev_b32_e32 v119, 16, v38
	v_mul_f32_e32 v102, v118, v119
	v_and_b32_e32 v34, 0xffff0000, v34
	v_and_b32_e32 v38, 0xffff0000, v38
	v_mul_f32_e32 v103, v34, v38
	v_lshlrev_b32_e32 v118, 16, v35
	v_lshlrev_b32_e32 v119, 16, v39
	v_mul_f32_e32 v104, v118, v119
	v_and_b32_e32 v35, 0xffff0000, v35
	v_and_b32_e32 v39, 0xffff0000, v39
	v_mul_f32_e32 v105, v35, v39
	v_lshlrev_b32_e32 v118, 16, v36
	v_lshlrev_b32_e32 v119, 16, v40
	v_mul_f32_e32 v106, v118, v119
	v_and_b32_e32 v36, 0xffff0000, v36
	v_and_b32_e32 v40, 0xffff0000, v40
	v_mul_f32_e32 v107, v36, v40
	v_lshlrev_b32_e32 v118, 16, v37
	v_lshlrev_b32_e32 v119, 16, v41
	v_mul_f32_e32 v108, v118, v119
	v_and_b32_e32 v37, 0xffff0000, v37
	v_and_b32_e32 v41, 0xffff0000, v41
	v_mul_f32_e32 v109, v37, v41
	s_add_u32 s10, s16, 0x6000
	s_addc_u32 s11, s17, 0
	global_load_dwordx4 v[26:29], v86, s[10:11]
	global_load_dwordx4 v[30:33], v86, s[10:11] offset:2048
	global_load_dwordx4 v[74:77], v86, s[10:11] offset:-2048
	s_waitcnt vmcnt(7)
	v_lshlrev_b32_e32 v118, 16, v42
	v_lshlrev_b32_e32 v119, 16, v46
	v_mul_f32_e32 v110, v118, v119
	v_and_b32_e32 v42, 0xffff0000, v42
	v_and_b32_e32 v46, 0xffff0000, v46
	v_mul_f32_e32 v111, v42, v46
	v_lshlrev_b32_e32 v118, 16, v43
	v_lshlrev_b32_e32 v119, 16, v47
	v_mul_f32_e32 v112, v118, v119
	v_and_b32_e32 v43, 0xffff0000, v43
	v_and_b32_e32 v47, 0xffff0000, v47
	v_mul_f32_e32 v113, v43, v47
	v_lshlrev_b32_e32 v118, 16, v44
	v_lshlrev_b32_e32 v119, 16, v48
	v_mul_f32_e32 v114, v118, v119
	v_and_b32_e32 v44, 0xffff0000, v44
	v_and_b32_e32 v48, 0xffff0000, v48
	v_mul_f32_e32 v115, v44, v48
	v_lshlrev_b32_e32 v118, 16, v45
	v_lshlrev_b32_e32 v119, 16, v49
	v_mul_f32_e32 v116, v118, v119
	v_and_b32_e32 v45, 0xffff0000, v45
	v_and_b32_e32 v49, 0xffff0000, v49
	v_mul_f32_e32 v117, v45, v49
	s_waitcnt vmcnt(9)
; __device__ __forceinline__ unsigned cvt_pk_bf16(float lo, float hi) { unsigned r; asm("v_cvt_pk_bf16_f32 %0, %1, %2" : "=v"(r) : "v"(lo), "v"(hi)); return r; }
; __device__ __forceinline__ float bf2f(unsigned b) { return __uint_as_float(b << 16); }
; __device__ __forceinline__ void r1s_phase(KP p, int G, int bid, int wv) {
;     ...
;         float o[8];
; #pragma unroll
;         for (int i = 0; i < 4; ++i) {
; #pragma unroll
;             for (int hh = 0; hh < 2; ++hh) {
;                 const int sh = hh * 16, ch = c8 + 2 * i + hh;
;                 const float m0 = bf2f((c0[i] >> sh) & 0xffffu) * bf2f((u0[i] >> sh) & 0xffffu);
;                 const float m1 = bf2f((c1[i] >> sh) & 0xffffu) * bf2f((u1[i] >> sh) & 0xffffu);
;                 const float m2 = bf2f((c2[i] >> sh) & 0xffffu) * bf2f((u2[i] >> sh) & 0xffffu);
;                 o[2 * i + hh] = bf2f((bg[i] >> sh) & 0xffffu) * (m0 * wc[ch] + m1 * wc[1024 + ch] + m2 * wc[2048 + ch]);
;             }
;         }
;         u32x4 w; w.x = cvt_pk_bf16(o[0], o[1]); w.y = cvt_pk_bf16(o[2], o[3]); w.z = cvt_pk_bf16(o[4], o[5]); w.w = cvt_pk_bf16(o[6], o[7]);
;         *(u32x4*)(Y + (size_t)row * DM + 1024 + c8) = w;
	v_mul_f32_e32 v78, v94, v2
	v_mul_f32_e32 v118, v110, v18
	v_fma_f32 v78, v102, v10, v78
	v_add_f32_e32 v78, v78, v118
	v_lshlrev_b32_e32 v119, 16, v62
	v_mul_f32_e32 v78, v78, v119
	v_mul_f32_e32 v79, v95, v3
	v_mul_f32_e32 v118, v111, v19
	v_fma_f32 v79, v103, v11, v79
	v_add_f32_e32 v79, v79, v118
	v_and_b32_e32 v119, 0xffff0000, v62
	v_mul_f32_e32 v79, v79, v119
	v_mul_f32_e32 v80, v96, v4
	v_mul_f32_e32 v118, v112, v20
	v_fma_f32 v80, v104, v12, v80
	v_add_f32_e32 v80, v80, v118
	v_lshlrev_b32_e32 v119, 16, v63
	v_mul_f32_e32 v80, v80, v119
	v_mul_f32_e32 v81, v97, v5
	v_mul_f32_e32 v118, v113, v21
	v_fma_f32 v81, v105, v13, v81
	v_add_f32_e32 v81, v81, v118
	v_and_b32_e32 v119, 0xffff0000, v63
	v_mul_f32_e32 v81, v81, v119
	v_mul_f32_e32 v82, v98, v6
	v_mul_f32_e32 v118, v114, v22
	v_fma_f32 v82, v106, v14, v82
	v_add_f32_e32 v82, v82, v118
	v_lshlrev_b32_e32 v119, 16, v64
	v_mul_f32_e32 v82, v82, v119
	v_mul_f32_e32 v83, v99, v7
	v_mul_f32_e32 v118, v115, v23
	v_fma_f32 v83, v107, v15, v83
	v_add_f32_e32 v83, v83, v118
	v_and_b32_e32 v119, 0xffff0000, v64
	v_mul_f32_e32 v83, v83, v119
	v_mul_f32_e32 v84, v100, v8
	v_mul_f32_e32 v118, v116, v24
	v_fma_f32 v84, v108, v16, v84
	v_add_f32_e32 v84, v84, v118
	v_lshlrev_b32_e32 v119, 16, v65
	v_mul_f32_e32 v84, v84, v119
	v_mul_f32_e32 v85, v101, v9
	v_mul_f32_e32 v118, v117, v25
	v_fma_f32 v85, v109, v17, v85
	v_add_f32_e32 v85, v85, v118
	v_and_b32_e32 v119, 0xffff0000, v65
	v_mul_f32_e32 v85, v85, v119
	v_cvt_pk_bf16_f32 v120, v78, v79
	v_cvt_pk_bf16_f32 v121, v80, v81
	v_cvt_pk_bf16_f32 v122, v82, v83
	v_cvt_pk_bf16_f32 v123, v84, v85
	global_store_dwordx4 v86, v[120:123], s[18:19]
	s_add_u32 s10, s16, 0x8000
	s_addc_u32 s11, s17, 0
	global_load_dwordx4 v[34:37], v86, s[10:11]
	global_load_dwordx4 v[38:41], v86, s[10:11] offset:2048
	global_load_dwordx4 v[62:65], v86, s[10:11] offset:-2048
	s_waitcnt vmcnt(8)
	v_lshlrev_b32_e32 v118, 16, v54
	v_lshlrev_b32_e32 v119, 16, v58
	v_mul_f32_e32 v94, v118, v119
	v_and_b32_e32 v54, 0xffff0000, v54
	v_and_b32_e32 v58, 0xffff0000, v58
	v_mul_f32_e32 v95, v54, v58
	v_lshlrev_b32_e32 v118, 16, v55
	v_lshlrev_b32_e32 v119, 16, v59
	v_mul_f32_e32 v96, v118, v119
	v_and_b32_e32 v55, 0xffff0000, v55
	v_and_b32_e32 v59, 0xffff0000, v59
	v_mul_f32_e32 v97, v55, v59
	v_lshlrev_b32_e32 v118, 16, v56
	v_lshlrev_b32_e32 v119, 16, v60
	v_mul_f32_e32 v98, v118, v119
	v_and_b32_e32 v56, 0xffff0000, v56
	v_and_b32_e32 v60, 0xffff0000, v60
	v_mul_f32_e32 v99, v56, v60
	v_lshlrev_b32_e32 v118, 16, v57
	v_lshlrev_b32_e32 v119, 16, v61
	v_mul_f32_e32 v100, v118, v119
	v_and_b32_e32 v57, 0xffff0000, v57
	v_and_b32_e32 v61, 0xffff0000, v61
	v_mul_f32_e32 v101, v57, v61
	s_waitcnt vmcnt(10)
	v_mul_f32_e32 v78, v102, v2
	v_mul_f32_e32 v118, v94, v18
	v_fma_f32 v78, v110, v10, v78
	v_add_f32_e32 v78, v78, v118
	v_lshlrev_b32_e32 v119, 16, v66
	v_mul_f32_e32 v78, v78, v119
	v_mul_f32_e32 v79, v103, v3
	v_mul_f32_e32 v118, v95, v19
	v_fma_f32 v79, v111, v11, v79
	v_add_f32_e32 v79, v79, v118
	v_and_b32_e32 v119, 0xffff0000, v66
	v_mul_f32_e32 v79, v79, v119
	v_mul_f32_e32 v80, v104, v4
	v_mul_f32_e32 v118, v96, v20
	v_fma_f32 v80, v112, v12, v80
	v_add_f32_e32 v80, v80, v118
	v_lshlrev_b32_e32 v119, 16, v67
	v_mul_f32_e32 v80, v80, v119
	v_mul_f32_e32 v81, v105, v5
	v_mul_f32_e32 v118, v97, v21
	v_fma_f32 v81, v113, v13, v81
	v_add_f32_e32 v81, v81, v118
	v_and_b32_e32 v119, 0xffff0000, v67
	v_mul_f32_e32 v81, v81, v119
	v_mul_f32_e32 v82, v106, v6
	v_mul_f32_e32 v118, v98, v22
	v_fma_f32 v82, v114, v14, v82
	v_add_f32_e32 v82, v82, v118
	v_lshlrev_b32_e32 v119, 16, v68
	v_mul_f32_e32 v82, v82, v119
	v_mul_f32_e32 v83, v107, v7
	v_mul_f32_e32 v118, v99, v23
	v_fma_f32 v83, v115, v15, v83
	v_add_f32_e32 v83, v83, v118
	v_and_b32_e32 v119, 0xffff0000, v68
	v_mul_f32_e32 v83, v83, v119
	v_mul_f32_e32 v84, v108, v8
	v_mul_f32_e32 v118, v100, v24
	v_fma_f32 v84, v116, v16, v84
	v_add_f32_e32 v84, v84, v118
	v_lshlrev_b32_e32 v119, 16, v69
	v_mul_f32_e32 v84, v84, v119
	v_mul_f32_e32 v85, v109, v9
	v_mul_f32_e32 v118, v101, v25
	v_fma_f32 v85, v117, v17, v85
	v_add_f32_e32 v85, v85, v118
	v_and_b32_e32 v119, 0xffff0000, v69
	v_mul_f32_e32 v85, v85, v119
	v_cvt_pk_bf16_f32 v120, v78, v79
	v_cvt_pk_bf16_f32 v121, v80, v81
	v_cvt_pk_bf16_f32 v122, v82, v83
	v_cvt_pk_bf16_f32 v123, v84, v85
	s_add_u32 s10, s18, 0x1000
	s_addc_u32 s11, s19, 0
	global_store_dwordx4 v86, v[120:123], s[10:11]
	s_add_u32 s10, s16, 0xa000
	s_addc_u32 s11, s17, 0
	global_load_dwordx4 v[42:45], v86, s[10:11]
	global_load_dwordx4 v[46:49], v86, s[10:11] offset:2048
	global_load_dwordx4 v[66:69], v86, s[10:11] offset:-2048
	s_waitcnt vmcnt(9)
	v_lshlrev_b32_e32 v118, 16, v26
	v_lshlrev_b32_e32 v119, 16, v30
	v_mul_f32_e32 v102, v118, v119
	v_and_b32_e32 v26, 0xffff0000, v26
	v_and_b32_e32 v30, 0xffff0000, v30
	v_mul_f32_e32 v103, v26, v30
	v_lshlrev_b32_e32 v118, 16, v27
	v_lshlrev_b32_e32 v119, 16, v31
	v_mul_f32_e32 v104, v118, v119
	v_and_b32_e32 v27, 0xffff0000, v27
	v_and_b32_e32 v31, 0xffff0000, v31
	v_mul_f32_e32 v105, v27, v31
	v_lshlrev_b32_e32 v118, 16, v28
	v_lshlrev_b32_e32 v119, 16, v32
	v_mul_f32_e32 v106, v118, v119
	v_and_b32_e32 v28, 0xffff0000, v28
	v_and_b32_e32 v32, 0xffff0000, v32
	v_mul_f32_e32 v107, v28, v32
	v_lshlrev_b32_e32 v118, 16, v29
	v_lshlrev_b32_e32 v119, 16, v33
	v_mul_f32_e32 v108, v118, v119
	v_and_b32_e32 v29, 0xffff0000, v29
	v_and_b32_e32 v33, 0xffff0000, v33
	v_mul_f32_e32 v109, v29, v33
	s_waitcnt vmcnt(11)
; __device__ __forceinline__ unsigned cvt_pk_bf16(float lo, float hi) { unsigned r; asm("v_cvt_pk_bf16_f32 %0, %1, %2" : "=v"(r) : "v"(lo), "v"(hi)); return r; }
; __device__ __forceinline__ float bf2f(unsigned b) { return __uint_as_float(b << 16); }
; __device__ __forceinline__ void r1s_phase(KP p, int G, int bid, int wv) {
;     ...
;         float o[8];
; #pragma unroll
;         for (int i = 0; i < 4; ++i) {
; #pragma unroll
;             for (int hh = 0; hh < 2; ++hh) {
;                 const int sh = hh * 16, ch = c8 + 2 * i + hh;
;                 const float m0 = bf2f((c0[i] >> sh) & 0xffffu) * bf2f((u0[i] >> sh) & 0xffffu);
;                 const float m1 = bf2f((c1[i] >> sh) & 0xffffu) * bf2f((u1[i] >> sh) & 0xffffu);
;                 const float m2 = bf2f((c2[i] >> sh) & 0xffffu) * bf2f((u2[i] >> sh) & 0xffffu);
;                 o[2 * i + hh] = bf2f((bg[i] >> sh) & 0xffffu) * (m0 * wc[ch] + m1 * wc[1024 + ch] + m2 * wc[2048 + ch]);
;             }
;         }
;         u32x4 w; w.x = cvt_pk_bf16(o[0], o[1]); w.y = cvt_pk_bf16(o[2], o[3]); w.z = cvt_pk_bf16(o[4], o[5]); w.w = cvt_pk_bf16(o[6], o[7]);
;         *(u32x4*)(Y + (size_t)row * DM + 1024 + c8) = w;
	v_mul_f32_e32 v78, v110, v2
	v_mul_f32_e32 v118, v102, v18
	v_fma_f32 v78, v94, v10, v78
	v_add_f32_e32 v78, v78, v118
	v_lshlrev_b32_e32 v119, 16, v70
	v_mul_f32_e32 v78, v78, v119
	v_mul_f32_e32 v79, v111, v3
	v_mul_f32_e32 v118, v103, v19
	v_fma_f32 v79, v95, v11, v79
	v_add_f32_e32 v79, v79, v118
	v_and_b32_e32 v119, 0xffff0000, v70
	v_mul_f32_e32 v79, v79, v119
	v_mul_f32_e32 v80, v112, v4
	v_mul_f32_e32 v118, v104, v20
	v_fma_f32 v80, v96, v12, v80
	v_add_f32_e32 v80, v80, v118
	v_lshlrev_b32_e32 v119, 16, v71
	v_mul_f32_e32 v80, v80, v119
	v_mul_f32_e32 v81, v113, v5
	v_mul_f32_e32 v118, v105, v21
	v_fma_f32 v81, v97, v13, v81
	v_add_f32_e32 v81, v81, v118
	v_and_b32_e32 v119, 0xffff0000, v71
	v_mul_f32_e32 v81, v81, v119
	v_mul_f32_e32 v82, v114, v6
	v_mul_f32_e32 v118, v106, v22
	v_fma_f32 v82, v98, v14, v82
	v_add_f32_e32 v82, v82, v118
	v_lshlrev_b32_e32 v119, 16, v72
	v_mul_f32_e32 v82, v82, v119
	v_mul_f32_e32 v83, v115, v7
	v_mul_f32_e32 v118, v107, v23
	v_fma_f32 v83, v99, v15, v83
	v_add_f32_e32 v83, v83, v118
	v_and_b32_e32 v119, 0xffff0000, v72
	v_mul_f32_e32 v83, v83, v119
	v_mul_f32_e32 v84, v116, v8
	v_mul_f32_e32 v118, v108, v24
	v_fma_f32 v84, v100, v16, v84
	v_add_f32_e32 v84, v84, v118
	v_lshlrev_b32_e32 v119, 16, v73
	v_mul_f32_e32 v84, v84, v119
	v_mul_f32_e32 v85, v117, v9
	v_mul_f32_e32 v118, v109, v25
	v_fma_f32 v85, v101, v17, v85
	v_add_f32_e32 v85, v85, v118
	v_and_b32_e32 v119, 0xffff0000, v73
	v_mul_f32_e32 v85, v85, v119
	v_cvt_pk_bf16_f32 v120, v78, v79
	v_cvt_pk_bf16_f32 v121, v80, v81
	v_cvt_pk_bf16_f32 v122, v82, v83
	v_cvt_pk_bf16_f32 v123, v84, v85
	s_add_u32 s10, s18, 0x2000
	s_addc_u32 s11, s19, 0
	global_store_dwordx4 v86, v[120:123], s[10:11]
	s_add_u32 s10, s16, 0xc000
	s_addc_u32 s11, s17, 0
	global_load_dwordx4 v[54:57], v86, s[10:11]
	global_load_dwordx4 v[58:61], v86, s[10:11] offset:2048
	global_load_dwordx4 v[70:73], v86, s[10:11] offset:-2048
	s_waitcnt vmcnt(9)
	v_lshlrev_b32_e32 v118, 16, v34
	v_lshlrev_b32_e32 v119, 16, v38
	v_mul_f32_e32 v110, v118, v119
	v_and_b32_e32 v34, 0xffff0000, v34
	v_and_b32_e32 v38, 0xffff0000, v38
	v_mul_f32_e32 v111, v34, v38
	v_lshlrev_b32_e32 v118, 16, v35
	v_lshlrev_b32_e32 v119, 16, v39
	v_mul_f32_e32 v112, v118, v119
	v_and_b32_e32 v35, 0xffff0000, v35
	v_and_b32_e32 v39, 0xffff0000, v39
	v_mul_f32_e32 v113, v35, v39
	v_lshlrev_b32_e32 v118, 16, v36
	v_lshlrev_b32_e32 v119, 16, v40
	v_mul_f32_e32 v114, v118, v119
	v_and_b32_e32 v36, 0xffff0000, v36
	v_and_b32_e32 v40, 0xffff0000, v40
	v_mul_f32_e32 v115, v36, v40
	v_lshlrev_b32_e32 v118, 16, v37
	v_lshlrev_b32_e32 v119, 16, v41
	v_mul_f32_e32 v116, v118, v119
	v_and_b32_e32 v37, 0xffff0000, v37
	v_and_b32_e32 v41, 0xffff0000, v41
	v_mul_f32_e32 v117, v37, v41
	s_waitcnt vmcnt(12)
	v_mul_f32_e32 v78, v94, v2
	v_mul_f32_e32 v118, v110, v18
	v_fma_f32 v78, v102, v10, v78
	v_add_f32_e32 v78, v78, v118
	v_lshlrev_b32_e32 v119, 16, v74
	v_mul_f32_e32 v78, v78, v119
	v_mul_f32_e32 v79, v95, v3
	v_mul_f32_e32 v118, v111, v19
	v_fma_f32 v79, v103, v11, v79
	v_add_f32_e32 v79, v79, v118
	v_and_b32_e32 v119, 0xffff0000, v74
	v_mul_f32_e32 v79, v79, v119
	v_mul_f32_e32 v80, v96, v4
	v_mul_f32_e32 v118, v112, v20
	v_fma_f32 v80, v104, v12, v80
	v_add_f32_e32 v80, v80, v118
	v_lshlrev_b32_e32 v119, 16, v75
	v_mul_f32_e32 v80, v80, v119
	v_mul_f32_e32 v81, v97, v5
	v_mul_f32_e32 v118, v113, v21
	v_fma_f32 v81, v105, v13, v81
	v_add_f32_e32 v81, v81, v118
	v_and_b32_e32 v119, 0xffff0000, v75
	v_mul_f32_e32 v81, v81, v119
	v_mul_f32_e32 v82, v98, v6
	v_mul_f32_e32 v118, v114, v22
	v_fma_f32 v82, v106, v14, v82
	v_add_f32_e32 v82, v82, v118
	v_lshlrev_b32_e32 v119, 16, v76
	v_mul_f32_e32 v82, v82, v119
	v_mul_f32_e32 v83, v99, v7
	v_mul_f32_e32 v118, v115, v23
	v_fma_f32 v83, v107, v15, v83
	v_add_f32_e32 v83, v83, v118
	v_and_b32_e32 v119, 0xffff0000, v76
	v_mul_f32_e32 v83, v83, v119
	v_mul_f32_e32 v84, v100, v8
	v_mul_f32_e32 v118, v116, v24
	v_fma_f32 v84, v108, v16, v84
	v_add_f32_e32 v84, v84, v118
	v_lshlrev_b32_e32 v119, 16, v77
	v_mul_f32_e32 v84, v84, v119
	v_mul_f32_e32 v85, v101, v9
	v_mul_f32_e32 v118, v117, v25
	v_fma_f32 v85, v109, v17, v85
	v_add_f32_e32 v85, v85, v118
	v_and_b32_e32 v119, 0xffff0000, v77
	v_mul_f32_e32 v85, v85, v119
	v_cvt_pk_bf16_f32 v120, v78, v79
	v_cvt_pk_bf16_f32 v121, v80, v81
	v_cvt_pk_bf16_f32 v122, v82, v83
	v_cvt_pk_bf16_f32 v123, v84, v85
	s_add_u32 s10, s18, 0x3000
	s_addc_u32 s11, s19, 0
	global_store_dwordx4 v86, v[120:123], s[10:11]
	s_add_u32 s10, s16, 0xe000
	s_addc_u32 s11, s17, 0
	global_load_dwordx4 v[26:29], v86, s[10:11]
	global_load_dwordx4 v[30:33], v86, s[10:11] offset:2048
	global_load_dwordx4 v[74:77], v86, s[10:11] offset:-2048
	s_waitcnt vmcnt(9)
	v_lshlrev_b32_e32 v118, 16, v42
	v_lshlrev_b32_e32 v119, 16, v46
	v_mul_f32_e32 v94, v118, v119
	v_and_b32_e32 v42, 0xffff0000, v42
	v_and_b32_e32 v46, 0xffff0000, v46
	v_mul_f32_e32 v95, v42, v46
	v_lshlrev_b32_e32 v118, 16, v43
	v_lshlrev_b32_e32 v119, 16, v47
	v_mul_f32_e32 v96, v118, v119
	v_and_b32_e32 v43, 0xffff0000, v43
	v_and_b32_e32 v47, 0xffff0000, v47
	v_mul_f32_e32 v97, v43, v47
	v_lshlrev_b32_e32 v118, 16, v44
	v_lshlrev_b32_e32 v119, 16, v48
	v_mul_f32_e32 v98, v118, v119
	v_and_b32_e32 v44, 0xffff0000, v44
	v_and_b32_e32 v48, 0xffff0000, v48
	v_mul_f32_e32 v99, v44, v48
	v_lshlrev_b32_e32 v118, 16, v45
	v_lshlrev_b32_e32 v119, 16, v49
	v_mul_f32_e32 v100, v118, v119
	v_and_b32_e32 v45, 0xffff0000, v45
	v_and_b32_e32 v49, 0xffff0000, v49
	v_mul_f32_e32 v101, v45, v49
	s_waitcnt vmcnt(12)
; __device__ __forceinline__ unsigned cvt_pk_bf16(float lo, float hi) { unsigned r; asm("v_cvt_pk_bf16_f32 %0, %1, %2" : "=v"(r) : "v"(lo), "v"(hi)); return r; }
; __device__ __forceinline__ float bf2f(unsigned b) { return __uint_as_float(b << 16); }
; __device__ __forceinline__ void r1s_phase(KP p, int G, int bid, int wv) {
;     ...
;         float o[8];
; #pragma unroll
;         for (int i = 0; i < 4; ++i) {
; #pragma unroll
;             for (int hh = 0; hh < 2; ++hh) {
;                 const int sh = hh * 16, ch = c8 + 2 * i + hh;
;                 const float m0 = bf2f((c0[i] >> sh) & 0xffffu) * bf2f((u0[i] >> sh) & 0xffffu);
;                 const float m1 = bf2f((c1[i] >> sh) & 0xffffu) * bf2f((u1[i] >> sh) & 0xffffu);
;                 const float m2 = bf2f((c2[i] >> sh) & 0xffffu) * bf2f((u2[i] >> sh) & 0xffffu);
;                 o[2 * i + hh] = bf2f((bg[i] >> sh) & 0xffffu) * (m0 * wc[ch] + m1 * wc[1024 + ch] + m2 * wc[2048 + ch]);
;             }
;         }
;         u32x4 w; w.x = cvt_pk_bf16(o[0], o[1]); w.y = cvt_pk_bf16(o[2], o[3]); w.z = cvt_pk_bf16(o[4], o[5]); w.w = cvt_pk_bf16(o[6], o[7]);
;         *(u32x4*)(Y + (size_t)row * DM + 1024 + c8) = w;
	v_mul_f32_e32 v78, v102, v2
	v_mul_f32_e32 v118, v94, v18
	v_fma_f32 v78, v110, v10, v78
	v_add_f32_e32 v78, v78, v118
	v_lshlrev_b32_e32 v119, 16, v62
	v_mul_f32_e32 v78, v78, v119
	v_mul_f32_e32 v79, v103, v3
	v_mul_f32_e32 v118, v95, v19
	v_fma_f32 v79, v111, v11, v79
	v_add_f32_e32 v79, v79, v118
	v_and_b32_e32 v119, 0xffff0000, v62
	v_mul_f32_e32 v79, v79, v119
	v_mul_f32_e32 v80, v104, v4
	v_mul_f32_e32 v118, v96, v20
	v_fma_f32 v80, v112, v12, v80
	v_add_f32_e32 v80, v80, v118
	v_lshlrev_b32_e32 v119, 16, v63
	v_mul_f32_e32 v80, v80, v119
	v_mul_f32_e32 v81, v105, v5
	v_mul_f32_e32 v118, v97, v21
	v_fma_f32 v81, v113, v13, v81
	v_add_f32_e32 v81, v81, v118
	v_and_b32_e32 v119, 0xffff0000, v63
	v_mul_f32_e32 v81, v81, v119
	v_mul_f32_e32 v82, v106, v6
	v_mul_f32_e32 v118, v98, v22
	v_fma_f32 v82, v114, v14, v82
	v_add_f32_e32 v82, v82, v118
	v_lshlrev_b32_e32 v119, 16, v64
	v_mul_f32_e32 v82, v82, v119
	v_mul_f32_e32 v83, v107, v7
	v_mul_f32_e32 v118, v99, v23
	v_fma_f32 v83, v115, v15, v83
	v_add_f32_e32 v83, v83, v118
	v_and_b32_e32 v119, 0xffff0000, v64
	v_mul_f32_e32 v83, v83, v119
	v_mul_f32_e32 v84, v108, v8
	v_mul_f32_e32 v118, v100, v24
	v_fma_f32 v84, v116, v16, v84
	v_add_f32_e32 v84, v84, v118
	v_lshlrev_b32_e32 v119, 16, v65
	v_mul_f32_e32 v84, v84, v119
	v_mul_f32_e32 v85, v109, v9
	v_mul_f32_e32 v118, v101, v25
	v_fma_f32 v85, v117, v17, v85
	v_add_f32_e32 v85, v85, v118
	v_and_b32_e32 v119, 0xffff0000, v65
	v_mul_f32_e32 v85, v85, v119
	v_cvt_pk_bf16_f32 v120, v78, v79
	v_cvt_pk_bf16_f32 v121, v80, v81
	v_cvt_pk_bf16_f32 v122, v82, v83
	v_cvt_pk_bf16_f32 v123, v84, v85
	s_add_u32 s10, s18, 0x4000
	s_addc_u32 s11, s19, 0
	global_store_dwordx4 v86, v[120:123], s[10:11]
	s_add_u32 s10, s16, 0x10000
	s_addc_u32 s11, s17, 0
	global_load_dwordx4 v[34:37], v86, s[10:11]
	global_load_dwordx4 v[38:41], v86, s[10:11] offset:2048
	s_waitcnt vmcnt(8)
	v_lshlrev_b32_e32 v118, 16, v54
	v_lshlrev_b32_e32 v119, 16, v58
	v_mul_f32_e32 v102, v118, v119
	v_and_b32_e32 v54, 0xffff0000, v54
	v_and_b32_e32 v58, 0xffff0000, v58
	v_mul_f32_e32 v103, v54, v58
	v_lshlrev_b32_e32 v118, 16, v55
	v_lshlrev_b32_e32 v119, 16, v59
	v_mul_f32_e32 v104, v118, v119
	v_and_b32_e32 v55, 0xffff0000, v55
	v_and_b32_e32 v59, 0xffff0000, v59
	v_mul_f32_e32 v105, v55, v59
	v_lshlrev_b32_e32 v118, 16, v56
	v_lshlrev_b32_e32 v119, 16, v60
	v_mul_f32_e32 v106, v118, v119
	v_and_b32_e32 v56, 0xffff0000, v56
	v_and_b32_e32 v60, 0xffff0000, v60
	v_mul_f32_e32 v107, v56, v60
	v_lshlrev_b32_e32 v118, 16, v57
	v_lshlrev_b32_e32 v119, 16, v61
	v_mul_f32_e32 v108, v118, v119
	v_and_b32_e32 v57, 0xffff0000, v57
	v_and_b32_e32 v61, 0xffff0000, v61
	v_mul_f32_e32 v109, v57, v61
	s_waitcnt vmcnt(11)
	v_mul_f32_e32 v78, v110, v2
	v_mul_f32_e32 v118, v102, v18
	v_fma_f32 v78, v94, v10, v78
	v_add_f32_e32 v78, v78, v118
	v_lshlrev_b32_e32 v119, 16, v66
	v_mul_f32_e32 v78, v78, v119
	v_mul_f32_e32 v79, v111, v3
	v_mul_f32_e32 v118, v103, v19
	v_fma_f32 v79, v95, v11, v79
	v_add_f32_e32 v79, v79, v118
	v_and_b32_e32 v119, 0xffff0000, v66
	v_mul_f32_e32 v79, v79, v119
	v_mul_f32_e32 v80, v112, v4
	v_mul_f32_e32 v118, v104, v20
	v_fma_f32 v80, v96, v12, v80
	v_add_f32_e32 v80, v80, v118
	v_lshlrev_b32_e32 v119, 16, v67
	v_mul_f32_e32 v80, v80, v119
	v_mul_f32_e32 v81, v113, v5
	v_mul_f32_e32 v118, v105, v21
	v_fma_f32 v81, v97, v13, v81
	v_add_f32_e32 v81, v81, v118
	v_and_b32_e32 v119, 0xffff0000, v67
	v_mul_f32_e32 v81, v81, v119
	v_mul_f32_e32 v82, v114, v6
	v_mul_f32_e32 v118, v106, v22
	v_fma_f32 v82, v98, v14, v82
	v_add_f32_e32 v82, v82, v118
	v_lshlrev_b32_e32 v119, 16, v68
	v_mul_f32_e32 v82, v82, v119
	v_mul_f32_e32 v83, v115, v7
	v_mul_f32_e32 v118, v107, v23
	v_fma_f32 v83, v99, v15, v83
	v_add_f32_e32 v83, v83, v118
	v_and_b32_e32 v119, 0xffff0000, v68
	v_mul_f32_e32 v83, v83, v119
	v_mul_f32_e32 v84, v116, v8
	v_mul_f32_e32 v118, v108, v24
	v_fma_f32 v84, v100, v16, v84
	v_add_f32_e32 v84, v84, v118
	v_lshlrev_b32_e32 v119, 16, v69
	v_mul_f32_e32 v84, v84, v119
	v_mul_f32_e32 v85, v117, v9
	v_mul_f32_e32 v118, v109, v25
	v_fma_f32 v85, v101, v17, v85
	v_add_f32_e32 v85, v85, v118
	v_and_b32_e32 v119, 0xffff0000, v69
	v_mul_f32_e32 v85, v85, v119
	v_cvt_pk_bf16_f32 v120, v78, v79
	v_cvt_pk_bf16_f32 v121, v80, v81
	v_cvt_pk_bf16_f32 v122, v82, v83
	v_cvt_pk_bf16_f32 v123, v84, v85
	s_add_u32 s10, s18, 0x5000
	s_addc_u32 s11, s19, 0
	global_store_dwordx4 v86, v[120:123], s[10:11]
	s_waitcnt vmcnt(5)
; __device__ __forceinline__ unsigned cvt_pk_bf16(float lo, float hi) { unsigned r; asm("v_cvt_pk_bf16_f32 %0, %1, %2" : "=v"(r) : "v"(lo), "v"(hi)); return r; }
; __device__ __forceinline__ float bf2f(unsigned b) { return __uint_as_float(b << 16); }
; __device__ __forceinline__ void r1s_phase(KP p, int G, int bid, int wv) {
;     ...
;         float o[8];
; #pragma unroll
;         for (int i = 0; i < 4; ++i) {
; #pragma unroll
;             for (int hh = 0; hh < 2; ++hh) {
;                 const int sh = hh * 16, ch = c8 + 2 * i + hh;
;                 const float m0 = bf2f((c0[i] >> sh) & 0xffffu) * bf2f((u0[i] >> sh) & 0xffffu);
;                 const float m1 = bf2f((c1[i] >> sh) & 0xffffu) * bf2f((u1[i] >> sh) & 0xffffu);
;                 const float m2 = bf2f((c2[i] >> sh) & 0xffffu) * bf2f((u2[i] >> sh) & 0xffffu);
;                 o[2 * i + hh] = bf2f((bg[i] >> sh) & 0xffffu) * (m0 * wc[ch] + m1 * wc[1024 + ch] + m2 * wc[2048 + ch]);
;             }
;         }
;         u32x4 w; w.x = cvt_pk_bf16(o[0], o[1]); w.y = cvt_pk_bf16(o[2], o[3]); w.z = cvt_pk_bf16(o[4], o[5]); w.w = cvt_pk_bf16(o[6], o[7]);
;         *(u32x4*)(Y + (size_t)row * DM + 1024 + c8) = w;
	v_lshlrev_b32_e32 v118, 16, v26
	v_lshlrev_b32_e32 v119, 16, v30
	v_mul_f32_e32 v110, v118, v119
	v_and_b32_e32 v26, 0xffff0000, v26
	v_and_b32_e32 v30, 0xffff0000, v30
	v_mul_f32_e32 v111, v26, v30
	v_lshlrev_b32_e32 v118, 16, v27
	v_lshlrev_b32_e32 v119, 16, v31
	v_mul_f32_e32 v112, v118, v119
	v_and_b32_e32 v27, 0xffff0000, v27
	v_and_b32_e32 v31, 0xffff0000, v31
	v_mul_f32_e32 v113, v27, v31
	v_lshlrev_b32_e32 v118, 16, v28
	v_lshlrev_b32_e32 v119, 16, v32
	v_mul_f32_e32 v114, v118, v119
	v_and_b32_e32 v28, 0xffff0000, v28
	v_and_b32_e32 v32, 0xffff0000, v32
	v_mul_f32_e32 v115, v28, v32
	v_lshlrev_b32_e32 v118, 16, v29
	v_lshlrev_b32_e32 v119, 16, v33
	v_mul_f32_e32 v116, v118, v119
	v_and_b32_e32 v29, 0xffff0000, v29
	v_and_b32_e32 v33, 0xffff0000, v33
	v_mul_f32_e32 v117, v29, v33
	s_waitcnt vmcnt(8)
	v_mul_f32_e32 v78, v94, v2
	v_mul_f32_e32 v118, v110, v18
	v_fma_f32 v78, v102, v10, v78
	v_add_f32_e32 v78, v78, v118
	v_lshlrev_b32_e32 v119, 16, v70
	v_mul_f32_e32 v78, v78, v119
	v_mul_f32_e32 v79, v95, v3
	v_mul_f32_e32 v118, v111, v19
	v_fma_f32 v79, v103, v11, v79
	v_add_f32_e32 v79, v79, v118
	v_and_b32_e32 v119, 0xffff0000, v70
	v_mul_f32_e32 v79, v79, v119
	v_mul_f32_e32 v80, v96, v4
	v_mul_f32_e32 v118, v112, v20
	v_fma_f32 v80, v104, v12, v80
	v_add_f32_e32 v80, v80, v118
	v_lshlrev_b32_e32 v119, 16, v71
	v_mul_f32_e32 v80, v80, v119
	v_mul_f32_e32 v81, v97, v5
	v_mul_f32_e32 v118, v113, v21
	v_fma_f32 v81, v105, v13, v81
	v_add_f32_e32 v81, v81, v118
	v_and_b32_e32 v119, 0xffff0000, v71
	v_mul_f32_e32 v81, v81, v119
	v_mul_f32_e32 v82, v98, v6
	v_mul_f32_e32 v118, v114, v22
	v_fma_f32 v82, v106, v14, v82
	v_add_f32_e32 v82, v82, v118
	v_lshlrev_b32_e32 v119, 16, v72
	v_mul_f32_e32 v82, v82, v119
	v_mul_f32_e32 v83, v99, v7
	v_mul_f32_e32 v118, v115, v23
	v_fma_f32 v83, v107, v15, v83
	v_add_f32_e32 v83, v83, v118
	v_and_b32_e32 v119, 0xffff0000, v72
	v_mul_f32_e32 v83, v83, v119
	v_mul_f32_e32 v84, v100, v8
	v_mul_f32_e32 v118, v116, v24
	v_fma_f32 v84, v108, v16, v84
	v_add_f32_e32 v84, v84, v118
	v_lshlrev_b32_e32 v119, 16, v73
	v_mul_f32_e32 v84, v84, v119
	v_mul_f32_e32 v85, v101, v9
	v_mul_f32_e32 v118, v117, v25
	v_fma_f32 v85, v109, v17, v85
	v_add_f32_e32 v85, v85, v118
	v_and_b32_e32 v119, 0xffff0000, v73
	v_mul_f32_e32 v85, v85, v119
	v_cvt_pk_bf16_f32 v120, v78, v79
	v_cvt_pk_bf16_f32 v121, v80, v81
	v_cvt_pk_bf16_f32 v122, v82, v83
	v_cvt_pk_bf16_f32 v123, v84, v85
	s_add_u32 s10, s18, 0x6000
	s_addc_u32 s11, s19, 0
	global_store_dwordx4 v86, v[120:123], s[10:11]
	s_cmp_eq_u32 s9, 0x7f8
	s_waitcnt vmcnt(2)
	s_cbranch_scc1 .Lgc_zero_2
	v_lshlrev_b32_e32 v118, 16, v34
	v_lshlrev_b32_e32 v119, 16, v38
	v_mul_f32_e32 v94, v118, v119
	v_and_b32_e32 v34, 0xffff0000, v34
	v_and_b32_e32 v38, 0xffff0000, v38
	v_mul_f32_e32 v95, v34, v38
	v_lshlrev_b32_e32 v118, 16, v35
	v_lshlrev_b32_e32 v119, 16, v39
	v_mul_f32_e32 v96, v118, v119
	v_and_b32_e32 v35, 0xffff0000, v35
	v_and_b32_e32 v39, 0xffff0000, v39
	v_mul_f32_e32 v97, v35, v39
	v_lshlrev_b32_e32 v118, 16, v36
	v_lshlrev_b32_e32 v119, 16, v40
	v_mul_f32_e32 v98, v118, v119
	v_and_b32_e32 v36, 0xffff0000, v36
	v_and_b32_e32 v40, 0xffff0000, v40
	v_mul_f32_e32 v99, v36, v40
	v_lshlrev_b32_e32 v118, 16, v37
	v_lshlrev_b32_e32 v119, 16, v41
	v_mul_f32_e32 v100, v118, v119
	v_and_b32_e32 v37, 0xffff0000, v37
	v_and_b32_e32 v41, 0xffff0000, v41
	v_mul_f32_e32 v101, v37, v41
	s_branch .Lgc_done_2

; __device__ __forceinline__ unsigned cvt_pk_bf16(float lo, float hi) { unsigned r; asm("v_cvt_pk_bf16_f32 %0, %1, %2" : "=v"(r) : "v"(lo), "v"(hi)); return r; }
; __device__ __forceinline__ float bf2f(unsigned b) { return __uint_as_float(b << 16); }
; __device__ __forceinline__ void r1s_phase(KP p, int G, int bid, int wv) {
;     ...
;         float o[8];
; #pragma unroll
;         for (int i = 0; i < 4; ++i) {
; #pragma unroll
;             for (int hh = 0; hh < 2; ++hh) {
;                 const int sh = hh * 16, ch = c8 + 2 * i + hh;
;                 const float m0 = bf2f((c0[i] >> sh) & 0xffffu) * bf2f((u0[i] >> sh) & 0xffffu);
;                 const float m1 = bf2f((c1[i] >> sh) & 0xffffu) * bf2f((u1[i] >> sh) & 0xffffu);
;                 const float m2 = bf2f((c2[i] >> sh) & 0xffffu) * bf2f((u2[i] >> sh) & 0xffffu);
;                 o[2 * i + hh] = bf2f((bg[i] >> sh) & 0xffffu) * (m0 * wc[ch] + m1 * wc[1024 + ch] + m2 * wc[2048 + ch]);
;             }
;         }
;         u32x4 w; w.x = cvt_pk_bf16(o[0], o[1]); w.y = cvt_pk_bf16(o[2], o[3]); w.z = cvt_pk_bf16(o[4], o[5]); w.w = cvt_pk_bf16(o[6], o[7]);
;         *(u32x4*)(Y + (size_t)row * DM + 1024 + c8) = w;
.Lgc_done_2:
	s_waitcnt vmcnt(5)
	v_mul_f32_e32 v78, v102, v2
	v_mul_f32_e32 v118, v94, v18
	v_fma_f32 v78, v110, v10, v78
	v_add_f32_e32 v78, v78, v118
	v_lshlrev_b32_e32 v119, 16, v74
	v_mul_f32_e32 v78, v78, v119
	v_mul_f32_e32 v79, v103, v3
	v_mul_f32_e32 v118, v95, v19
	v_fma_f32 v79, v111, v11, v79
	v_add_f32_e32 v79, v79, v118
	v_and_b32_e32 v119, 0xffff0000, v74
	v_mul_f32_e32 v79, v79, v119
	v_mul_f32_e32 v80, v104, v4
	v_mul_f32_e32 v118, v96, v20
	v_fma_f32 v80, v112, v12, v80
	v_add_f32_e32 v80, v80, v118
	v_lshlrev_b32_e32 v119, 16, v75
	v_mul_f32_e32 v80, v80, v119
	v_mul_f32_e32 v81, v105, v5
	v_mul_f32_e32 v118, v97, v21
	v_fma_f32 v81, v113, v13, v81
	v_add_f32_e32 v81, v81, v118
	v_and_b32_e32 v119, 0xffff0000, v75
	v_mul_f32_e32 v81, v81, v119
	v_mul_f32_e32 v82, v106, v6
	v_mul_f32_e32 v118, v98, v22
	v_fma_f32 v82, v114, v14, v82
	v_add_f32_e32 v82, v82, v118
	v_lshlrev_b32_e32 v119, 16, v76
	v_mul_f32_e32 v82, v82, v119
	v_mul_f32_e32 v83, v107, v7
	v_mul_f32_e32 v118, v99, v23
	v_fma_f32 v83, v115, v15, v83
	v_add_f32_e32 v83, v83, v118
	v_and_b32_e32 v119, 0xffff0000, v76
	v_mul_f32_e32 v83, v83, v119
	v_mul_f32_e32 v84, v108, v8
	v_mul_f32_e32 v118, v100, v24
	v_fma_f32 v84, v116, v16, v84
	v_add_f32_e32 v84, v84, v118
	v_lshlrev_b32_e32 v119, 16, v77
	v_mul_f32_e32 v84, v84, v119
	v_mul_f32_e32 v85, v109, v9
	v_mul_f32_e32 v118, v101, v25
	v_fma_f32 v85, v117, v17, v85
	v_add_f32_e32 v85, v85, v118
	v_and_b32_e32 v119, 0xffff0000, v77
	v_mul_f32_e32 v85, v85, v119
	v_cvt_pk_bf16_f32 v120, v78, v79
	v_cvt_pk_bf16_f32 v121, v80, v81
	v_cvt_pk_bf16_f32 v122, v82, v83
	v_cvt_pk_bf16_f32 v123, v84, v85
	s_add_u32 s10, s18, 0x7000
	s_addc_u32 s11, s19, 0
	global_store_dwordx4 v86, v[120:123], s[10:11]
